# amax chains as v_max3 with abs modifiers in the fp6 epilogues; mid-segment s_setprio pairs removed from bf16 loops
# speedup vs baseline: 1.0075x; 1.0075x over previous
.LBB0_193:
	ds_read_b128 v[142:145], v160
	ds_read_b128 v[146:149], v160 offset:1024
	ds_read_b128 v[150:153], v160 offset:2048
	ds_read_b128 v[154:157], v160 offset:3072
	ds_read_b128 v[164:167], v161
	ds_read_b128 v[168:171], v161 offset:1024
	ds_read_b128 v[172:175], v161 offset:2048
	ds_read_b128 v[176:179], v161 offset:3072
	s_add_u32 s67, s88, 0xfff80080
	s_addc_u32 s90, s89, -1
	s_cmp_eq_u32 s65, 28
	s_cselect_b32 s91, s9, s90
	s_cselect_b32 s90, s11, s67
	s_cselect_b32 s93, s26, s53
	s_cselect_b32 s92, s47, s52
	v_lshl_add_u64 v[158:159], s[88:89], 0, v[136:137]
	s_add_i32 m0, s24, 0xc000
	ds_read_b128 v[180:183], v162
	ds_read_b128 v[184:187], v162 offset:1024
	ds_read_b128 v[188:191], v162 offset:2048
	ds_read_b128 v[192:195], v162 offset:3072
	ds_read_b128 v[196:199], v162 offset:4096
	ds_read_b128 v[200:203], v162 offset:5120
	ds_read_b128 v[204:207], v162 offset:6144
	ds_read_b128 v[208:211], v162 offset:7168
	global_load_lds_dwordx4 v[158:159], off
	v_lshl_add_u64 v[158:159], v[158:159], 0, s[16:17]
	s_add_i32 m0, s24, 0xe000
	s_nop 0
	global_load_lds_dwordx4 v[158:159], off
	s_waitcnt vmcnt(8)
	s_waitcnt lgkmcnt(0)
	s_barrier
	s_setprio 1
	s_waitcnt lgkmcnt(0)
	v_mfma_f32_16x16x32_bf16 v[126:129], v[142:145], v[180:183], v[126:129]
	v_mfma_f32_16x16x32_bf16 v[122:125], v[150:153], v[180:183], v[122:125]
	v_mfma_f32_16x16x32_bf16 v[118:121], v[142:145], v[188:191], v[118:121]
	v_mfma_f32_16x16x32_bf16 v[114:117], v[150:153], v[188:191], v[114:117]
	v_mfma_f32_16x16x32_bf16 v[110:113], v[142:145], v[196:199], v[110:113]
	v_mfma_f32_16x16x32_bf16 v[106:109], v[150:153], v[196:199], v[106:109]
	v_mfma_f32_16x16x32_bf16 v[102:105], v[142:145], v[204:207], v[102:105]
	v_mfma_f32_16x16x32_bf16 v[98:101], v[150:153], v[204:207], v[98:101]
	v_mfma_f32_16x16x32_bf16 v[126:129], v[146:149], v[184:187], v[126:129]
	v_mfma_f32_16x16x32_bf16 v[122:125], v[154:157], v[184:187], v[122:125]
	v_mfma_f32_16x16x32_bf16 v[118:121], v[146:149], v[192:195], v[118:121]
	v_mfma_f32_16x16x32_bf16 v[114:117], v[154:157], v[192:195], v[114:117]
	v_mfma_f32_16x16x32_bf16 v[110:113], v[146:149], v[200:203], v[110:113]
	v_mfma_f32_16x16x32_bf16 v[106:109], v[154:157], v[200:203], v[106:109]
	v_mfma_f32_16x16x32_bf16 v[102:105], v[146:149], v[208:211], v[102:105]
	v_mfma_f32_16x16x32_bf16 v[98:101], v[154:157], v[208:211], v[98:101]
	v_mfma_f32_16x16x32_bf16 v[62:65], v[164:167], v[180:183], v[62:65]
	v_mfma_f32_16x16x32_bf16 v[58:61], v[172:175], v[180:183], v[58:61]
	v_mfma_f32_16x16x32_bf16 v[54:57], v[164:167], v[188:191], v[54:57]
	v_mfma_f32_16x16x32_bf16 v[50:53], v[172:175], v[188:191], v[50:53]
	v_mfma_f32_16x16x32_bf16 v[46:49], v[164:167], v[196:199], v[46:49]
	v_mfma_f32_16x16x32_bf16 v[42:45], v[172:175], v[196:199], v[42:45]
	v_mfma_f32_16x16x32_bf16 v[38:41], v[164:167], v[204:207], v[38:41]
	v_mfma_f32_16x16x32_bf16 v[34:37], v[172:175], v[204:207], v[34:37]
	v_mfma_f32_16x16x32_bf16 v[62:65], v[168:171], v[184:187], v[62:65]
	v_mfma_f32_16x16x32_bf16 v[58:61], v[176:179], v[184:187], v[58:61]
	v_mfma_f32_16x16x32_bf16 v[54:57], v[168:171], v[192:195], v[54:57]
	v_mfma_f32_16x16x32_bf16 v[50:53], v[176:179], v[192:195], v[50:53]
	v_mfma_f32_16x16x32_bf16 v[46:49], v[168:171], v[200:203], v[46:49]
	v_mfma_f32_16x16x32_bf16 v[42:45], v[176:179], v[200:203], v[42:45]
	v_mfma_f32_16x16x32_bf16 v[38:41], v[168:171], v[208:211], v[38:41]
	v_mfma_f32_16x16x32_bf16 v[34:37], v[176:179], v[208:211], v[34:37]
	s_setprio 0
	s_barrier
	s_add_i32 s67, s51, s13
	v_lshl_add_u64 v[158:159], s[92:93], 0, v[132:133]
	s_mov_b32 m0, s67
	ds_read_b128 v[180:183], v162 offset:16384
	ds_read_b128 v[184:187], v162 offset:17408
	ds_read_b128 v[188:191], v162 offset:18432
	ds_read_b128 v[192:195], v162 offset:19456
	ds_read_b128 v[196:199], v162 offset:20480
	ds_read_b128 v[200:203], v162 offset:21504
	ds_read_b128 v[204:207], v162 offset:22528
	ds_read_b128 v[208:211], v162 offset:23552
	global_load_lds_dwordx4 v[158:159], off
	v_lshl_add_u64 v[212:213], v[158:159], 0, s[16:17]
	s_add_i32 m0, s67, 0x2000
	s_add_i32 s67, s34, s13
	global_load_lds_dwordx4 v[212:213], off
	v_lshl_add_u64 v[212:213], v[158:159], 0, s[18:19]
	s_mov_b32 m0, s67
	s_nop 0
	global_load_lds_dwordx4 v[212:213], off
	v_lshl_add_u64 v[212:213], v[158:159], 0, s[20:21]
	s_add_i32 m0, s67, 0x2000
	s_nop 0
	global_load_lds_dwordx4 v[212:213], off
	v_lshl_add_u64 v[212:213], s[90:91], 0, v[130:131]
	s_mov_b32 m0, s24
	v_lshl_add_u64 v[214:215], v[212:213], 0, s[16:17]
	global_load_lds_dwordx4 v[212:213], off
	s_mov_b32 m0, s25
	s_nop 0
	global_load_lds_dwordx4 v[214:215], off
	s_waitcnt vmcnt(8)
	s_waitcnt lgkmcnt(0)
	s_barrier
	s_setprio 1
	s_waitcnt lgkmcnt(0)
	v_mfma_f32_16x16x32_bf16 v[94:97], v[142:145], v[180:183], v[94:97]
	v_mfma_f32_16x16x32_bf16 v[90:93], v[150:153], v[180:183], v[90:93]
	v_mfma_f32_16x16x32_bf16 v[86:89], v[142:145], v[188:191], v[86:89]
	v_mfma_f32_16x16x32_bf16 v[82:85], v[150:153], v[188:191], v[82:85]
	v_mfma_f32_16x16x32_bf16 v[78:81], v[142:145], v[196:199], v[78:81]
	v_mfma_f32_16x16x32_bf16 v[74:77], v[150:153], v[196:199], v[74:77]
	v_mfma_f32_16x16x32_bf16 v[70:73], v[142:145], v[204:207], v[70:73]
	v_mfma_f32_16x16x32_bf16 v[66:69], v[150:153], v[204:207], v[66:69]
	v_mfma_f32_16x16x32_bf16 v[94:97], v[146:149], v[184:187], v[94:97]
	v_mfma_f32_16x16x32_bf16 v[90:93], v[154:157], v[184:187], v[90:93]
	v_mfma_f32_16x16x32_bf16 v[86:89], v[146:149], v[192:195], v[86:89]
	v_mfma_f32_16x16x32_bf16 v[82:85], v[154:157], v[192:195], v[82:85]
	v_mfma_f32_16x16x32_bf16 v[78:81], v[146:149], v[200:203], v[78:81]
	v_mfma_f32_16x16x32_bf16 v[74:77], v[154:157], v[200:203], v[74:77]
	v_mfma_f32_16x16x32_bf16 v[70:73], v[146:149], v[208:211], v[70:73]
	v_mfma_f32_16x16x32_bf16 v[66:69], v[154:157], v[208:211], v[66:69]
	v_mfma_f32_16x16x32_bf16 v[30:33], v[164:167], v[180:183], v[30:33]
	v_mfma_f32_16x16x32_bf16 v[26:29], v[172:175], v[180:183], v[26:29]
	v_mfma_f32_16x16x32_bf16 v[22:25], v[164:167], v[188:191], v[22:25]
	v_mfma_f32_16x16x32_bf16 v[18:21], v[172:175], v[188:191], v[18:21]
	v_mfma_f32_16x16x32_bf16 v[14:17], v[164:167], v[196:199], v[14:17]
	v_mfma_f32_16x16x32_bf16 v[10:13], v[172:175], v[196:199], v[10:13]
	v_mfma_f32_16x16x32_bf16 v[6:9], v[164:167], v[204:207], v[6:9]
	v_mfma_f32_16x16x32_bf16 v[2:5], v[172:175], v[204:207], v[2:5]
	v_mfma_f32_16x16x32_bf16 v[30:33], v[168:171], v[184:187], v[30:33]
	v_mfma_f32_16x16x32_bf16 v[26:29], v[176:179], v[184:187], v[26:29]
	v_mfma_f32_16x16x32_bf16 v[22:25], v[168:171], v[192:195], v[22:25]
	v_mfma_f32_16x16x32_bf16 v[18:21], v[176:179], v[192:195], v[18:21]
	v_mfma_f32_16x16x32_bf16 v[14:17], v[168:171], v[200:203], v[14:17]
	v_mfma_f32_16x16x32_bf16 v[10:13], v[176:179], v[200:203], v[10:13]
	v_mfma_f32_16x16x32_bf16 v[6:9], v[168:171], v[208:211], v[6:9]
	v_mfma_f32_16x16x32_bf16 v[2:5], v[176:179], v[208:211], v[2:5]
	s_setprio 0
	s_barrier
	s_add_i32 s67, 0, 0x18000
	v_add_u32_e32 v134, s67, v1
	s_add_i32 s90, 0, 0x1c000
	ds_read_b128 v[142:145], v134
	ds_read_b128 v[146:149], v134 offset:1024
	ds_read_b128 v[150:153], v134 offset:2048
	ds_read_b128 v[154:157], v134 offset:3072
	v_add_u32_e32 v134, s90, v1
	ds_read_b128 v[164:167], v134
	ds_read_b128 v[168:171], v134 offset:1024
	ds_read_b128 v[172:175], v134 offset:2048
	ds_read_b128 v[176:179], v134 offset:3072
	s_mov_b32 m0, s28
	v_lshl_add_u64 v[214:215], v[212:213], 0, s[18:19]
	ds_read_b128 v[180:183], v162 offset:32768
	ds_read_b128 v[184:187], v162 offset:33792
	ds_read_b128 v[188:191], v162 offset:34816
	ds_read_b128 v[192:195], v162 offset:35840
	ds_read_b128 v[196:199], v162 offset:36864
	ds_read_b128 v[200:203], v162 offset:37888
	ds_read_b128 v[204:207], v162 offset:38912
	ds_read_b128 v[208:211], v162 offset:39936
	global_load_lds_dwordx4 v[214:215], off
	v_lshl_add_u64 v[214:215], v[212:213], 0, s[20:21]
	s_mov_b32 m0, s29
	s_nop 0
	global_load_lds_dwordx4 v[214:215], off
	s_waitcnt vmcnt(8)
	s_waitcnt lgkmcnt(0)
	s_barrier
	s_setprio 1
	s_waitcnt lgkmcnt(0)
	v_mfma_f32_16x16x32_bf16 v[126:129], v[142:145], v[180:183], v[126:129]
	v_mfma_f32_16x16x32_bf16 v[122:125], v[150:153], v[180:183], v[122:125]
	v_mfma_f32_16x16x32_bf16 v[118:121], v[142:145], v[188:191], v[118:121]
	v_mfma_f32_16x16x32_bf16 v[114:117], v[150:153], v[188:191], v[114:117]
	v_mfma_f32_16x16x32_bf16 v[110:113], v[142:145], v[196:199], v[110:113]
	v_mfma_f32_16x16x32_bf16 v[106:109], v[150:153], v[196:199], v[106:109]
	v_mfma_f32_16x16x32_bf16 v[102:105], v[142:145], v[204:207], v[102:105]
	v_mfma_f32_16x16x32_bf16 v[98:101], v[150:153], v[204:207], v[98:101]
	v_mfma_f32_16x16x32_bf16 v[126:129], v[146:149], v[184:187], v[126:129]
	v_mfma_f32_16x16x32_bf16 v[122:125], v[154:157], v[184:187], v[122:125]
	v_mfma_f32_16x16x32_bf16 v[118:121], v[146:149], v[192:195], v[118:121]
	v_mfma_f32_16x16x32_bf16 v[114:117], v[154:157], v[192:195], v[114:117]
	v_mfma_f32_16x16x32_bf16 v[110:113], v[146:149], v[200:203], v[110:113]
	v_mfma_f32_16x16x32_bf16 v[106:109], v[154:157], v[200:203], v[106:109]
	v_mfma_f32_16x16x32_bf16 v[102:105], v[146:149], v[208:211], v[102:105]
	v_mfma_f32_16x16x32_bf16 v[98:101], v[154:157], v[208:211], v[98:101]
	v_mfma_f32_16x16x32_bf16 v[62:65], v[164:167], v[180:183], v[62:65]
	v_mfma_f32_16x16x32_bf16 v[58:61], v[172:175], v[180:183], v[58:61]
	v_mfma_f32_16x16x32_bf16 v[54:57], v[164:167], v[188:191], v[54:57]
	v_mfma_f32_16x16x32_bf16 v[50:53], v[172:175], v[188:191], v[50:53]
	v_mfma_f32_16x16x32_bf16 v[46:49], v[164:167], v[196:199], v[46:49]
	v_mfma_f32_16x16x32_bf16 v[42:45], v[172:175], v[196:199], v[42:45]
	v_mfma_f32_16x16x32_bf16 v[38:41], v[164:167], v[204:207], v[38:41]
	v_mfma_f32_16x16x32_bf16 v[34:37], v[172:175], v[204:207], v[34:37]
	v_mfma_f32_16x16x32_bf16 v[62:65], v[168:171], v[184:187], v[62:65]
	v_mfma_f32_16x16x32_bf16 v[58:61], v[176:179], v[184:187], v[58:61]
	v_mfma_f32_16x16x32_bf16 v[54:57], v[168:171], v[192:195], v[54:57]
	v_mfma_f32_16x16x32_bf16 v[50:53], v[176:179], v[192:195], v[50:53]
	v_mfma_f32_16x16x32_bf16 v[46:49], v[168:171], v[200:203], v[46:49]
	v_mfma_f32_16x16x32_bf16 v[42:45], v[176:179], v[200:203], v[42:45]
	v_mfma_f32_16x16x32_bf16 v[38:41], v[168:171], v[208:211], v[38:41]
	v_mfma_f32_16x16x32_bf16 v[34:37], v[176:179], v[208:211], v[34:37]
	s_setprio 0
	s_barrier
	s_add_i32 s67, s67, s13
	v_lshl_add_u64 v[214:215], v[158:159], 0, s[54:55]
	s_mov_b32 m0, s67
	ds_read_b128 v[180:183], v162 offset:49152
	ds_read_b128 v[184:187], v162 offset:50176
	ds_read_b128 v[188:191], v162 offset:51200
	ds_read_b128 v[192:195], v162 offset:52224
	ds_read_b128 v[196:199], v162 offset:53248
	ds_read_b128 v[200:203], v162 offset:54272
	ds_read_b128 v[204:207], v162 offset:55296
	ds_read_b128 v[208:211], v162 offset:56320
	global_load_lds_dwordx4 v[214:215], off
	v_lshl_add_u64 v[214:215], v[158:159], 0, s[56:57]
	s_add_i32 m0, s67, 0x2000
	s_add_i32 s67, s90, s13
	global_load_lds_dwordx4 v[214:215], off
	v_lshl_add_u64 v[214:215], v[158:159], 0, s[58:59]
	s_mov_b32 m0, s67
	v_lshl_add_u64 v[158:159], v[158:159], 0, s[60:61]
	global_load_lds_dwordx4 v[214:215], off
	s_add_i32 m0, s67, 0x2000
	s_nop 0
	global_load_lds_dwordx4 v[158:159], off
	v_lshl_add_u64 v[158:159], v[212:213], 0, s[54:55]
	s_mov_b32 m0, s33
	s_nop 0
	global_load_lds_dwordx4 v[158:159], off
	v_lshl_add_u64 v[158:159], v[212:213], 0, s[56:57]
	s_mov_b32 m0, s40
	s_nop 0
	global_load_lds_dwordx4 v[158:159], off
	s_waitcnt vmcnt(8)
	s_waitcnt lgkmcnt(0)
	s_barrier
	s_setprio 1
	s_waitcnt lgkmcnt(0)
	v_mfma_f32_16x16x32_bf16 v[94:97], v[142:145], v[180:183], v[94:97]
	v_mfma_f32_16x16x32_bf16 v[90:93], v[150:153], v[180:183], v[90:93]
	v_mfma_f32_16x16x32_bf16 v[86:89], v[142:145], v[188:191], v[86:89]
	v_mfma_f32_16x16x32_bf16 v[82:85], v[150:153], v[188:191], v[82:85]
	v_mfma_f32_16x16x32_bf16 v[78:81], v[142:145], v[196:199], v[78:81]
	v_mfma_f32_16x16x32_bf16 v[74:77], v[150:153], v[196:199], v[74:77]
	v_mfma_f32_16x16x32_bf16 v[70:73], v[142:145], v[204:207], v[70:73]
	v_mfma_f32_16x16x32_bf16 v[66:69], v[150:153], v[204:207], v[66:69]
	v_mfma_f32_16x16x32_bf16 v[94:97], v[146:149], v[184:187], v[94:97]
	v_mfma_f32_16x16x32_bf16 v[90:93], v[154:157], v[184:187], v[90:93]
	v_mfma_f32_16x16x32_bf16 v[86:89], v[146:149], v[192:195], v[86:89]
	v_mfma_f32_16x16x32_bf16 v[82:85], v[154:157], v[192:195], v[82:85]
	v_mfma_f32_16x16x32_bf16 v[78:81], v[146:149], v[200:203], v[78:81]
	v_mfma_f32_16x16x32_bf16 v[74:77], v[154:157], v[200:203], v[74:77]
	v_mfma_f32_16x16x32_bf16 v[70:73], v[146:149], v[208:211], v[70:73]
	v_mfma_f32_16x16x32_bf16 v[66:69], v[154:157], v[208:211], v[66:69]
	v_mfma_f32_16x16x32_bf16 v[30:33], v[164:167], v[180:183], v[30:33]
	v_mfma_f32_16x16x32_bf16 v[26:29], v[172:175], v[180:183], v[26:29]
	v_mfma_f32_16x16x32_bf16 v[22:25], v[164:167], v[188:191], v[22:25]
	v_mfma_f32_16x16x32_bf16 v[18:21], v[172:175], v[188:191], v[18:21]
	v_mfma_f32_16x16x32_bf16 v[14:17], v[164:167], v[196:199], v[14:17]
	v_mfma_f32_16x16x32_bf16 v[10:13], v[172:175], v[196:199], v[10:13]
	v_mfma_f32_16x16x32_bf16 v[6:9], v[164:167], v[204:207], v[6:9]
	v_mfma_f32_16x16x32_bf16 v[2:5], v[172:175], v[204:207], v[2:5]
	v_mfma_f32_16x16x32_bf16 v[30:33], v[168:171], v[184:187], v[30:33]
	v_mfma_f32_16x16x32_bf16 v[26:29], v[176:179], v[184:187], v[26:29]
	v_mfma_f32_16x16x32_bf16 v[22:25], v[168:171], v[192:195], v[22:25]
	v_mfma_f32_16x16x32_bf16 v[18:21], v[176:179], v[192:195], v[18:21]
	v_mfma_f32_16x16x32_bf16 v[14:17], v[168:171], v[200:203], v[14:17]
	v_mfma_f32_16x16x32_bf16 v[10:13], v[176:179], v[200:203], v[10:13]
	v_mfma_f32_16x16x32_bf16 v[6:9], v[168:171], v[208:211], v[6:9]
	v_mfma_f32_16x16x32_bf16 v[2:5], v[176:179], v[208:211], v[2:5]
	s_setprio 0
	s_barrier
	s_add_i32 s65, s65, 2
	s_add_u32 s88, s88, 0x100
	s_addc_u32 s89, s89, 0
	s_add_u32 s52, s52, 0x100
	s_addc_u32 s53, s53, 0
	s_cmp_gt_u32 s65, 29
	s_cbranch_scc0 .LBB0_193
	s_and_b64 vcc, exec, s[62:63]
	s_cbranch_vccz .LBB0_196
	s_barrier

.LBB0_419:
	ds_read_b128 v[138:141], v156
	ds_read_b128 v[142:145], v156 offset:1024
	ds_read_b128 v[146:149], v156 offset:2048
	ds_read_b128 v[150:153], v156 offset:3072
	ds_read_b128 v[160:163], v157
	ds_read_b128 v[164:167], v157 offset:1024
	ds_read_b128 v[168:171], v157 offset:2048
	ds_read_b128 v[172:175], v157 offset:3072
	s_add_u32 s88, s8, 0xfff80080
	s_addc_u32 s89, s9, -1
	s_cmp_eq_u32 s87, 28
	s_cselect_b32 s89, s5, s89
	s_cselect_b32 s88, s7, s88
	s_cselect_b32 s91, s30, s86
	s_cselect_b32 s90, s63, s65
	v_lshl_add_u64 v[154:155], s[8:9], 0, v[136:137]
	s_add_i32 m0, s12, 0xc000
	ds_read_b128 v[176:179], v158
	ds_read_b128 v[180:183], v158 offset:1024
	ds_read_b128 v[184:187], v158 offset:2048
	ds_read_b128 v[188:191], v158 offset:3072
	ds_read_b128 v[192:195], v158 offset:4096
	ds_read_b128 v[196:199], v158 offset:5120
	ds_read_b128 v[200:203], v158 offset:6144
	ds_read_b128 v[204:207], v158 offset:7168
	global_load_lds_dwordx4 v[154:155], off
	v_lshl_add_u64 v[154:155], v[154:155], 0, s[18:19]
	s_add_i32 m0, s12, 0xe000
	s_nop 0
	global_load_lds_dwordx4 v[154:155], off
	s_waitcnt vmcnt(8)
	s_waitcnt lgkmcnt(0)
	s_barrier
	s_setprio 1
	s_waitcnt lgkmcnt(0)
	v_mfma_f32_16x16x32_bf16 v[126:129], v[138:141], v[176:179], v[126:129]
	v_mfma_f32_16x16x32_bf16 v[122:125], v[146:149], v[176:179], v[122:125]
	v_mfma_f32_16x16x32_bf16 v[118:121], v[138:141], v[184:187], v[118:121]
	v_mfma_f32_16x16x32_bf16 v[114:117], v[146:149], v[184:187], v[114:117]
	v_mfma_f32_16x16x32_bf16 v[110:113], v[138:141], v[192:195], v[110:113]
	v_mfma_f32_16x16x32_bf16 v[106:109], v[146:149], v[192:195], v[106:109]
	v_mfma_f32_16x16x32_bf16 v[102:105], v[138:141], v[200:203], v[102:105]
	v_mfma_f32_16x16x32_bf16 v[98:101], v[146:149], v[200:203], v[98:101]
	v_mfma_f32_16x16x32_bf16 v[126:129], v[142:145], v[180:183], v[126:129]
	v_mfma_f32_16x16x32_bf16 v[122:125], v[150:153], v[180:183], v[122:125]
	v_mfma_f32_16x16x32_bf16 v[118:121], v[142:145], v[188:191], v[118:121]
	v_mfma_f32_16x16x32_bf16 v[114:117], v[150:153], v[188:191], v[114:117]
	v_mfma_f32_16x16x32_bf16 v[110:113], v[142:145], v[196:199], v[110:113]
	v_mfma_f32_16x16x32_bf16 v[106:109], v[150:153], v[196:199], v[106:109]
	v_mfma_f32_16x16x32_bf16 v[102:105], v[142:145], v[204:207], v[102:105]
	v_mfma_f32_16x16x32_bf16 v[98:101], v[150:153], v[204:207], v[98:101]
	v_mfma_f32_16x16x32_bf16 v[62:65], v[160:163], v[176:179], v[62:65]
	v_mfma_f32_16x16x32_bf16 v[58:61], v[168:171], v[176:179], v[58:61]
	v_mfma_f32_16x16x32_bf16 v[54:57], v[160:163], v[184:187], v[54:57]
	v_mfma_f32_16x16x32_bf16 v[50:53], v[168:171], v[184:187], v[50:53]
	v_mfma_f32_16x16x32_bf16 v[46:49], v[160:163], v[192:195], v[46:49]
	v_mfma_f32_16x16x32_bf16 v[42:45], v[168:171], v[192:195], v[42:45]
	v_mfma_f32_16x16x32_bf16 v[38:41], v[160:163], v[200:203], v[38:41]
	v_mfma_f32_16x16x32_bf16 v[34:37], v[168:171], v[200:203], v[34:37]
	v_mfma_f32_16x16x32_bf16 v[62:65], v[164:167], v[180:183], v[62:65]
	v_mfma_f32_16x16x32_bf16 v[58:61], v[172:175], v[180:183], v[58:61]
	v_mfma_f32_16x16x32_bf16 v[54:57], v[164:167], v[188:191], v[54:57]
	v_mfma_f32_16x16x32_bf16 v[50:53], v[172:175], v[188:191], v[50:53]
	v_mfma_f32_16x16x32_bf16 v[46:49], v[164:167], v[196:199], v[46:49]
	v_mfma_f32_16x16x32_bf16 v[42:45], v[172:175], v[196:199], v[42:45]
	v_mfma_f32_16x16x32_bf16 v[38:41], v[164:167], v[204:207], v[38:41]
	v_mfma_f32_16x16x32_bf16 v[34:37], v[172:175], v[204:207], v[34:37]
	s_setprio 0
	s_barrier
	v_lshl_add_u64 v[154:155], s[90:91], 0, v[132:133]
	s_add_i32 s90, s42, s11
	s_mov_b32 m0, s90
	ds_read_b128 v[176:179], v158 offset:16384
	ds_read_b128 v[180:183], v158 offset:17408
	ds_read_b128 v[184:187], v158 offset:18432
	ds_read_b128 v[188:191], v158 offset:19456
	ds_read_b128 v[192:195], v158 offset:20480
	ds_read_b128 v[196:199], v158 offset:21504
	ds_read_b128 v[200:203], v158 offset:22528
	ds_read_b128 v[204:207], v158 offset:23552
	global_load_lds_dwordx4 v[154:155], off
	v_lshl_add_u64 v[208:209], v[154:155], 0, s[18:19]
	s_add_i32 m0, s90, 0x2000
	s_add_i32 s90, s43, s11
	global_load_lds_dwordx4 v[208:209], off
	v_lshl_add_u64 v[208:209], v[154:155], 0, s[20:21]
	s_mov_b32 m0, s90
	s_nop 0
	global_load_lds_dwordx4 v[208:209], off
	v_lshl_add_u64 v[208:209], v[154:155], 0, s[22:23]
	s_add_i32 m0, s90, 0x2000
	s_nop 0
	global_load_lds_dwordx4 v[208:209], off
	v_lshl_add_u64 v[208:209], s[88:89], 0, v[130:131]
	s_mov_b32 m0, s12
	v_lshl_add_u64 v[210:211], v[208:209], 0, s[18:19]
	global_load_lds_dwordx4 v[208:209], off
	s_mov_b32 m0, s13
	s_nop 0
	global_load_lds_dwordx4 v[210:211], off
	s_waitcnt vmcnt(8)
	s_waitcnt lgkmcnt(0)
	s_barrier
	s_setprio 1
	s_waitcnt lgkmcnt(0)
	v_mfma_f32_16x16x32_bf16 v[94:97], v[138:141], v[176:179], v[94:97]
	v_mfma_f32_16x16x32_bf16 v[90:93], v[146:149], v[176:179], v[90:93]
	v_mfma_f32_16x16x32_bf16 v[86:89], v[138:141], v[184:187], v[86:89]
	v_mfma_f32_16x16x32_bf16 v[82:85], v[146:149], v[184:187], v[82:85]
	v_mfma_f32_16x16x32_bf16 v[78:81], v[138:141], v[192:195], v[78:81]
	v_mfma_f32_16x16x32_bf16 v[74:77], v[146:149], v[192:195], v[74:77]
	v_mfma_f32_16x16x32_bf16 v[70:73], v[138:141], v[200:203], v[70:73]
	v_mfma_f32_16x16x32_bf16 v[66:69], v[146:149], v[200:203], v[66:69]
	v_mfma_f32_16x16x32_bf16 v[94:97], v[142:145], v[180:183], v[94:97]
	v_mfma_f32_16x16x32_bf16 v[90:93], v[150:153], v[180:183], v[90:93]
	v_mfma_f32_16x16x32_bf16 v[86:89], v[142:145], v[188:191], v[86:89]
	v_mfma_f32_16x16x32_bf16 v[82:85], v[150:153], v[188:191], v[82:85]
	v_mfma_f32_16x16x32_bf16 v[78:81], v[142:145], v[196:199], v[78:81]
	v_mfma_f32_16x16x32_bf16 v[74:77], v[150:153], v[196:199], v[74:77]
	v_mfma_f32_16x16x32_bf16 v[70:73], v[142:145], v[204:207], v[70:73]
	v_mfma_f32_16x16x32_bf16 v[66:69], v[150:153], v[204:207], v[66:69]
	v_mfma_f32_16x16x32_bf16 v[30:33], v[160:163], v[176:179], v[30:33]
	v_mfma_f32_16x16x32_bf16 v[26:29], v[168:171], v[176:179], v[26:29]
	v_mfma_f32_16x16x32_bf16 v[22:25], v[160:163], v[184:187], v[22:25]
	v_mfma_f32_16x16x32_bf16 v[18:21], v[168:171], v[184:187], v[18:21]
	v_mfma_f32_16x16x32_bf16 v[14:17], v[160:163], v[192:195], v[14:17]
	v_mfma_f32_16x16x32_bf16 v[10:13], v[168:171], v[192:195], v[10:13]
	v_mfma_f32_16x16x32_bf16 v[6:9], v[160:163], v[200:203], v[6:9]
	v_mfma_f32_16x16x32_bf16 v[2:5], v[168:171], v[200:203], v[2:5]
	v_mfma_f32_16x16x32_bf16 v[30:33], v[164:167], v[180:183], v[30:33]
	v_mfma_f32_16x16x32_bf16 v[26:29], v[172:175], v[180:183], v[26:29]
	v_mfma_f32_16x16x32_bf16 v[22:25], v[164:167], v[188:191], v[22:25]
	v_mfma_f32_16x16x32_bf16 v[18:21], v[172:175], v[188:191], v[18:21]
	v_mfma_f32_16x16x32_bf16 v[14:17], v[164:167], v[196:199], v[14:17]
	v_mfma_f32_16x16x32_bf16 v[10:13], v[172:175], v[196:199], v[10:13]
	v_mfma_f32_16x16x32_bf16 v[6:9], v[164:167], v[204:207], v[6:9]
	v_mfma_f32_16x16x32_bf16 v[2:5], v[172:175], v[204:207], v[2:5]
	s_setprio 0
	s_barrier
	s_add_i32 s88, 0, 0x18000
	v_add_u32_e32 v134, s88, v1
	s_add_i32 s89, 0, 0x1c000
	ds_read_b128 v[138:141], v134
	ds_read_b128 v[142:145], v134 offset:1024
	ds_read_b128 v[146:149], v134 offset:2048
	ds_read_b128 v[150:153], v134 offset:3072
	v_add_u32_e32 v134, s89, v1
	ds_read_b128 v[160:163], v134
	ds_read_b128 v[164:167], v134 offset:1024
	ds_read_b128 v[168:171], v134 offset:2048
	ds_read_b128 v[172:175], v134 offset:3072
	s_mov_b32 m0, s24
	v_lshl_add_u64 v[210:211], v[208:209], 0, s[20:21]
	ds_read_b128 v[176:179], v158 offset:32768
	ds_read_b128 v[180:183], v158 offset:33792
	ds_read_b128 v[184:187], v158 offset:34816
	ds_read_b128 v[188:191], v158 offset:35840
	ds_read_b128 v[192:195], v158 offset:36864
	ds_read_b128 v[196:199], v158 offset:37888
	ds_read_b128 v[200:203], v158 offset:38912
	ds_read_b128 v[204:207], v158 offset:39936
	global_load_lds_dwordx4 v[210:211], off
	v_lshl_add_u64 v[210:211], v[208:209], 0, s[22:23]
	s_mov_b32 m0, s25
	s_nop 0
	global_load_lds_dwordx4 v[210:211], off
	s_waitcnt vmcnt(8)
	s_waitcnt lgkmcnt(0)
	s_barrier
	s_setprio 1
	s_waitcnt lgkmcnt(0)
	v_mfma_f32_16x16x32_bf16 v[126:129], v[138:141], v[176:179], v[126:129]
	v_mfma_f32_16x16x32_bf16 v[122:125], v[146:149], v[176:179], v[122:125]
	v_mfma_f32_16x16x32_bf16 v[118:121], v[138:141], v[184:187], v[118:121]
	v_mfma_f32_16x16x32_bf16 v[114:117], v[146:149], v[184:187], v[114:117]
	v_mfma_f32_16x16x32_bf16 v[110:113], v[138:141], v[192:195], v[110:113]
	v_mfma_f32_16x16x32_bf16 v[106:109], v[146:149], v[192:195], v[106:109]
	v_mfma_f32_16x16x32_bf16 v[102:105], v[138:141], v[200:203], v[102:105]
	v_mfma_f32_16x16x32_bf16 v[98:101], v[146:149], v[200:203], v[98:101]
	v_mfma_f32_16x16x32_bf16 v[126:129], v[142:145], v[180:183], v[126:129]
	v_mfma_f32_16x16x32_bf16 v[122:125], v[150:153], v[180:183], v[122:125]
	v_mfma_f32_16x16x32_bf16 v[118:121], v[142:145], v[188:191], v[118:121]
	v_mfma_f32_16x16x32_bf16 v[114:117], v[150:153], v[188:191], v[114:117]
	v_mfma_f32_16x16x32_bf16 v[110:113], v[142:145], v[196:199], v[110:113]
	v_mfma_f32_16x16x32_bf16 v[106:109], v[150:153], v[196:199], v[106:109]
	v_mfma_f32_16x16x32_bf16 v[102:105], v[142:145], v[204:207], v[102:105]
	v_mfma_f32_16x16x32_bf16 v[98:101], v[150:153], v[204:207], v[98:101]
	v_mfma_f32_16x16x32_bf16 v[62:65], v[160:163], v[176:179], v[62:65]
	v_mfma_f32_16x16x32_bf16 v[58:61], v[168:171], v[176:179], v[58:61]
	v_mfma_f32_16x16x32_bf16 v[54:57], v[160:163], v[184:187], v[54:57]
	v_mfma_f32_16x16x32_bf16 v[50:53], v[168:171], v[184:187], v[50:53]
	v_mfma_f32_16x16x32_bf16 v[46:49], v[160:163], v[192:195], v[46:49]
	v_mfma_f32_16x16x32_bf16 v[42:45], v[168:171], v[192:195], v[42:45]
	v_mfma_f32_16x16x32_bf16 v[38:41], v[160:163], v[200:203], v[38:41]
	v_mfma_f32_16x16x32_bf16 v[34:37], v[168:171], v[200:203], v[34:37]
	v_mfma_f32_16x16x32_bf16 v[62:65], v[164:167], v[180:183], v[62:65]
	v_mfma_f32_16x16x32_bf16 v[58:61], v[172:175], v[180:183], v[58:61]
	v_mfma_f32_16x16x32_bf16 v[54:57], v[164:167], v[188:191], v[54:57]
	v_mfma_f32_16x16x32_bf16 v[50:53], v[172:175], v[188:191], v[50:53]
	v_mfma_f32_16x16x32_bf16 v[46:49], v[164:167], v[196:199], v[46:49]
	v_mfma_f32_16x16x32_bf16 v[42:45], v[172:175], v[196:199], v[42:45]
	v_mfma_f32_16x16x32_bf16 v[38:41], v[164:167], v[204:207], v[38:41]
	v_mfma_f32_16x16x32_bf16 v[34:37], v[172:175], v[204:207], v[34:37]
	s_setprio 0
	s_barrier
	s_add_i32 s88, s88, s11
	v_lshl_add_u64 v[210:211], v[154:155], 0, s[52:53]
	s_mov_b32 m0, s88
	ds_read_b128 v[176:179], v158 offset:49152
	ds_read_b128 v[180:183], v158 offset:50176
	ds_read_b128 v[184:187], v158 offset:51200
	ds_read_b128 v[188:191], v158 offset:52224
	ds_read_b128 v[192:195], v158 offset:53248
	ds_read_b128 v[196:199], v158 offset:54272
	ds_read_b128 v[200:203], v158 offset:55296
	ds_read_b128 v[204:207], v158 offset:56320
	global_load_lds_dwordx4 v[210:211], off
	v_lshl_add_u64 v[210:211], v[154:155], 0, s[54:55]
	s_add_i32 m0, s88, 0x2000
	s_add_i32 s88, s89, s11
	global_load_lds_dwordx4 v[210:211], off
	v_lshl_add_u64 v[210:211], v[154:155], 0, s[56:57]
	s_mov_b32 m0, s88
	v_lshl_add_u64 v[154:155], v[154:155], 0, s[58:59]
	global_load_lds_dwordx4 v[210:211], off
	s_add_i32 m0, s88, 0x2000
	s_nop 0
	global_load_lds_dwordx4 v[154:155], off
	v_lshl_add_u64 v[154:155], v[208:209], 0, s[52:53]
	s_mov_b32 m0, s33
	s_nop 0
	global_load_lds_dwordx4 v[154:155], off
	v_lshl_add_u64 v[154:155], v[208:209], 0, s[54:55]
	s_mov_b32 m0, s40
	s_nop 0
	global_load_lds_dwordx4 v[154:155], off
	s_waitcnt vmcnt(8)
	s_waitcnt lgkmcnt(0)
	s_barrier
	s_setprio 1
	s_waitcnt lgkmcnt(0)
	v_mfma_f32_16x16x32_bf16 v[94:97], v[138:141], v[176:179], v[94:97]
	v_mfma_f32_16x16x32_bf16 v[90:93], v[146:149], v[176:179], v[90:93]
	v_mfma_f32_16x16x32_bf16 v[86:89], v[138:141], v[184:187], v[86:89]
	v_mfma_f32_16x16x32_bf16 v[82:85], v[146:149], v[184:187], v[82:85]
	v_mfma_f32_16x16x32_bf16 v[78:81], v[138:141], v[192:195], v[78:81]
	v_mfma_f32_16x16x32_bf16 v[74:77], v[146:149], v[192:195], v[74:77]
	v_mfma_f32_16x16x32_bf16 v[70:73], v[138:141], v[200:203], v[70:73]
	v_mfma_f32_16x16x32_bf16 v[66:69], v[146:149], v[200:203], v[66:69]
	v_mfma_f32_16x16x32_bf16 v[94:97], v[142:145], v[180:183], v[94:97]
	v_mfma_f32_16x16x32_bf16 v[90:93], v[150:153], v[180:183], v[90:93]
	v_mfma_f32_16x16x32_bf16 v[86:89], v[142:145], v[188:191], v[86:89]
	v_mfma_f32_16x16x32_bf16 v[82:85], v[150:153], v[188:191], v[82:85]
	v_mfma_f32_16x16x32_bf16 v[78:81], v[142:145], v[196:199], v[78:81]
	v_mfma_f32_16x16x32_bf16 v[74:77], v[150:153], v[196:199], v[74:77]
	v_mfma_f32_16x16x32_bf16 v[70:73], v[142:145], v[204:207], v[70:73]
	v_mfma_f32_16x16x32_bf16 v[66:69], v[150:153], v[204:207], v[66:69]
	v_mfma_f32_16x16x32_bf16 v[30:33], v[160:163], v[176:179], v[30:33]
	v_mfma_f32_16x16x32_bf16 v[26:29], v[168:171], v[176:179], v[26:29]
	v_mfma_f32_16x16x32_bf16 v[22:25], v[160:163], v[184:187], v[22:25]
	v_mfma_f32_16x16x32_bf16 v[18:21], v[168:171], v[184:187], v[18:21]
	v_mfma_f32_16x16x32_bf16 v[14:17], v[160:163], v[192:195], v[14:17]
	v_mfma_f32_16x16x32_bf16 v[10:13], v[168:171], v[192:195], v[10:13]
	v_mfma_f32_16x16x32_bf16 v[6:9], v[160:163], v[200:203], v[6:9]
	v_mfma_f32_16x16x32_bf16 v[2:5], v[168:171], v[200:203], v[2:5]
	v_mfma_f32_16x16x32_bf16 v[30:33], v[164:167], v[180:183], v[30:33]
	v_mfma_f32_16x16x32_bf16 v[26:29], v[172:175], v[180:183], v[26:29]
	v_mfma_f32_16x16x32_bf16 v[22:25], v[164:167], v[188:191], v[22:25]
	v_mfma_f32_16x16x32_bf16 v[18:21], v[172:175], v[188:191], v[18:21]
	v_mfma_f32_16x16x32_bf16 v[14:17], v[164:167], v[196:199], v[14:17]
	v_mfma_f32_16x16x32_bf16 v[10:13], v[172:175], v[196:199], v[10:13]
	v_mfma_f32_16x16x32_bf16 v[6:9], v[164:167], v[204:207], v[6:9]
	v_mfma_f32_16x16x32_bf16 v[2:5], v[172:175], v[204:207], v[2:5]
	s_setprio 0
	s_barrier
	s_add_i32 s87, s87, 2
	s_add_u32 s8, s8, 0x100
	s_addc_u32 s9, s9, 0
	s_add_u32 s65, s65, 0x100
	s_addc_u32 s86, s86, 0
	s_cmp_gt_u32 s87, 29
	s_cbranch_scc0 .LBB0_419
	s_and_b64 vcc, exec, s[60:61]
	s_cbranch_vccz .LBB0_422
	s_barrier

.LBB0_570:
	ds_read_b128 v[140:143], v157
	ds_read_b128 v[144:147], v157 offset:1024
	ds_read_b128 v[148:151], v157 offset:2048
	ds_read_b128 v[152:155], v157 offset:3072
	ds_read_b128 v[186:189], v161
	ds_read_b128 v[190:193], v161 offset:1024
	ds_read_b128 v[198:201], v161 offset:2048
	ds_read_b128 v[202:205], v161 offset:3072
	s_add_u32 s41, s58, 0xfffe0080
	s_addc_u32 s42, s59, -1
	s_cmp_eq_u32 s25, 4
	s_cselect_b32 s43, s4, s42
	s_cselect_b32 s42, s5, s41
	s_cselect_b32 s51, s7, s24
	s_cselect_b32 s50, s12, s13
	v_lshl_add_u64 v[158:159], s[58:59], 0, v[136:137]
	s_add_i32 m0, s84, 0xc000
	ds_read_b128 v[206:209], v165
	ds_read_b128 v[210:213], v165 offset:1024
	ds_read_b128 v[214:217], v165 offset:2048
	ds_read_b128 v[218:221], v165 offset:3072
	ds_read_b128 v[222:225], v165 offset:4096
	ds_read_b128 v[226:229], v165 offset:5120
	ds_read_b128 v[230:233], v165 offset:6144
	ds_read_b128 v[234:237], v165 offset:7168
	global_load_lds_dwordx4 v[158:159], off
	v_lshl_add_u64 v[158:159], v[158:159], 0, s[8:9]
	s_add_i32 m0, s84, 0xe000
	s_nop 0
	global_load_lds_dwordx4 v[158:159], off
	s_waitcnt vmcnt(8)
	s_waitcnt lgkmcnt(0)
	s_barrier
	s_setprio 1
	s_waitcnt lgkmcnt(0)
	v_mfma_f32_16x16x32_bf16 v[18:21], v[140:143], v[206:209], v[18:21]
	v_mfma_f32_16x16x32_bf16 v[22:25], v[148:151], v[206:209], v[22:25]
	v_mfma_f32_16x16x32_bf16 v[26:29], v[140:143], v[214:217], v[26:29]
	v_mfma_f32_16x16x32_bf16 v[30:33], v[148:151], v[214:217], v[30:33]
	v_mfma_f32_16x16x32_bf16 v[2:5], v[140:143], v[222:225], v[2:5]
	v_mfma_f32_16x16x32_bf16 v[6:9], v[148:151], v[222:225], v[6:9]
	v_mfma_f32_16x16x32_bf16 v[10:13], v[140:143], v[230:233], v[10:13]
	v_mfma_f32_16x16x32_bf16 v[14:17], v[148:151], v[230:233], v[14:17]
	v_mfma_f32_16x16x32_bf16 v[18:21], v[144:147], v[210:213], v[18:21]
	v_mfma_f32_16x16x32_bf16 v[22:25], v[152:155], v[210:213], v[22:25]
	v_mfma_f32_16x16x32_bf16 v[26:29], v[144:147], v[218:221], v[26:29]
	v_mfma_f32_16x16x32_bf16 v[30:33], v[152:155], v[218:221], v[30:33]
	v_mfma_f32_16x16x32_bf16 v[2:5], v[144:147], v[226:229], v[2:5]
	v_mfma_f32_16x16x32_bf16 v[6:9], v[152:155], v[226:229], v[6:9]
	v_mfma_f32_16x16x32_bf16 v[10:13], v[144:147], v[234:237], v[10:13]
	v_mfma_f32_16x16x32_bf16 v[14:17], v[152:155], v[234:237], v[14:17]
	v_mfma_f32_16x16x32_bf16 v[84:87], v[186:189], v[206:209], v[84:87]
	v_mfma_f32_16x16x32_bf16 v[88:91], v[198:201], v[206:209], v[88:91]
	v_mfma_f32_16x16x32_bf16 v[92:95], v[186:189], v[214:217], v[92:95]
	v_mfma_f32_16x16x32_bf16 v[96:99], v[198:201], v[214:217], v[96:99]
	v_mfma_f32_16x16x32_bf16 v[68:71], v[186:189], v[222:225], v[68:71]
	v_mfma_f32_16x16x32_bf16 v[72:75], v[198:201], v[222:225], v[72:75]
	v_mfma_f32_16x16x32_bf16 v[76:79], v[186:189], v[230:233], v[76:79]
	v_mfma_f32_16x16x32_bf16 v[80:83], v[198:201], v[230:233], v[80:83]
	v_mfma_f32_16x16x32_bf16 v[84:87], v[190:193], v[210:213], v[84:87]
	v_mfma_f32_16x16x32_bf16 v[88:91], v[202:205], v[210:213], v[88:91]
	v_mfma_f32_16x16x32_bf16 v[92:95], v[190:193], v[218:221], v[92:95]
	v_mfma_f32_16x16x32_bf16 v[96:99], v[202:205], v[218:221], v[96:99]
	v_mfma_f32_16x16x32_bf16 v[68:71], v[190:193], v[226:229], v[68:71]
	v_mfma_f32_16x16x32_bf16 v[72:75], v[202:205], v[226:229], v[72:75]
	v_mfma_f32_16x16x32_bf16 v[76:79], v[190:193], v[234:237], v[76:79]
	v_mfma_f32_16x16x32_bf16 v[80:83], v[202:205], v[234:237], v[80:83]
	s_setprio 0
	s_barrier
	s_add_i32 s41, s94, s67
	v_lshl_add_u64 v[158:159], s[50:51], 0, v[134:135]
	s_mov_b32 m0, s41
	ds_read_b128 v[206:209], v165 offset:16384
	ds_read_b128 v[210:213], v165 offset:17408
	ds_read_b128 v[214:217], v165 offset:18432
	ds_read_b128 v[218:221], v165 offset:19456
	ds_read_b128 v[222:225], v165 offset:20480
	ds_read_b128 v[226:229], v165 offset:21504
	ds_read_b128 v[230:233], v165 offset:22528
	ds_read_b128 v[234:237], v165 offset:23552
	global_load_lds_dwordx4 v[158:159], off
	v_lshl_add_u64 v[162:163], v[158:159], 0, s[8:9]
	s_add_i32 m0, s41, 0x2000
	s_add_i32 s41, s95, s67
	global_load_lds_dwordx4 v[162:163], off
	v_lshl_add_u64 v[162:163], v[158:159], 0, s[18:19]
	s_mov_b32 m0, s41
	s_nop 0
	global_load_lds_dwordx4 v[162:163], off
	v_lshl_add_u64 v[162:163], v[158:159], 0, s[20:21]
	s_add_i32 m0, s41, 0x2000
	s_nop 0
	global_load_lds_dwordx4 v[162:163], off
	v_lshl_add_u64 v[162:163], s[42:43], 0, v[132:133]
	s_mov_b32 m0, s84
	v_lshl_add_u64 v[166:167], v[162:163], 0, s[8:9]
	global_load_lds_dwordx4 v[162:163], off
	s_mov_b32 m0, s85
	s_nop 0
	global_load_lds_dwordx4 v[166:167], off
	s_waitcnt vmcnt(8)
	s_waitcnt lgkmcnt(0)
	s_barrier
	s_setprio 1
	s_waitcnt lgkmcnt(0)
	v_mfma_f32_16x16x32_bf16 v[116:119], v[140:143], v[206:209], v[116:119]
	v_mfma_f32_16x16x32_bf16 v[120:123], v[148:151], v[206:209], v[120:123]
	v_mfma_f32_16x16x32_bf16 v[124:127], v[140:143], v[214:217], v[124:127]
	v_mfma_f32_16x16x32_bf16 v[128:131], v[148:151], v[214:217], v[128:131]
	v_mfma_f32_16x16x32_bf16 v[100:103], v[140:143], v[222:225], v[100:103]
	v_mfma_f32_16x16x32_bf16 v[104:107], v[148:151], v[222:225], v[104:107]
	v_mfma_f32_16x16x32_bf16 v[108:111], v[140:143], v[230:233], v[108:111]
	v_mfma_f32_16x16x32_bf16 v[112:115], v[148:151], v[230:233], v[112:115]
	v_mfma_f32_16x16x32_bf16 v[116:119], v[144:147], v[210:213], v[116:119]
	v_mfma_f32_16x16x32_bf16 v[120:123], v[152:155], v[210:213], v[120:123]
	v_mfma_f32_16x16x32_bf16 v[124:127], v[144:147], v[218:221], v[124:127]
	v_mfma_f32_16x16x32_bf16 v[128:131], v[152:155], v[218:221], v[128:131]
	v_mfma_f32_16x16x32_bf16 v[100:103], v[144:147], v[226:229], v[100:103]
	v_mfma_f32_16x16x32_bf16 v[104:107], v[152:155], v[226:229], v[104:107]
	v_mfma_f32_16x16x32_bf16 v[108:111], v[144:147], v[234:237], v[108:111]
	v_mfma_f32_16x16x32_bf16 v[112:115], v[152:155], v[234:237], v[112:115]
	v_mfma_f32_16x16x32_bf16 v[52:55], v[186:189], v[206:209], v[52:55]
	v_mfma_f32_16x16x32_bf16 v[56:59], v[198:201], v[206:209], v[56:59]
	v_mfma_f32_16x16x32_bf16 v[60:63], v[186:189], v[214:217], v[60:63]
	v_mfma_f32_16x16x32_bf16 v[64:67], v[198:201], v[214:217], v[64:67]
	v_mfma_f32_16x16x32_bf16 v[36:39], v[186:189], v[222:225], v[36:39]
	v_mfma_f32_16x16x32_bf16 v[44:47], v[198:201], v[222:225], v[44:47]
	v_mfma_f32_16x16x32_bf16 v[48:51], v[186:189], v[230:233], v[48:51]
	v_mfma_f32_16x16x32_bf16 v[40:43], v[198:201], v[230:233], v[40:43]
	v_mfma_f32_16x16x32_bf16 v[52:55], v[190:193], v[210:213], v[52:55]
	v_mfma_f32_16x16x32_bf16 v[56:59], v[202:205], v[210:213], v[56:59]
	v_mfma_f32_16x16x32_bf16 v[60:63], v[190:193], v[218:221], v[60:63]
	v_mfma_f32_16x16x32_bf16 v[64:67], v[202:205], v[218:221], v[64:67]
	v_mfma_f32_16x16x32_bf16 v[36:39], v[190:193], v[226:229], v[36:39]
	v_mfma_f32_16x16x32_bf16 v[44:47], v[202:205], v[226:229], v[44:47]
	v_mfma_f32_16x16x32_bf16 v[48:51], v[190:193], v[234:237], v[48:51]
	v_mfma_f32_16x16x32_bf16 v[40:43], v[202:205], v[234:237], v[40:43]
	s_setprio 0
	s_barrier
	s_add_i32 s41, 0, 0x18000
	v_add_u32_e32 v34, s41, v1
	s_add_i32 s42, 0, 0x1c000
	ds_read_b128 v[140:143], v34
	ds_read_b128 v[144:147], v34 offset:1024
	ds_read_b128 v[148:151], v34 offset:2048
	ds_read_b128 v[152:155], v34 offset:3072
	v_add_u32_e32 v34, s42, v1
	ds_read_b128 v[186:189], v34
	ds_read_b128 v[190:193], v34 offset:1024
	ds_read_b128 v[198:201], v34 offset:2048
	ds_read_b128 v[202:205], v34 offset:3072
	s_mov_b32 m0, s86
	v_lshl_add_u64 v[166:167], v[162:163], 0, s[18:19]
	ds_read_b128 v[206:209], v165 offset:32768
	ds_read_b128 v[210:213], v165 offset:33792
	ds_read_b128 v[214:217], v165 offset:34816
	ds_read_b128 v[218:221], v165 offset:35840
	ds_read_b128 v[222:225], v165 offset:36864
	ds_read_b128 v[226:229], v165 offset:37888
	ds_read_b128 v[230:233], v165 offset:38912
	ds_read_b128 v[234:237], v165 offset:39936
	global_load_lds_dwordx4 v[166:167], off
	v_lshl_add_u64 v[166:167], v[162:163], 0, s[20:21]
	s_mov_b32 m0, s87
	s_nop 0
	global_load_lds_dwordx4 v[166:167], off
	s_waitcnt vmcnt(8)
	s_waitcnt lgkmcnt(0)
	s_barrier
	s_setprio 1
	s_waitcnt lgkmcnt(0)
	v_mfma_f32_16x16x32_bf16 v[18:21], v[140:143], v[206:209], v[18:21]
	v_mfma_f32_16x16x32_bf16 v[22:25], v[148:151], v[206:209], v[22:25]
	v_mfma_f32_16x16x32_bf16 v[26:29], v[140:143], v[214:217], v[26:29]
	v_mfma_f32_16x16x32_bf16 v[30:33], v[148:151], v[214:217], v[30:33]
	v_mfma_f32_16x16x32_bf16 v[2:5], v[140:143], v[222:225], v[2:5]
	v_mfma_f32_16x16x32_bf16 v[6:9], v[148:151], v[222:225], v[6:9]
	v_mfma_f32_16x16x32_bf16 v[10:13], v[140:143], v[230:233], v[10:13]
	v_mfma_f32_16x16x32_bf16 v[14:17], v[148:151], v[230:233], v[14:17]
	v_mfma_f32_16x16x32_bf16 v[18:21], v[144:147], v[210:213], v[18:21]
	v_mfma_f32_16x16x32_bf16 v[22:25], v[152:155], v[210:213], v[22:25]
	v_mfma_f32_16x16x32_bf16 v[26:29], v[144:147], v[218:221], v[26:29]
	v_mfma_f32_16x16x32_bf16 v[30:33], v[152:155], v[218:221], v[30:33]
	v_mfma_f32_16x16x32_bf16 v[2:5], v[144:147], v[226:229], v[2:5]
	v_mfma_f32_16x16x32_bf16 v[6:9], v[152:155], v[226:229], v[6:9]
	v_mfma_f32_16x16x32_bf16 v[10:13], v[144:147], v[234:237], v[10:13]
	v_mfma_f32_16x16x32_bf16 v[14:17], v[152:155], v[234:237], v[14:17]
	v_mfma_f32_16x16x32_bf16 v[84:87], v[186:189], v[206:209], v[84:87]
	v_mfma_f32_16x16x32_bf16 v[88:91], v[198:201], v[206:209], v[88:91]
	v_mfma_f32_16x16x32_bf16 v[92:95], v[186:189], v[214:217], v[92:95]
	v_mfma_f32_16x16x32_bf16 v[96:99], v[198:201], v[214:217], v[96:99]
	v_mfma_f32_16x16x32_bf16 v[68:71], v[186:189], v[222:225], v[68:71]
	v_mfma_f32_16x16x32_bf16 v[72:75], v[198:201], v[222:225], v[72:75]
	v_mfma_f32_16x16x32_bf16 v[76:79], v[186:189], v[230:233], v[76:79]
	v_mfma_f32_16x16x32_bf16 v[80:83], v[198:201], v[230:233], v[80:83]
	v_mfma_f32_16x16x32_bf16 v[84:87], v[190:193], v[210:213], v[84:87]
	v_mfma_f32_16x16x32_bf16 v[88:91], v[202:205], v[210:213], v[88:91]
	v_mfma_f32_16x16x32_bf16 v[92:95], v[190:193], v[218:221], v[92:95]
	v_mfma_f32_16x16x32_bf16 v[96:99], v[202:205], v[218:221], v[96:99]
	v_mfma_f32_16x16x32_bf16 v[68:71], v[190:193], v[226:229], v[68:71]
	v_mfma_f32_16x16x32_bf16 v[72:75], v[202:205], v[226:229], v[72:75]
	v_mfma_f32_16x16x32_bf16 v[76:79], v[190:193], v[234:237], v[76:79]
	v_mfma_f32_16x16x32_bf16 v[80:83], v[202:205], v[234:237], v[80:83]
	s_setprio 0
	s_barrier
	s_add_i32 s41, s41, s67
	v_lshl_add_u64 v[166:167], v[158:159], 0, s[34:35]
	s_mov_b32 m0, s41
	ds_read_b128 v[206:209], v165 offset:49152
	ds_read_b128 v[210:213], v165 offset:50176
	ds_read_b128 v[214:217], v165 offset:51200
	ds_read_b128 v[218:221], v165 offset:52224
	ds_read_b128 v[222:225], v165 offset:53248
	ds_read_b128 v[226:229], v165 offset:54272
	ds_read_b128 v[230:233], v165 offset:55296
	ds_read_b128 v[234:237], v165 offset:56320
	global_load_lds_dwordx4 v[166:167], off
	v_lshl_add_u64 v[166:167], v[158:159], 0, s[36:37]
	s_add_i32 m0, s41, 0x2000
	s_add_i32 s41, s42, s67
	global_load_lds_dwordx4 v[166:167], off
	v_lshl_add_u64 v[166:167], v[158:159], 0, s[38:39]
	s_mov_b32 m0, s41
	v_lshl_add_u64 v[158:159], v[158:159], 0, s[44:45]
	global_load_lds_dwordx4 v[166:167], off
	s_add_i32 m0, s41, 0x2000
	s_nop 0
	global_load_lds_dwordx4 v[158:159], off
	v_lshl_add_u64 v[158:159], v[162:163], 0, s[34:35]
	s_mov_b32 m0, s89
	s_nop 0
	global_load_lds_dwordx4 v[158:159], off
	v_lshl_add_u64 v[158:159], v[162:163], 0, s[36:37]
	s_mov_b32 m0, s90
	s_nop 0
	global_load_lds_dwordx4 v[158:159], off
	s_waitcnt vmcnt(8)
	s_waitcnt lgkmcnt(0)
	s_barrier
	s_setprio 1
	s_waitcnt lgkmcnt(0)
	v_mfma_f32_16x16x32_bf16 v[116:119], v[140:143], v[206:209], v[116:119]
	v_mfma_f32_16x16x32_bf16 v[120:123], v[148:151], v[206:209], v[120:123]
	v_mfma_f32_16x16x32_bf16 v[124:127], v[140:143], v[214:217], v[124:127]
	v_mfma_f32_16x16x32_bf16 v[128:131], v[148:151], v[214:217], v[128:131]
	v_mfma_f32_16x16x32_bf16 v[100:103], v[140:143], v[222:225], v[100:103]
	v_mfma_f32_16x16x32_bf16 v[104:107], v[148:151], v[222:225], v[104:107]
	v_mfma_f32_16x16x32_bf16 v[108:111], v[140:143], v[230:233], v[108:111]
	v_mfma_f32_16x16x32_bf16 v[112:115], v[148:151], v[230:233], v[112:115]
	v_mfma_f32_16x16x32_bf16 v[116:119], v[144:147], v[210:213], v[116:119]
	v_mfma_f32_16x16x32_bf16 v[120:123], v[152:155], v[210:213], v[120:123]
	v_mfma_f32_16x16x32_bf16 v[124:127], v[144:147], v[218:221], v[124:127]
	v_mfma_f32_16x16x32_bf16 v[128:131], v[152:155], v[218:221], v[128:131]
	v_mfma_f32_16x16x32_bf16 v[100:103], v[144:147], v[226:229], v[100:103]
	v_mfma_f32_16x16x32_bf16 v[104:107], v[152:155], v[226:229], v[104:107]
	v_mfma_f32_16x16x32_bf16 v[108:111], v[144:147], v[234:237], v[108:111]
	v_mfma_f32_16x16x32_bf16 v[112:115], v[152:155], v[234:237], v[112:115]
	v_mfma_f32_16x16x32_bf16 v[52:55], v[186:189], v[206:209], v[52:55]
	v_mfma_f32_16x16x32_bf16 v[56:59], v[198:201], v[206:209], v[56:59]
	v_mfma_f32_16x16x32_bf16 v[60:63], v[186:189], v[214:217], v[60:63]
	v_mfma_f32_16x16x32_bf16 v[64:67], v[198:201], v[214:217], v[64:67]
	v_mfma_f32_16x16x32_bf16 v[36:39], v[186:189], v[222:225], v[36:39]
	v_mfma_f32_16x16x32_bf16 v[44:47], v[198:201], v[222:225], v[44:47]
	v_mfma_f32_16x16x32_bf16 v[48:51], v[186:189], v[230:233], v[48:51]
	v_mfma_f32_16x16x32_bf16 v[40:43], v[198:201], v[230:233], v[40:43]
	v_mfma_f32_16x16x32_bf16 v[52:55], v[190:193], v[210:213], v[52:55]
	v_mfma_f32_16x16x32_bf16 v[56:59], v[202:205], v[210:213], v[56:59]
	v_mfma_f32_16x16x32_bf16 v[60:63], v[190:193], v[218:221], v[60:63]
	v_mfma_f32_16x16x32_bf16 v[64:67], v[202:205], v[218:221], v[64:67]
	v_mfma_f32_16x16x32_bf16 v[36:39], v[190:193], v[226:229], v[36:39]
	v_mfma_f32_16x16x32_bf16 v[44:47], v[202:205], v[226:229], v[44:47]
	v_mfma_f32_16x16x32_bf16 v[48:51], v[190:193], v[234:237], v[48:51]
	v_mfma_f32_16x16x32_bf16 v[40:43], v[202:205], v[234:237], v[40:43]
	s_setprio 0
	s_barrier
	s_add_i32 s25, s25, 2
	s_add_u32 s58, s58, 0x100
	s_addc_u32 s59, s59, 0
	s_add_u32 s13, s13, 0x100
	s_addc_u32 s24, s24, 0
	s_cmp_gt_u32 s25, 5
	s_cbranch_scc0 .LBB0_570
	s_and_b64 vcc, exec, s[46:47]
	s_cbranch_vccz .LBB0_573
	s_barrier

.LBB0_629:
	ds_read_b128 v[4:7], v150
	ds_read_b128 v[8:11], v150 offset:1024
	ds_read_b128 v[12:15], v150 offset:2048
	ds_read_b128 v[16:19], v150 offset:3072
	ds_read_b128 v[20:23], v151
	ds_read_b128 v[24:27], v151 offset:1024
	ds_read_b128 v[28:31], v151 offset:2048
	ds_read_b128 v[36:39], v151 offset:3072
	s_ashr_i32 s67, s66, 31
	s_lshl_b64 s[86:87], s[66:67], 17
	s_add_u32 s86, s1, s86
	s_addc_u32 s87, s3, s87
	s_and_b64 s[88:89], s[96:97], exec
	s_cselect_b32 s93, s87, s95
	s_cselect_b32 s92, s86, s94
	s_ashr_i32 s85, s84, 31
	s_lshl_b64 s[88:89], s[84:85], 17
	s_add_u32 s88, s4, s88
	s_addc_u32 s89, s5, s89
	s_and_b64 s[96:97], s[96:97], exec
	s_cselect_b32 s97, s89, s91
	s_cselect_b32 s96, s88, s90
	v_lshl_add_u64 v[2:3], s[94:95], 0, v[134:135]
	s_mov_b32 m0, s51
	v_lshl_add_u64 v[32:33], v[2:3], 0, s[38:39]
	ds_read_b128 v[40:43], v152
	ds_read_b128 v[44:47], v152 offset:1024
	ds_read_b128 v[48:51], v152 offset:2048
	ds_read_b128 v[52:55], v152 offset:3072
	ds_read_b128 v[56:59], v152 offset:4096
	ds_read_b128 v[60:63], v152 offset:5120
	ds_read_b128 v[64:67], v152 offset:6144
	ds_read_b128 v[68:71], v152 offset:7168
	global_load_lds_dwordx4 v[32:33], off
	v_lshl_add_u64 v[32:33], v[2:3], 0, s[44:45]
	s_mov_b32 m0, s18
	s_nop 0
	global_load_lds_dwordx4 v[32:33], off
	s_waitcnt vmcnt(8)
	s_waitcnt lgkmcnt(0)
	s_barrier
	s_setprio 1
	s_waitcnt lgkmcnt(0)
	v_mfma_f32_16x16x32_bf16 v[72:75], v[4:7], v[40:43], 0
	v_mfma_f32_16x16x32_bf16 v[76:79], v[12:15], v[40:43], 0
	v_mfma_f32_16x16x32_bf16 v[80:83], v[4:7], v[48:51], 0
	v_mfma_f32_16x16x32_bf16 v[84:87], v[12:15], v[48:51], 0
	v_mfma_f32_16x16x32_bf16 v[88:91], v[4:7], v[56:59], 0
	v_mfma_f32_16x16x32_bf16 v[92:95], v[12:15], v[56:59], 0
	v_mfma_f32_16x16x32_bf16 v[96:99], v[4:7], v[64:67], 0
	v_mfma_f32_16x16x32_bf16 v[100:103], v[12:15], v[64:67], 0
	v_mfma_f32_16x16x32_bf16 v[72:75], v[8:11], v[44:47], v[72:75]
	v_mfma_f32_16x16x32_bf16 v[76:79], v[16:19], v[44:47], v[76:79]
	v_mfma_f32_16x16x32_bf16 v[80:83], v[8:11], v[52:55], v[80:83]
	v_mfma_f32_16x16x32_bf16 v[84:87], v[16:19], v[52:55], v[84:87]
	v_mfma_f32_16x16x32_bf16 v[88:91], v[8:11], v[60:63], v[88:91]
	v_mfma_f32_16x16x32_bf16 v[92:95], v[16:19], v[60:63], v[92:95]
	v_mfma_f32_16x16x32_bf16 v[96:99], v[8:11], v[68:71], v[96:99]
	v_mfma_f32_16x16x32_bf16 v[100:103], v[16:19], v[68:71], v[100:103]
	v_mfma_f32_16x16x32_bf16 v[104:107], v[20:23], v[40:43], 0
	v_mfma_f32_16x16x32_bf16 v[40:43], v[28:31], v[40:43], 0
	v_mfma_f32_16x16x32_bf16 v[104:107], v[24:27], v[44:47], v[104:107]
	v_mfma_f32_16x16x32_bf16 v[40:43], v[36:39], v[44:47], v[40:43]
	v_mfma_f32_16x16x32_bf16 v[44:47], v[20:23], v[48:51], 0
	v_mfma_f32_16x16x32_bf16 v[48:51], v[28:31], v[48:51], 0
	v_mfma_f32_16x16x32_bf16 v[44:47], v[24:27], v[52:55], v[44:47]
	v_mfma_f32_16x16x32_bf16 v[48:51], v[36:39], v[52:55], v[48:51]
	v_mfma_f32_16x16x32_bf16 v[52:55], v[20:23], v[56:59], 0
	v_mfma_f32_16x16x32_bf16 v[56:59], v[28:31], v[56:59], 0
	v_mfma_f32_16x16x32_bf16 v[52:55], v[24:27], v[60:63], v[52:55]
	v_mfma_f32_16x16x32_bf16 v[56:59], v[36:39], v[60:63], v[56:59]
	v_mfma_f32_16x16x32_bf16 v[60:63], v[20:23], v[64:67], 0
	v_mfma_f32_16x16x32_bf16 v[64:67], v[28:31], v[64:67], 0
	v_mfma_f32_16x16x32_bf16 v[60:63], v[24:27], v[68:71], v[60:63]
	v_mfma_f32_16x16x32_bf16 v[64:67], v[36:39], v[68:71], v[64:67]
	s_setprio 0
	s_barrier
	v_lshl_add_u64 v[32:33], s[90:91], 0, v[132:133]
	s_mov_b32 m0, s19
	v_lshl_add_u64 v[140:141], v[32:33], 0, s[48:49]
	ds_read_b128 v[68:71], v152 offset:16384
	ds_read_b128 v[108:111], v152 offset:17408
	ds_read_b128 v[112:115], v152 offset:18432
	ds_read_b128 v[116:119], v152 offset:19456
	ds_read_b128 v[120:123], v152 offset:20480
	ds_read_b128 v[124:127], v152 offset:21504
	ds_read_b128 v[128:131], v152 offset:22528
	ds_read_b128 v[136:139], v152 offset:23552
	global_load_lds_dwordx4 v[140:141], off
	v_lshl_add_u64 v[140:141], v[32:33], 0, s[52:53]
	s_mov_b32 m0, s12
	s_add_i32 s9, s13, 0x2000
	global_load_lds_dwordx4 v[140:141], off
	v_lshl_add_u64 v[140:141], v[32:33], 0, s[54:55]
	s_mov_b32 m0, s13
	s_nop 0
	global_load_lds_dwordx4 v[140:141], off
	v_lshl_add_u64 v[140:141], v[32:33], 0, s[56:57]
	s_mov_b32 m0, s9
	s_nop 0
	global_load_lds_dwordx4 v[140:141], off
	v_lshl_add_u64 v[140:141], v[2:3], 0, s[48:49]
	s_mov_b32 m0, s11
	s_nop 0
	global_load_lds_dwordx4 v[140:141], off
	v_lshl_add_u64 v[140:141], v[2:3], 0, s[52:53]
	s_mov_b32 m0, s28
	s_nop 0
	global_load_lds_dwordx4 v[140:141], off
	s_waitcnt vmcnt(8)
	s_waitcnt lgkmcnt(0)
	s_barrier
	s_setprio 1
	s_waitcnt lgkmcnt(0)
	v_mfma_f32_16x16x32_bf16 v[140:143], v[4:7], v[68:71], 0
	v_mfma_f32_16x16x32_bf16 v[156:159], v[4:7], v[112:115], 0
	v_mfma_f32_16x16x32_bf16 v[164:167], v[4:7], v[120:123], 0
	v_mfma_f32_16x16x32_bf16 v[4:7], v[4:7], v[128:131], 0
	v_mfma_f32_16x16x32_bf16 v[140:143], v[8:11], v[108:111], v[140:143]
	v_mfma_f32_16x16x32_bf16 v[156:159], v[8:11], v[116:119], v[156:159]
	v_mfma_f32_16x16x32_bf16 v[164:167], v[8:11], v[124:127], v[164:167]
	v_mfma_f32_16x16x32_bf16 v[4:7], v[8:11], v[136:139], v[4:7]
	v_mfma_f32_16x16x32_bf16 v[8:11], v[12:15], v[128:131], 0
	v_mfma_f32_16x16x32_bf16 v[144:147], v[12:15], v[68:71], 0
	v_mfma_f32_16x16x32_bf16 v[160:163], v[12:15], v[112:115], 0
	v_mfma_f32_16x16x32_bf16 v[168:171], v[12:15], v[120:123], 0
	v_mfma_f32_16x16x32_bf16 v[8:11], v[16:19], v[136:139], v[8:11]
	v_mfma_f32_16x16x32_bf16 v[144:147], v[16:19], v[108:111], v[144:147]
	v_mfma_f32_16x16x32_bf16 v[160:163], v[16:19], v[116:119], v[160:163]
	v_mfma_f32_16x16x32_bf16 v[168:171], v[16:19], v[124:127], v[168:171]
	v_mfma_f32_16x16x32_bf16 v[12:15], v[20:23], v[68:71], 0
	v_mfma_f32_16x16x32_bf16 v[16:19], v[28:31], v[68:71], 0
	v_mfma_f32_16x16x32_bf16 v[12:15], v[24:27], v[108:111], v[12:15]
	v_mfma_f32_16x16x32_bf16 v[16:19], v[36:39], v[108:111], v[16:19]
	v_mfma_f32_16x16x32_bf16 v[68:71], v[20:23], v[112:115], 0
	v_mfma_f32_16x16x32_bf16 v[108:111], v[28:31], v[112:115], 0
	v_mfma_f32_16x16x32_bf16 v[112:115], v[20:23], v[120:123], 0
	v_mfma_f32_16x16x32_bf16 v[20:23], v[20:23], v[128:131], 0
	v_mfma_f32_16x16x32_bf16 v[68:71], v[24:27], v[116:119], v[68:71]
	v_mfma_f32_16x16x32_bf16 v[108:111], v[36:39], v[116:119], v[108:111]
	v_mfma_f32_16x16x32_bf16 v[112:115], v[24:27], v[124:127], v[112:115]
	v_mfma_f32_16x16x32_bf16 v[116:119], v[28:31], v[120:123], 0
	v_mfma_f32_16x16x32_bf16 v[20:23], v[24:27], v[136:139], v[20:23]
	v_mfma_f32_16x16x32_bf16 v[24:27], v[28:31], v[128:131], 0
	v_mfma_f32_16x16x32_bf16 v[116:119], v[36:39], v[124:127], v[116:119]
	v_mfma_f32_16x16x32_bf16 v[24:27], v[36:39], v[136:139], v[24:27]
	s_setprio 0
	s_barrier
	s_add_i32 s91, 0, 0x18000
	s_add_i32 s85, 0, 0x1c000
	v_add_u32_e32 v34, s91, v1
	v_add_u32_e32 v155, s85, v1
	ds_read_b128 v[28:31], v34
	ds_read_b128 v[36:39], v34 offset:1024
	ds_read_b128 v[120:123], v34 offset:2048
	ds_read_b128 v[124:127], v34 offset:3072
	ds_read_b128 v[128:131], v155
	ds_read_b128 v[136:139], v155 offset:1024
	ds_read_b128 v[172:175], v155 offset:2048
	ds_read_b128 v[176:179], v155 offset:3072
	s_mov_b32 m0, s29
	v_lshl_add_u64 v[148:149], v[2:3], 0, s[54:55]
	ds_read_b128 v[180:183], v152 offset:32768
	ds_read_b128 v[184:187], v152 offset:33792
	ds_read_b128 v[188:191], v152 offset:34816
	ds_read_b128 v[192:195], v152 offset:35840
	ds_read_b128 v[196:199], v152 offset:36864
	ds_read_b128 v[200:203], v152 offset:37888
	ds_read_b128 v[204:207], v152 offset:38912
	ds_read_b128 v[208:211], v152 offset:39936
	global_load_lds_dwordx4 v[148:149], off
	v_lshl_add_u64 v[148:149], v[2:3], 0, s[56:57]
	s_mov_b32 m0, s33
	s_nop 0
	global_load_lds_dwordx4 v[148:149], off
	s_waitcnt vmcnt(8)
	s_waitcnt lgkmcnt(0)
	s_barrier
	s_setprio 1
	s_waitcnt lgkmcnt(0)
	v_mfma_f32_16x16x32_bf16 v[72:75], v[28:31], v[180:183], v[72:75]
	v_mfma_f32_16x16x32_bf16 v[76:79], v[120:123], v[180:183], v[76:79]
	v_mfma_f32_16x16x32_bf16 v[80:83], v[28:31], v[188:191], v[80:83]
	v_mfma_f32_16x16x32_bf16 v[84:87], v[120:123], v[188:191], v[84:87]
	v_mfma_f32_16x16x32_bf16 v[88:91], v[28:31], v[196:199], v[88:91]
	v_mfma_f32_16x16x32_bf16 v[92:95], v[120:123], v[196:199], v[92:95]
	v_mfma_f32_16x16x32_bf16 v[96:99], v[28:31], v[204:207], v[96:99]
	v_mfma_f32_16x16x32_bf16 v[100:103], v[120:123], v[204:207], v[100:103]
	v_mfma_f32_16x16x32_bf16 v[72:75], v[36:39], v[184:187], v[72:75]
	v_mfma_f32_16x16x32_bf16 v[76:79], v[124:127], v[184:187], v[76:79]
	v_mfma_f32_16x16x32_bf16 v[80:83], v[36:39], v[192:195], v[80:83]
	v_mfma_f32_16x16x32_bf16 v[84:87], v[124:127], v[192:195], v[84:87]
	v_mfma_f32_16x16x32_bf16 v[88:91], v[36:39], v[200:203], v[88:91]
	v_mfma_f32_16x16x32_bf16 v[92:95], v[124:127], v[200:203], v[92:95]
	v_mfma_f32_16x16x32_bf16 v[96:99], v[36:39], v[208:211], v[96:99]
	v_mfma_f32_16x16x32_bf16 v[100:103], v[124:127], v[208:211], v[100:103]
	v_mfma_f32_16x16x32_bf16 v[104:107], v[128:131], v[180:183], v[104:107]
	v_mfma_f32_16x16x32_bf16 v[40:43], v[172:175], v[180:183], v[40:43]
	v_mfma_f32_16x16x32_bf16 v[44:47], v[128:131], v[188:191], v[44:47]
	v_mfma_f32_16x16x32_bf16 v[48:51], v[172:175], v[188:191], v[48:51]
	v_mfma_f32_16x16x32_bf16 v[52:55], v[128:131], v[196:199], v[52:55]
	v_mfma_f32_16x16x32_bf16 v[56:59], v[172:175], v[196:199], v[56:59]
	v_mfma_f32_16x16x32_bf16 v[60:63], v[128:131], v[204:207], v[60:63]
	v_mfma_f32_16x16x32_bf16 v[64:67], v[172:175], v[204:207], v[64:67]
	v_mfma_f32_16x16x32_bf16 v[104:107], v[136:139], v[184:187], v[104:107]
	v_mfma_f32_16x16x32_bf16 v[40:43], v[176:179], v[184:187], v[40:43]
	v_mfma_f32_16x16x32_bf16 v[44:47], v[136:139], v[192:195], v[44:47]
	v_mfma_f32_16x16x32_bf16 v[48:51], v[176:179], v[192:195], v[48:51]
	v_mfma_f32_16x16x32_bf16 v[52:55], v[136:139], v[200:203], v[52:55]
	v_mfma_f32_16x16x32_bf16 v[56:59], v[176:179], v[200:203], v[56:59]
	v_mfma_f32_16x16x32_bf16 v[60:63], v[136:139], v[208:211], v[60:63]
	v_mfma_f32_16x16x32_bf16 v[64:67], v[176:179], v[208:211], v[64:67]
	s_setprio 0
	s_barrier
	s_add_i32 s91, s91, s10
	v_lshl_add_u64 v[148:149], v[32:33], 0, s[58:59]
	s_mov_b32 m0, s91
	s_add_i32 s67, s91, 0x2000
	ds_read_b128 v[180:183], v152 offset:49152
	ds_read_b128 v[184:187], v152 offset:50176
	ds_read_b128 v[188:191], v152 offset:51200
	ds_read_b128 v[192:195], v152 offset:52224
	ds_read_b128 v[196:199], v152 offset:53248
	ds_read_b128 v[200:203], v152 offset:54272
	ds_read_b128 v[204:207], v152 offset:55296
	ds_read_b128 v[208:211], v152 offset:56320
	global_load_lds_dwordx4 v[148:149], off
	v_lshl_add_u64 v[148:149], v[32:33], 0, s[60:61]
	s_mov_b32 m0, s67
	s_add_i32 s85, s85, s10
	global_load_lds_dwordx4 v[148:149], off
	v_lshl_add_u64 v[148:149], v[32:33], 0, s[62:63]
	s_mov_b32 m0, s85
	s_add_i32 s90, s85, 0x2000
	global_load_lds_dwordx4 v[148:149], off
	v_lshl_add_u64 v[32:33], v[32:33], 0, s[64:65]
	s_mov_b32 m0, s90
	s_nop 0
	global_load_lds_dwordx4 v[32:33], off
	v_lshl_add_u64 v[32:33], v[2:3], 0, s[58:59]
	s_mov_b32 m0, s41
	s_nop 0
	global_load_lds_dwordx4 v[32:33], off
	v_lshl_add_u64 v[32:33], v[2:3], 0, s[60:61]
	s_mov_b32 m0, s42
	s_nop 0
	global_load_lds_dwordx4 v[32:33], off
	s_waitcnt vmcnt(8)
	s_waitcnt lgkmcnt(0)
	s_barrier
	s_setprio 1
	s_waitcnt lgkmcnt(0)
	v_mfma_f32_16x16x32_bf16 v[4:7], v[28:31], v[204:207], v[4:7]
	v_mfma_f32_16x16x32_bf16 v[8:11], v[120:123], v[204:207], v[8:11]
	v_mfma_f32_16x16x32_bf16 v[140:143], v[28:31], v[180:183], v[140:143]
	v_mfma_f32_16x16x32_bf16 v[144:147], v[120:123], v[180:183], v[144:147]
	v_mfma_f32_16x16x32_bf16 v[156:159], v[28:31], v[188:191], v[156:159]
	v_mfma_f32_16x16x32_bf16 v[160:163], v[120:123], v[188:191], v[160:163]
	v_mfma_f32_16x16x32_bf16 v[164:167], v[28:31], v[196:199], v[164:167]
	v_mfma_f32_16x16x32_bf16 v[168:171], v[120:123], v[196:199], v[168:171]
	v_mfma_f32_16x16x32_bf16 v[4:7], v[36:39], v[208:211], v[4:7]
	v_mfma_f32_16x16x32_bf16 v[8:11], v[124:127], v[208:211], v[8:11]
	v_mfma_f32_16x16x32_bf16 v[140:143], v[36:39], v[184:187], v[140:143]
	v_mfma_f32_16x16x32_bf16 v[144:147], v[124:127], v[184:187], v[144:147]
	v_mfma_f32_16x16x32_bf16 v[156:159], v[36:39], v[192:195], v[156:159]
	v_mfma_f32_16x16x32_bf16 v[160:163], v[124:127], v[192:195], v[160:163]
	v_mfma_f32_16x16x32_bf16 v[164:167], v[36:39], v[200:203], v[164:167]
	v_mfma_f32_16x16x32_bf16 v[168:171], v[124:127], v[200:203], v[168:171]
	v_mfma_f32_16x16x32_bf16 v[12:15], v[128:131], v[180:183], v[12:15]
	v_mfma_f32_16x16x32_bf16 v[16:19], v[172:175], v[180:183], v[16:19]
	v_mfma_f32_16x16x32_bf16 v[28:31], v[128:131], v[188:191], v[68:71]
	v_mfma_f32_16x16x32_bf16 v[36:39], v[172:175], v[188:191], v[108:111]
	v_mfma_f32_16x16x32_bf16 v[68:71], v[128:131], v[196:199], v[112:115]
	v_mfma_f32_16x16x32_bf16 v[108:111], v[172:175], v[196:199], v[116:119]
	v_mfma_f32_16x16x32_bf16 v[20:23], v[128:131], v[204:207], v[20:23]
	v_mfma_f32_16x16x32_bf16 v[24:27], v[172:175], v[204:207], v[24:27]
	v_mfma_f32_16x16x32_bf16 v[12:15], v[136:139], v[184:187], v[12:15]
	v_mfma_f32_16x16x32_bf16 v[16:19], v[176:179], v[184:187], v[16:19]
	v_mfma_f32_16x16x32_bf16 v[28:31], v[136:139], v[192:195], v[28:31]
	v_mfma_f32_16x16x32_bf16 v[36:39], v[176:179], v[192:195], v[36:39]
	v_mfma_f32_16x16x32_bf16 v[68:71], v[136:139], v[200:203], v[68:71]
	v_mfma_f32_16x16x32_bf16 v[108:111], v[176:179], v[200:203], v[108:111]
	v_mfma_f32_16x16x32_bf16 v[20:23], v[136:139], v[208:211], v[20:23]
	v_mfma_f32_16x16x32_bf16 v[24:27], v[176:179], v[208:211], v[24:27]
	s_setprio 0
	s_barrier
	ds_read_b128 v[112:115], v150
	ds_read_b128 v[116:119], v150 offset:1024
	ds_read_b128 v[120:123], v150 offset:2048
	ds_read_b128 v[124:127], v150 offset:3072
	ds_read_b128 v[128:131], v151
	ds_read_b128 v[136:139], v151 offset:1024
	ds_read_b128 v[172:175], v151 offset:2048
	ds_read_b128 v[176:179], v151 offset:3072
	s_mov_b32 m0, s51
	v_lshl_add_u64 v[32:33], v[2:3], 0, s[62:63]
	ds_read_b128 v[180:183], v152
	ds_read_b128 v[184:187], v152 offset:1024
	ds_read_b128 v[188:191], v152 offset:2048
	ds_read_b128 v[192:195], v152 offset:3072
	ds_read_b128 v[196:199], v152 offset:4096
	ds_read_b128 v[200:203], v152 offset:5120
	ds_read_b128 v[204:207], v152 offset:6144
	ds_read_b128 v[208:211], v152 offset:7168
	global_load_lds_dwordx4 v[32:33], off
	v_lshl_add_u64 v[2:3], v[2:3], 0, s[64:65]
	s_mov_b32 m0, s18
	s_nop 0
	global_load_lds_dwordx4 v[2:3], off
	s_waitcnt vmcnt(8)
	s_waitcnt lgkmcnt(0)
	s_barrier
	s_setprio 1
	s_waitcnt lgkmcnt(0)
	v_mfma_f32_16x16x32_bf16 v[72:75], v[112:115], v[180:183], v[72:75]
	v_mfma_f32_16x16x32_bf16 v[76:79], v[120:123], v[180:183], v[76:79]
	v_mfma_f32_16x16x32_bf16 v[80:83], v[112:115], v[188:191], v[80:83]
	v_mfma_f32_16x16x32_bf16 v[84:87], v[120:123], v[188:191], v[84:87]
	v_mfma_f32_16x16x32_bf16 v[88:91], v[112:115], v[196:199], v[88:91]
	v_mfma_f32_16x16x32_bf16 v[92:95], v[120:123], v[196:199], v[92:95]
	v_mfma_f32_16x16x32_bf16 v[96:99], v[112:115], v[204:207], v[96:99]
	v_mfma_f32_16x16x32_bf16 v[100:103], v[120:123], v[204:207], v[100:103]
	v_mfma_f32_16x16x32_bf16 v[72:75], v[116:119], v[184:187], v[72:75]
	v_mfma_f32_16x16x32_bf16 v[76:79], v[124:127], v[184:187], v[76:79]
	v_mfma_f32_16x16x32_bf16 v[80:83], v[116:119], v[192:195], v[80:83]
	v_mfma_f32_16x16x32_bf16 v[84:87], v[124:127], v[192:195], v[84:87]
	v_mfma_f32_16x16x32_bf16 v[88:91], v[116:119], v[200:203], v[88:91]
	v_mfma_f32_16x16x32_bf16 v[92:95], v[124:127], v[200:203], v[92:95]
	v_mfma_f32_16x16x32_bf16 v[96:99], v[116:119], v[208:211], v[96:99]
	v_mfma_f32_16x16x32_bf16 v[100:103], v[124:127], v[208:211], v[100:103]
	v_mfma_f32_16x16x32_bf16 v[104:107], v[128:131], v[180:183], v[104:107]
	v_mfma_f32_16x16x32_bf16 v[40:43], v[172:175], v[180:183], v[40:43]
	v_mfma_f32_16x16x32_bf16 v[44:47], v[128:131], v[188:191], v[44:47]
	v_mfma_f32_16x16x32_bf16 v[48:51], v[172:175], v[188:191], v[48:51]
	v_mfma_f32_16x16x32_bf16 v[52:55], v[128:131], v[196:199], v[52:55]
	v_mfma_f32_16x16x32_bf16 v[56:59], v[172:175], v[196:199], v[56:59]
	v_mfma_f32_16x16x32_bf16 v[60:63], v[128:131], v[204:207], v[60:63]
	v_mfma_f32_16x16x32_bf16 v[64:67], v[172:175], v[204:207], v[64:67]
	v_mfma_f32_16x16x32_bf16 v[104:107], v[136:139], v[184:187], v[104:107]
	v_mfma_f32_16x16x32_bf16 v[40:43], v[176:179], v[184:187], v[40:43]
	v_mfma_f32_16x16x32_bf16 v[44:47], v[136:139], v[192:195], v[44:47]
	v_mfma_f32_16x16x32_bf16 v[48:51], v[176:179], v[192:195], v[48:51]
	v_mfma_f32_16x16x32_bf16 v[52:55], v[136:139], v[200:203], v[52:55]
	v_mfma_f32_16x16x32_bf16 v[56:59], v[176:179], v[200:203], v[56:59]
	v_mfma_f32_16x16x32_bf16 v[60:63], v[136:139], v[208:211], v[60:63]
	v_mfma_f32_16x16x32_bf16 v[64:67], v[176:179], v[208:211], v[64:67]
	s_setprio 0
	s_barrier
	s_mov_b32 m0, s19
	v_lshl_add_u64 v[148:149], s[96:97], 0, v[132:133]
	s_mov_b64 s[94:95], 0x8000
	ds_read_b128 v[180:183], v152 offset:16384
	ds_read_b128 v[184:187], v152 offset:17408
	ds_read_b128 v[188:191], v152 offset:18432
	ds_read_b128 v[192:195], v152 offset:19456
	ds_read_b128 v[196:199], v152 offset:20480
	ds_read_b128 v[200:203], v152 offset:21504
	ds_read_b128 v[204:207], v152 offset:22528
	ds_read_b128 v[208:211], v152 offset:23552
	global_load_lds_dwordx4 v[148:149], off
	v_lshl_add_u64 v[2:3], v[148:149], 0, s[94:95]
	s_mov_b32 m0, s12
	v_lshl_add_u64 v[252:253], s[92:93], 0, v[134:135]
	global_load_lds_dwordx4 v[2:3], off
	v_lshl_add_u64 v[2:3], v[148:149], 0, s[14:15]
	s_mov_b32 m0, s13
	s_nop 0
	global_load_lds_dwordx4 v[2:3], off
	v_lshl_add_u64 v[2:3], v[148:149], 0, s[16:17]
	s_mov_b32 m0, s9
	s_nop 0
	global_load_lds_dwordx4 v[2:3], off
	s_mov_b32 m0, s11
	v_lshl_add_u64 v[2:3], v[252:253], 0, s[94:95]
	global_load_lds_dwordx4 v[252:253], off
	s_mov_b32 m0, s28
	s_nop 0
	global_load_lds_dwordx4 v[2:3], off
	s_waitcnt vmcnt(8)
	s_waitcnt lgkmcnt(0)
	s_barrier
	s_setprio 1
	s_waitcnt lgkmcnt(0)
	v_mfma_f32_16x16x32_bf16 v[2:5], v[112:115], v[204:207], v[4:7]
	v_mfma_f32_16x16x32_bf16 v[140:143], v[112:115], v[180:183], v[140:143]
	v_mfma_f32_16x16x32_bf16 v[144:147], v[120:123], v[180:183], v[144:147]
	v_mfma_f32_16x16x32_bf16 v[156:159], v[112:115], v[188:191], v[156:159]
	v_mfma_f32_16x16x32_bf16 v[160:163], v[120:123], v[188:191], v[160:163]
	v_mfma_f32_16x16x32_bf16 v[164:167], v[112:115], v[196:199], v[164:167]
	v_mfma_f32_16x16x32_bf16 v[168:171], v[120:123], v[196:199], v[168:171]
	v_mfma_f32_16x16x32_bf16 v[212:215], v[116:119], v[208:211], v[2:5]
	v_mfma_f32_16x16x32_bf16 v[2:5], v[120:123], v[204:207], v[8:11]
	v_mfma_f32_16x16x32_bf16 v[140:143], v[116:119], v[184:187], v[140:143]
	v_mfma_f32_16x16x32_bf16 v[144:147], v[124:127], v[184:187], v[144:147]
	v_mfma_f32_16x16x32_bf16 v[156:159], v[116:119], v[192:195], v[156:159]
	v_mfma_f32_16x16x32_bf16 v[160:163], v[124:127], v[192:195], v[160:163]
	v_mfma_f32_16x16x32_bf16 v[164:167], v[116:119], v[200:203], v[164:167]
	v_mfma_f32_16x16x32_bf16 v[168:171], v[124:127], v[200:203], v[168:171]
	v_mfma_f32_16x16x32_bf16 v[216:219], v[124:127], v[208:211], v[2:5]
	v_mfma_f32_16x16x32_bf16 v[2:5], v[128:131], v[180:183], v[12:15]
	v_mfma_f32_16x16x32_bf16 v[220:223], v[136:139], v[184:187], v[2:5]
	v_mfma_f32_16x16x32_bf16 v[2:5], v[172:175], v[180:183], v[16:19]
	v_mfma_f32_16x16x32_bf16 v[180:183], v[176:179], v[184:187], v[2:5]
	v_mfma_f32_16x16x32_bf16 v[2:5], v[128:131], v[188:191], v[28:31]
	v_mfma_f32_16x16x32_bf16 v[184:187], v[136:139], v[192:195], v[2:5]
	v_mfma_f32_16x16x32_bf16 v[2:5], v[172:175], v[188:191], v[36:39]
	v_mfma_f32_16x16x32_bf16 v[188:191], v[176:179], v[192:195], v[2:5]
	v_mfma_f32_16x16x32_bf16 v[2:5], v[128:131], v[196:199], v[68:71]
	v_mfma_f32_16x16x32_bf16 v[68:71], v[136:139], v[200:203], v[2:5]
	v_mfma_f32_16x16x32_bf16 v[2:5], v[172:175], v[196:199], v[108:111]
	v_mfma_f32_16x16x32_bf16 v[192:195], v[176:179], v[200:203], v[2:5]
	v_mfma_f32_16x16x32_bf16 v[2:5], v[128:131], v[204:207], v[20:23]
	v_mfma_f32_16x16x32_bf16 v[136:139], v[136:139], v[208:211], v[2:5]
	v_mfma_f32_16x16x32_bf16 v[2:5], v[172:175], v[204:207], v[24:27]
	v_mfma_f32_16x16x32_bf16 v[172:175], v[176:179], v[208:211], v[2:5]
	s_setprio 0
	s_barrier
	ds_read_b128 v[176:179], v34
	ds_read_b128 v[196:199], v34 offset:1024
	ds_read_b128 v[200:203], v34 offset:2048
	ds_read_b128 v[204:207], v34 offset:3072
	ds_read_b128 v[208:211], v155
	ds_read_b128 v[224:227], v155 offset:1024
	ds_read_b128 v[228:231], v155 offset:2048
	ds_read_b128 v[232:235], v155 offset:3072
	s_mov_b32 m0, s29
	v_lshl_add_u64 v[2:3], v[252:253], 0, s[14:15]
	ds_read_b128 v[36:39], v152 offset:32768
	ds_read_b128 v[108:111], v152 offset:33792
	ds_read_b128 v[112:115], v152 offset:34816
	ds_read_b128 v[120:123], v152 offset:35840
	ds_read_b128 v[236:239], v152 offset:36864
	ds_read_b128 v[240:243], v152 offset:37888
	ds_read_b128 v[244:247], v152 offset:38912
	ds_read_b128 v[248:251], v152 offset:39936
	global_load_lds_dwordx4 v[2:3], off
	v_lshl_add_u64 v[2:3], v[252:253], 0, s[16:17]
	s_mov_b32 m0, s33
	s_nop 0
	global_load_lds_dwordx4 v[2:3], off
	s_waitcnt vmcnt(8)
	s_waitcnt lgkmcnt(0)
	s_barrier
	s_setprio 1
	s_waitcnt lgkmcnt(0)
	v_mfma_f32_16x16x32_bf16 v[2:5], v[176:179], v[36:39], v[72:75]
	v_mfma_f32_16x16x32_bf16 v[6:9], v[200:203], v[36:39], v[76:79]
	v_mfma_f32_16x16x32_bf16 v[10:13], v[176:179], v[112:115], v[80:83]
	v_mfma_f32_16x16x32_bf16 v[14:17], v[200:203], v[112:115], v[84:87]
	v_mfma_f32_16x16x32_bf16 v[18:21], v[176:179], v[236:239], v[88:91]
	v_mfma_f32_16x16x32_bf16 v[22:25], v[200:203], v[236:239], v[92:95]
	v_mfma_f32_16x16x32_bf16 v[26:29], v[176:179], v[244:247], v[96:99]
	v_mfma_f32_16x16x32_bf16 v[30:33], v[200:203], v[244:247], v[100:103]
	v_mfma_f32_16x16x32_bf16 v[2:5], v[196:199], v[108:111], v[2:5]
	v_mfma_f32_16x16x32_bf16 v[6:9], v[204:207], v[108:111], v[6:9]
	v_mfma_f32_16x16x32_bf16 v[10:13], v[196:199], v[120:123], v[10:13]
	v_mfma_f32_16x16x32_bf16 v[14:17], v[204:207], v[120:123], v[14:17]
	v_mfma_f32_16x16x32_bf16 v[18:21], v[196:199], v[240:243], v[18:21]
	v_mfma_f32_16x16x32_bf16 v[22:25], v[204:207], v[240:243], v[22:25]
	v_mfma_f32_16x16x32_bf16 v[26:29], v[196:199], v[248:251], v[26:29]
	v_mfma_f32_16x16x32_bf16 v[30:33], v[204:207], v[248:251], v[30:33]
	v_mfma_f32_16x16x32_bf16 v[72:75], v[208:211], v[36:39], v[104:107]
	v_mfma_f32_16x16x32_bf16 v[36:39], v[228:231], v[36:39], v[40:43]
	v_mfma_f32_16x16x32_bf16 v[128:131], v[232:235], v[108:111], v[36:39]
	v_mfma_f32_16x16x32_bf16 v[36:39], v[208:211], v[112:115], v[44:47]
	v_mfma_f32_16x16x32_bf16 v[116:119], v[224:227], v[120:123], v[36:39]
	v_mfma_f32_16x16x32_bf16 v[36:39], v[228:231], v[112:115], v[48:51]
	v_mfma_f32_16x16x32_bf16 v[120:123], v[232:235], v[120:123], v[36:39]
	v_mfma_f32_16x16x32_bf16 v[36:39], v[208:211], v[236:239], v[52:55]
	v_mfma_f32_16x16x32_bf16 v[124:127], v[224:227], v[108:111], v[72:75]
	v_mfma_f32_16x16x32_bf16 v[108:111], v[224:227], v[240:243], v[36:39]
	v_mfma_f32_16x16x32_bf16 v[36:39], v[228:231], v[236:239], v[56:59]
	v_mfma_f32_16x16x32_bf16 v[112:115], v[232:235], v[240:243], v[36:39]
	v_mfma_f32_16x16x32_bf16 v[36:39], v[208:211], v[244:247], v[60:63]
	v_mfma_f32_16x16x32_bf16 v[100:103], v[224:227], v[248:251], v[36:39]
	v_mfma_f32_16x16x32_bf16 v[36:39], v[228:231], v[244:247], v[64:67]
	v_mfma_f32_16x16x32_bf16 v[104:107], v[232:235], v[248:251], v[36:39]
	s_setprio 0
	s_barrier
	s_mov_b32 m0, s91
	s_nop 3
	v_lshl_add_u64 v[36:37], v[148:149], 0, s[34:35]
	ds_read_b128 v[72:75], v152 offset:49152
	ds_read_b128 v[76:79], v152 offset:50176
	ds_read_b128 v[80:83], v152 offset:51200
	ds_read_b128 v[88:91], v152 offset:52224
	ds_read_b128 v[236:239], v152 offset:53248
	ds_read_b128 v[240:243], v152 offset:54272
	ds_read_b128 v[244:247], v152 offset:55296
	ds_read_b128 v[248:251], v152 offset:56320
	global_load_lds_dwordx4 v[36:37], off
	v_lshl_add_u64 v[36:37], v[148:149], 0, s[36:37]
	s_mov_b32 m0, s67
	s_nop 0
	global_load_lds_dwordx4 v[36:37], off
	v_lshl_add_u64 v[36:37], v[148:149], 0, s[38:39]
	s_mov_b32 m0, s85
	s_nop 0
	global_load_lds_dwordx4 v[36:37], off
	v_lshl_add_u64 v[36:37], v[148:149], 0, s[44:45]
	s_mov_b32 m0, s90
	s_nop 0
	global_load_lds_dwordx4 v[36:37], off
	v_lshl_add_u64 v[36:37], v[252:253], 0, s[34:35]
	s_mov_b32 m0, s41
	s_nop 0
	global_load_lds_dwordx4 v[36:37], off
	v_lshl_add_u64 v[36:37], v[252:253], 0, s[36:37]
	s_mov_b32 m0, s42
	s_nop 0
	global_load_lds_dwordx4 v[36:37], off
	s_waitcnt vmcnt(8)
	s_waitcnt lgkmcnt(0)
	s_barrier
	s_setprio 1
	s_waitcnt lgkmcnt(0)
	v_mfma_f32_16x16x32_bf16 v[40:43], v[200:203], v[72:75], v[144:147]
	v_mfma_f32_16x16x32_bf16 v[44:47], v[204:207], v[76:79], v[40:43]
	v_mfma_f32_16x16x32_bf16 v[40:43], v[176:179], v[80:83], v[156:159]
	v_mfma_f32_16x16x32_bf16 v[52:55], v[196:199], v[88:91], v[40:43]
	v_mfma_f32_16x16x32_bf16 v[40:43], v[200:203], v[80:83], v[160:163]
	v_mfma_f32_16x16x32_bf16 v[36:39], v[176:179], v[72:75], v[140:143]
	v_mfma_f32_16x16x32_bf16 v[60:63], v[204:207], v[88:91], v[40:43]
	v_mfma_f32_16x16x32_bf16 v[40:43], v[176:179], v[236:239], v[164:167]
	v_mfma_f32_16x16x32_bf16 v[48:51], v[200:203], v[236:239], v[168:171]
	v_mfma_f32_16x16x32_bf16 v[56:59], v[176:179], v[244:247], v[212:215]
	v_mfma_f32_16x16x32_bf16 v[64:67], v[200:203], v[244:247], v[216:219]
	v_mfma_f32_16x16x32_bf16 v[36:39], v[196:199], v[76:79], v[36:39]
	v_mfma_f32_16x16x32_bf16 v[40:43], v[196:199], v[240:243], v[40:43]
	v_mfma_f32_16x16x32_bf16 v[48:51], v[204:207], v[240:243], v[48:51]
	v_mfma_f32_16x16x32_bf16 v[56:59], v[196:199], v[248:251], v[56:59]
	v_mfma_f32_16x16x32_bf16 v[64:67], v[204:207], v[248:251], v[64:67]
	v_mfma_f32_16x16x32_bf16 v[84:87], v[208:211], v[72:75], v[220:223]
	v_mfma_f32_16x16x32_bf16 v[72:75], v[228:231], v[72:75], v[180:183]
	v_mfma_f32_16x16x32_bf16 v[96:99], v[232:235], v[76:79], v[72:75]
	v_mfma_f32_16x16x32_bf16 v[72:75], v[208:211], v[80:83], v[184:187]
	v_mfma_f32_16x16x32_bf16 v[68:71], v[208:211], v[236:239], v[68:71]
	v_mfma_f32_16x16x32_bf16 v[92:95], v[224:227], v[76:79], v[84:87]
	v_mfma_f32_16x16x32_bf16 v[84:87], v[224:227], v[88:91], v[72:75]
	v_mfma_f32_16x16x32_bf16 v[72:75], v[228:231], v[80:83], v[188:191]
	v_mfma_f32_16x16x32_bf16 v[76:79], v[224:227], v[240:243], v[68:71]
	v_mfma_f32_16x16x32_bf16 v[68:71], v[228:231], v[236:239], v[192:195]
	v_mfma_f32_16x16x32_bf16 v[88:91], v[232:235], v[88:91], v[72:75]
	v_mfma_f32_16x16x32_bf16 v[80:83], v[232:235], v[240:243], v[68:71]
	v_mfma_f32_16x16x32_bf16 v[68:71], v[208:211], v[244:247], v[136:139]
	v_mfma_f32_16x16x32_bf16 v[72:75], v[228:231], v[244:247], v[172:175]
	v_mfma_f32_16x16x32_bf16 v[68:71], v[224:227], v[248:251], v[68:71]
	v_mfma_f32_16x16x32_bf16 v[72:75], v[232:235], v[248:251], v[72:75]
	s_setprio 0
	s_barrier
	s_andn2_b64 vcc, exec, s[46:47]
	s_cbranch_vccnz .LBB0_631
	s_barrier

.LBB0_857:
	v_add_u32_e32 v3, s51, v1
	ds_read_b128 v[134:137], v3
	ds_read_b128 v[138:141], v3 offset:1024
	ds_read_b128 v[142:145], v3 offset:2048
	ds_read_b128 v[146:149], v3 offset:3072
	v_add_u32_e32 v3, s64, v1
	s_add_u32 s8, s60, s62
	ds_read_b128 v[166:169], v3
	ds_read_b128 v[170:173], v3 offset:1024
	ds_read_b128 v[174:177], v3 offset:2048
	ds_read_b128 v[178:181], v3 offset:3072
	s_addc_u32 s9, s61, s63
	s_add_u32 s8, s8, 0x100
	s_addc_u32 s9, s9, 0
	s_add_u32 s86, s67, s62
	s_addc_u32 s87, s84, s63
	s_cmpk_eq_i32 s62, 0xf00
	s_cselect_b32 s9, s4, s9
	s_cselect_b32 s8, s5, s8
	s_cselect_b32 s87, s55, s87
	s_cselect_b32 s86, s66, s86
	v_lshl_add_u64 v[4:5], v[160:161], 0, s[62:63]
	v_lshl_add_u64 v[214:215], v[4:5], 0, s[36:37]
	s_add_i32 m0, s24, 0xc000
	ds_read_b128 v[182:185], v163
	ds_read_b128 v[186:189], v163 offset:1024
	ds_read_b128 v[190:193], v163 offset:2048
	ds_read_b128 v[194:197], v163 offset:3072
	ds_read_b128 v[198:201], v163 offset:4096
	ds_read_b128 v[202:205], v163 offset:5120
	ds_read_b128 v[206:209], v163 offset:6144
	ds_read_b128 v[210:213], v163 offset:7168
	global_load_lds_dwordx4 v[214:215], off
	v_lshl_add_u64 v[4:5], v[4:5], 0, s[38:39]
	s_add_i32 m0, s24, 0xe000
	s_nop 0
	global_load_lds_dwordx4 v[4:5], off
	s_waitcnt vmcnt(8)
	s_waitcnt lgkmcnt(0)
	s_barrier
	s_setprio 1
	s_waitcnt lgkmcnt(0)
	v_mfma_f32_16x16x32_bf16 v[130:133], v[134:137], v[182:185], v[130:133]
	v_mfma_f32_16x16x32_bf16 v[126:129], v[142:145], v[182:185], v[126:129]
	v_mfma_f32_16x16x32_bf16 v[114:117], v[134:137], v[190:193], v[114:117]
	v_mfma_f32_16x16x32_bf16 v[110:113], v[142:145], v[190:193], v[110:113]
	v_mfma_f32_16x16x32_bf16 v[98:101], v[134:137], v[198:201], v[98:101]
	v_mfma_f32_16x16x32_bf16 v[94:97], v[142:145], v[198:201], v[94:97]
	v_mfma_f32_16x16x32_bf16 v[82:85], v[134:137], v[206:209], v[82:85]
	v_mfma_f32_16x16x32_bf16 v[78:81], v[142:145], v[206:209], v[78:81]
	v_mfma_f32_16x16x32_bf16 v[130:133], v[138:141], v[186:189], v[130:133]
	v_mfma_f32_16x16x32_bf16 v[126:129], v[146:149], v[186:189], v[126:129]
	v_mfma_f32_16x16x32_bf16 v[114:117], v[138:141], v[194:197], v[114:117]
	v_mfma_f32_16x16x32_bf16 v[110:113], v[146:149], v[194:197], v[110:113]
	v_mfma_f32_16x16x32_bf16 v[98:101], v[138:141], v[202:205], v[98:101]
	v_mfma_f32_16x16x32_bf16 v[94:97], v[146:149], v[202:205], v[94:97]
	v_mfma_f32_16x16x32_bf16 v[82:85], v[138:141], v[210:213], v[82:85]
	v_mfma_f32_16x16x32_bf16 v[78:81], v[146:149], v[210:213], v[78:81]
	v_mfma_f32_16x16x32_bf16 v[122:125], v[166:169], v[182:185], v[122:125]
	v_mfma_f32_16x16x32_bf16 v[118:121], v[174:177], v[182:185], v[118:121]
	v_mfma_f32_16x16x32_bf16 v[106:109], v[166:169], v[190:193], v[106:109]
	v_mfma_f32_16x16x32_bf16 v[102:105], v[174:177], v[190:193], v[102:105]
	v_mfma_f32_16x16x32_bf16 v[90:93], v[166:169], v[198:201], v[90:93]
	v_mfma_f32_16x16x32_bf16 v[86:89], v[174:177], v[198:201], v[86:89]
	v_mfma_f32_16x16x32_bf16 v[74:77], v[166:169], v[206:209], v[74:77]
	v_mfma_f32_16x16x32_bf16 v[70:73], v[174:177], v[206:209], v[70:73]
	v_mfma_f32_16x16x32_bf16 v[122:125], v[170:173], v[186:189], v[122:125]
	v_mfma_f32_16x16x32_bf16 v[118:121], v[178:181], v[186:189], v[118:121]
	v_mfma_f32_16x16x32_bf16 v[106:109], v[170:173], v[194:197], v[106:109]
	v_mfma_f32_16x16x32_bf16 v[102:105], v[178:181], v[194:197], v[102:105]
	v_mfma_f32_16x16x32_bf16 v[90:93], v[170:173], v[202:205], v[90:93]
	v_mfma_f32_16x16x32_bf16 v[86:89], v[178:181], v[202:205], v[86:89]
	v_mfma_f32_16x16x32_bf16 v[74:77], v[170:173], v[210:213], v[74:77]
	v_mfma_f32_16x16x32_bf16 v[70:73], v[178:181], v[210:213], v[70:73]
	s_setprio 0
	s_barrier
	v_lshl_add_u64 v[214:215], s[86:87], 0, v[152:153]
	s_add_i32 s86, s51, s13
	s_mov_b32 m0, s86
	ds_read_b128 v[182:185], v163 offset:16384
	ds_read_b128 v[186:189], v163 offset:17408
	ds_read_b128 v[190:193], v163 offset:18432
	ds_read_b128 v[194:197], v163 offset:19456
	ds_read_b128 v[198:201], v163 offset:20480
	ds_read_b128 v[202:205], v163 offset:21504
	ds_read_b128 v[206:209], v163 offset:22528
	ds_read_b128 v[210:213], v163 offset:23552
	global_load_lds_dwordx4 v[214:215], off
	v_lshl_add_u64 v[4:5], v[214:215], 0, s[14:15]
	s_add_i32 m0, s86, 0x2000
	s_add_i32 s86, s64, s13
	global_load_lds_dwordx4 v[4:5], off
	v_lshl_add_u64 v[4:5], v[214:215], 0, s[16:17]
	s_mov_b32 m0, s86
	v_lshl_add_u64 v[216:217], s[8:9], 0, v[150:151]
	global_load_lds_dwordx4 v[4:5], off
	v_lshl_add_u64 v[4:5], v[214:215], 0, s[18:19]
	s_add_i32 m0, s86, 0x2000
	s_nop 0
	global_load_lds_dwordx4 v[4:5], off
	s_mov_b32 m0, s24
	v_lshl_add_u64 v[4:5], v[216:217], 0, s[14:15]
	global_load_lds_dwordx4 v[216:217], off
	s_mov_b32 m0, s25
	s_nop 0
	global_load_lds_dwordx4 v[4:5], off
	s_waitcnt vmcnt(8)
	s_waitcnt lgkmcnt(0)
	s_barrier
	s_setprio 1
	s_waitcnt lgkmcnt(0)
	v_mfma_f32_16x16x32_bf16 v[66:69], v[134:137], v[182:185], v[66:69]
	v_mfma_f32_16x16x32_bf16 v[62:65], v[142:145], v[182:185], v[62:65]
	v_mfma_f32_16x16x32_bf16 v[50:53], v[134:137], v[190:193], v[50:53]
	v_mfma_f32_16x16x32_bf16 v[46:49], v[142:145], v[190:193], v[46:49]
	v_mfma_f32_16x16x32_bf16 v[34:37], v[134:137], v[198:201], v[34:37]
	v_mfma_f32_16x16x32_bf16 v[30:33], v[142:145], v[198:201], v[30:33]
	v_mfma_f32_16x16x32_bf16 v[18:21], v[134:137], v[206:209], v[18:21]
	v_mfma_f32_16x16x32_bf16 v[14:17], v[142:145], v[206:209], v[14:17]
	v_mfma_f32_16x16x32_bf16 v[66:69], v[138:141], v[186:189], v[66:69]
	v_mfma_f32_16x16x32_bf16 v[62:65], v[146:149], v[186:189], v[62:65]
	v_mfma_f32_16x16x32_bf16 v[50:53], v[138:141], v[194:197], v[50:53]
	v_mfma_f32_16x16x32_bf16 v[46:49], v[146:149], v[194:197], v[46:49]
	v_mfma_f32_16x16x32_bf16 v[34:37], v[138:141], v[202:205], v[34:37]
	v_mfma_f32_16x16x32_bf16 v[30:33], v[146:149], v[202:205], v[30:33]
	v_mfma_f32_16x16x32_bf16 v[18:21], v[138:141], v[210:213], v[18:21]
	v_mfma_f32_16x16x32_bf16 v[14:17], v[146:149], v[210:213], v[14:17]
	v_mfma_f32_16x16x32_bf16 v[58:61], v[166:169], v[182:185], v[58:61]
	v_mfma_f32_16x16x32_bf16 v[54:57], v[174:177], v[182:185], v[54:57]
	v_mfma_f32_16x16x32_bf16 v[42:45], v[166:169], v[190:193], v[42:45]
	v_mfma_f32_16x16x32_bf16 v[38:41], v[174:177], v[190:193], v[38:41]
	v_mfma_f32_16x16x32_bf16 v[26:29], v[166:169], v[198:201], v[26:29]
	v_mfma_f32_16x16x32_bf16 v[22:25], v[174:177], v[198:201], v[22:25]
	v_mfma_f32_16x16x32_bf16 v[10:13], v[166:169], v[206:209], v[10:13]
	v_mfma_f32_16x16x32_bf16 v[4:7], v[174:177], v[206:209], v[6:9]
	v_mfma_f32_16x16x32_bf16 v[58:61], v[170:173], v[186:189], v[58:61]
	v_mfma_f32_16x16x32_bf16 v[54:57], v[178:181], v[186:189], v[54:57]
	v_mfma_f32_16x16x32_bf16 v[42:45], v[170:173], v[194:197], v[42:45]
	v_mfma_f32_16x16x32_bf16 v[38:41], v[178:181], v[194:197], v[38:41]
	v_mfma_f32_16x16x32_bf16 v[26:29], v[170:173], v[202:205], v[26:29]
	v_mfma_f32_16x16x32_bf16 v[22:25], v[178:181], v[202:205], v[22:25]
	v_mfma_f32_16x16x32_bf16 v[10:13], v[170:173], v[210:213], v[10:13]
	v_mfma_f32_16x16x32_bf16 v[4:7], v[178:181], v[210:213], v[4:7]
	s_setprio 0
	s_barrier
	s_add_i32 s8, 0, 0x18000
	v_add_u32_e32 v3, s8, v1
	s_add_i32 s9, 0, 0x1c000
	ds_read_b128 v[134:137], v3
	ds_read_b128 v[138:141], v3 offset:1024
	ds_read_b128 v[142:145], v3 offset:2048
	ds_read_b128 v[146:149], v3 offset:3072
	v_add_u32_e32 v3, s9, v1
	ds_read_b128 v[166:169], v3
	ds_read_b128 v[170:173], v3 offset:1024
	ds_read_b128 v[174:177], v3 offset:2048
	ds_read_b128 v[178:181], v3 offset:3072
	s_mov_b32 m0, s28
	v_lshl_add_u64 v[8:9], v[216:217], 0, s[16:17]
	ds_read_b128 v[182:185], v163 offset:32768
	ds_read_b128 v[186:189], v163 offset:33792
	ds_read_b128 v[190:193], v163 offset:34816
	ds_read_b128 v[194:197], v163 offset:35840
	ds_read_b128 v[198:201], v163 offset:36864
	ds_read_b128 v[202:205], v163 offset:37888
	ds_read_b128 v[206:209], v163 offset:38912
	ds_read_b128 v[210:213], v163 offset:39936
	global_load_lds_dwordx4 v[8:9], off
	v_lshl_add_u64 v[8:9], v[216:217], 0, s[18:19]
	s_mov_b32 m0, s29
	s_nop 0
	global_load_lds_dwordx4 v[8:9], off
	s_waitcnt vmcnt(8)
	s_waitcnt lgkmcnt(0)
	s_barrier
	s_setprio 1
	s_waitcnt lgkmcnt(0)
	v_mfma_f32_16x16x32_bf16 v[130:133], v[134:137], v[182:185], v[130:133]
	v_mfma_f32_16x16x32_bf16 v[126:129], v[142:145], v[182:185], v[126:129]
	v_mfma_f32_16x16x32_bf16 v[114:117], v[134:137], v[190:193], v[114:117]
	v_mfma_f32_16x16x32_bf16 v[110:113], v[142:145], v[190:193], v[110:113]
	v_mfma_f32_16x16x32_bf16 v[98:101], v[134:137], v[198:201], v[98:101]
	v_mfma_f32_16x16x32_bf16 v[94:97], v[142:145], v[198:201], v[94:97]
	v_mfma_f32_16x16x32_bf16 v[82:85], v[134:137], v[206:209], v[82:85]
	v_mfma_f32_16x16x32_bf16 v[78:81], v[142:145], v[206:209], v[78:81]
	v_mfma_f32_16x16x32_bf16 v[130:133], v[138:141], v[186:189], v[130:133]
	v_mfma_f32_16x16x32_bf16 v[126:129], v[146:149], v[186:189], v[126:129]
	v_mfma_f32_16x16x32_bf16 v[114:117], v[138:141], v[194:197], v[114:117]
	v_mfma_f32_16x16x32_bf16 v[110:113], v[146:149], v[194:197], v[110:113]
	v_mfma_f32_16x16x32_bf16 v[98:101], v[138:141], v[202:205], v[98:101]
	v_mfma_f32_16x16x32_bf16 v[94:97], v[146:149], v[202:205], v[94:97]
	v_mfma_f32_16x16x32_bf16 v[82:85], v[138:141], v[210:213], v[82:85]
	v_mfma_f32_16x16x32_bf16 v[78:81], v[146:149], v[210:213], v[78:81]
	v_mfma_f32_16x16x32_bf16 v[122:125], v[166:169], v[182:185], v[122:125]
	v_mfma_f32_16x16x32_bf16 v[118:121], v[174:177], v[182:185], v[118:121]
	v_mfma_f32_16x16x32_bf16 v[106:109], v[166:169], v[190:193], v[106:109]
	v_mfma_f32_16x16x32_bf16 v[102:105], v[174:177], v[190:193], v[102:105]
	v_mfma_f32_16x16x32_bf16 v[90:93], v[166:169], v[198:201], v[90:93]
	v_mfma_f32_16x16x32_bf16 v[86:89], v[174:177], v[198:201], v[86:89]
	v_mfma_f32_16x16x32_bf16 v[74:77], v[166:169], v[206:209], v[74:77]
	v_mfma_f32_16x16x32_bf16 v[70:73], v[174:177], v[206:209], v[70:73]
	v_mfma_f32_16x16x32_bf16 v[122:125], v[170:173], v[186:189], v[122:125]
	v_mfma_f32_16x16x32_bf16 v[118:121], v[178:181], v[186:189], v[118:121]
	v_mfma_f32_16x16x32_bf16 v[106:109], v[170:173], v[194:197], v[106:109]
	v_mfma_f32_16x16x32_bf16 v[102:105], v[178:181], v[194:197], v[102:105]
	v_mfma_f32_16x16x32_bf16 v[90:93], v[170:173], v[202:205], v[90:93]
	v_mfma_f32_16x16x32_bf16 v[86:89], v[178:181], v[202:205], v[86:89]
	v_mfma_f32_16x16x32_bf16 v[74:77], v[170:173], v[210:213], v[74:77]
	v_mfma_f32_16x16x32_bf16 v[70:73], v[178:181], v[210:213], v[70:73]
	s_setprio 0
	s_barrier
	s_add_i32 s8, s8, s13
	v_lshl_add_u64 v[8:9], v[214:215], 0, s[30:31]
	s_mov_b32 m0, s8
	ds_read_b128 v[182:185], v163 offset:49152
	ds_read_b128 v[186:189], v163 offset:50176
	ds_read_b128 v[190:193], v163 offset:51200
	ds_read_b128 v[194:197], v163 offset:52224
	ds_read_b128 v[198:201], v163 offset:53248
	ds_read_b128 v[202:205], v163 offset:54272
	ds_read_b128 v[206:209], v163 offset:55296
	ds_read_b128 v[210:213], v163 offset:56320
	global_load_lds_dwordx4 v[8:9], off
	v_lshl_add_u64 v[8:9], v[214:215], 0, s[34:35]
	s_add_i32 m0, s8, 0x2000
	s_add_i32 s8, s9, s13
	global_load_lds_dwordx4 v[8:9], off
	v_lshl_add_u64 v[8:9], v[214:215], 0, s[36:37]
	s_mov_b32 m0, s8
	s_nop 0
	global_load_lds_dwordx4 v[8:9], off
	v_lshl_add_u64 v[8:9], v[214:215], 0, s[38:39]
	s_add_i32 m0, s8, 0x2000
	s_nop 0
	global_load_lds_dwordx4 v[8:9], off
	v_lshl_add_u64 v[8:9], v[216:217], 0, s[30:31]
	s_mov_b32 m0, s41
	s_nop 0
	global_load_lds_dwordx4 v[8:9], off
	v_lshl_add_u64 v[8:9], v[216:217], 0, s[34:35]
	s_mov_b32 m0, s42
	s_nop 0
	global_load_lds_dwordx4 v[8:9], off
	s_waitcnt vmcnt(8)
	s_waitcnt lgkmcnt(0)
	s_barrier
	s_setprio 1
	s_waitcnt lgkmcnt(0)
	v_mfma_f32_16x16x32_bf16 v[66:69], v[134:137], v[182:185], v[66:69]
	v_mfma_f32_16x16x32_bf16 v[62:65], v[142:145], v[182:185], v[62:65]
	v_mfma_f32_16x16x32_bf16 v[50:53], v[134:137], v[190:193], v[50:53]
	v_mfma_f32_16x16x32_bf16 v[46:49], v[142:145], v[190:193], v[46:49]
	v_mfma_f32_16x16x32_bf16 v[34:37], v[134:137], v[198:201], v[34:37]
	v_mfma_f32_16x16x32_bf16 v[30:33], v[142:145], v[198:201], v[30:33]
	v_mfma_f32_16x16x32_bf16 v[18:21], v[134:137], v[206:209], v[18:21]
	v_mfma_f32_16x16x32_bf16 v[14:17], v[142:145], v[206:209], v[14:17]
	v_mfma_f32_16x16x32_bf16 v[66:69], v[138:141], v[186:189], v[66:69]
	v_mfma_f32_16x16x32_bf16 v[62:65], v[146:149], v[186:189], v[62:65]
	v_mfma_f32_16x16x32_bf16 v[50:53], v[138:141], v[194:197], v[50:53]
	v_mfma_f32_16x16x32_bf16 v[46:49], v[146:149], v[194:197], v[46:49]
	v_mfma_f32_16x16x32_bf16 v[34:37], v[138:141], v[202:205], v[34:37]
	v_mfma_f32_16x16x32_bf16 v[30:33], v[146:149], v[202:205], v[30:33]
	v_mfma_f32_16x16x32_bf16 v[18:21], v[138:141], v[210:213], v[18:21]
	v_mfma_f32_16x16x32_bf16 v[14:17], v[146:149], v[210:213], v[14:17]
	v_mfma_f32_16x16x32_bf16 v[58:61], v[166:169], v[182:185], v[58:61]
	v_mfma_f32_16x16x32_bf16 v[54:57], v[174:177], v[182:185], v[54:57]
	v_mfma_f32_16x16x32_bf16 v[42:45], v[166:169], v[190:193], v[42:45]
	v_mfma_f32_16x16x32_bf16 v[38:41], v[174:177], v[190:193], v[38:41]
	v_mfma_f32_16x16x32_bf16 v[26:29], v[166:169], v[198:201], v[26:29]
	v_mfma_f32_16x16x32_bf16 v[22:25], v[174:177], v[198:201], v[22:25]
	v_mfma_f32_16x16x32_bf16 v[8:11], v[166:169], v[206:209], v[10:13]
	v_mfma_f32_16x16x32_bf16 v[4:7], v[174:177], v[206:209], v[4:7]
	v_mfma_f32_16x16x32_bf16 v[58:61], v[170:173], v[186:189], v[58:61]
	v_mfma_f32_16x16x32_bf16 v[54:57], v[178:181], v[186:189], v[54:57]
	v_mfma_f32_16x16x32_bf16 v[42:45], v[170:173], v[194:197], v[42:45]
	v_mfma_f32_16x16x32_bf16 v[38:41], v[178:181], v[194:197], v[38:41]
	v_mfma_f32_16x16x32_bf16 v[26:29], v[170:173], v[202:205], v[26:29]
	v_mfma_f32_16x16x32_bf16 v[22:25], v[178:181], v[202:205], v[22:25]
	v_mfma_f32_16x16x32_bf16 v[10:13], v[170:173], v[210:213], v[8:11]
	v_mfma_f32_16x16x32_bf16 v[6:9], v[178:181], v[210:213], v[4:7]
	s_setprio 0
	s_barrier
	s_add_i32 s85, s85, 2
	s_add_u32 s62, s62, 0x100
	s_addc_u32 s63, s63, 0
	s_cmp_gt_u32 s85, 29
	s_cbranch_scc1 .LBB0_860

.LBB0_994:
	v_mul_f32_e32 v145, 0xbfb8aa3b, v128
	v_exp_f32_e32 v145, v145
	v_mul_f32_e32 v146, 0xbfb8aa3b, v129
	v_exp_f32_e32 v146, v146
	v_mov_b32_e32 v34, v0
	v_add_f32_e32 v145, 1.0, v145
	v_rcp_f32_e32 v145, v145
	v_add_f32_e32 v146, 1.0, v146
	v_rcp_f32_e32 v146, v146
	s_nop 15
	s_nop 15
	s_nop 0
	v_and_or_b32 v147, v34, 63, s51
	v_mul_f32_e32 v34, v128, v145
	v_mul_f32_e32 v128, 0xbfb8aa3b, v130
	v_mul_f32_e32 v2, v34, v2
	v_mul_f32_e32 v34, v129, v146
	v_exp_f32_e32 v128, v128
	v_mul_f32_e32 v129, 0xbfb8aa3b, v131
	v_exp_f32_e32 v129, v129
	v_mul_f32_e32 v3, v34, v3
	v_add_f32_e32 v34, 1.0, v128
	v_rcp_f32_e32 v34, v34
	v_add_f32_e32 v128, 1.0, v129
	v_mul_f32_e32 v129, 0xbfb8aa3b, v124
	v_rcp_f32_e32 v128, v128
	v_exp_f32_e32 v129, v129
	v_mul_f32_e32 v34, v130, v34
	v_mul_f32_e32 v4, v34, v4
	v_mul_f32_e32 v34, v131, v128
	v_add_f32_e32 v128, 1.0, v129
	v_rcp_f32_e32 v128, v128
	v_mul_f32_e32 v129, 0xbfb8aa3b, v125
	v_exp_f32_e32 v129, v129
	v_mul_f32_e32 v5, v34, v5
	v_mul_f32_e32 v34, v124, v128
	v_mul_f32_e32 v124, 0xbfb8aa3b, v126
	v_mul_f32_e32 v6, v34, v6
	v_add_f32_e32 v34, 1.0, v129
	v_exp_f32_e32 v124, v124
	v_mul_f32_e32 v128, 0xbfb8aa3b, v127
	v_rcp_f32_e32 v34, v34
	v_exp_f32_e32 v128, v128
	v_add_f32_e32 v124, 1.0, v124
	v_rcp_f32_e32 v124, v124
	v_mul_f32_e32 v34, v125, v34
	v_add_f32_e32 v125, 1.0, v128
	v_rcp_f32_e32 v125, v125
	v_mul_f32_e32 v7, v34, v7
	v_mul_f32_e32 v34, v126, v124
	v_mul_f32_e32 v8, v34, v8
	v_mul_f32_e32 v34, v127, v125
	v_mul_f32_e32 v124, 0xbfb8aa3b, v120
	v_mul_f32_e32 v125, 0xbfb8aa3b, v121
	v_exp_f32_e32 v124, v124
	v_exp_f32_e32 v125, v125
	v_mul_f32_e32 v9, v34, v9
	v_add_f32_e32 v34, 1.0, v124
	v_add_f32_e32 v124, 1.0, v125
	v_mul_f32_e32 v125, 0xbfb8aa3b, v122
	v_rcp_f32_e32 v34, v34
	v_exp_f32_e32 v125, v125
	v_rcp_f32_e32 v124, v124
	v_mul_f32_e32 v34, v120, v34
	v_add_f32_e32 v120, 1.0, v125
	v_mul_f32_e32 v10, v34, v10
	v_mul_f32_e32 v34, v121, v124
	v_rcp_f32_e32 v120, v120
	v_mul_f32_e32 v121, 0xbfb8aa3b, v123
	v_exp_f32_e32 v121, v121
	v_mul_f32_e32 v11, v34, v11
	v_mul_f32_e32 v34, v122, v120
	v_mul_f32_e32 v120, 0xbfb8aa3b, v116
	v_mul_f32_e32 v12, v34, v12
	v_add_f32_e32 v34, 1.0, v121
	v_exp_f32_e32 v120, v120
	v_mul_f32_e32 v121, 0xbfb8aa3b, v117
	v_exp_f32_e32 v121, v121
	v_rcp_f32_e32 v34, v34
	v_add_f32_e32 v120, 1.0, v120
	v_rcp_f32_e32 v120, v120
	v_add_f32_e32 v121, 1.0, v121
	v_rcp_f32_e32 v121, v121
	v_mul_f32_e32 v34, v123, v34
	v_mul_f32_e32 v13, v34, v13
	v_mul_f32_e32 v34, v116, v120
	v_mul_f32_e32 v116, 0xbfb8aa3b, v118
	v_mul_f32_e32 v14, v34, v14
	v_mul_f32_e32 v34, v117, v121
	v_exp_f32_e32 v116, v116
	v_mul_f32_e32 v117, 0xbfb8aa3b, v119
	v_exp_f32_e32 v117, v117
	v_mul_f32_e32 v15, v34, v15
	v_add_f32_e32 v34, 1.0, v116
	v_rcp_f32_e32 v34, v34
	v_add_f32_e32 v116, 1.0, v117
	v_mul_f32_e32 v117, 0xbfb8aa3b, v112
	v_rcp_f32_e32 v116, v116
	v_exp_f32_e32 v117, v117
	v_mul_f32_e32 v34, v118, v34
	v_mul_f32_e32 v16, v34, v16
	v_mul_f32_e32 v34, v119, v116
	v_add_f32_e32 v116, 1.0, v117
	v_rcp_f32_e32 v116, v116
	v_mul_f32_e32 v117, 0xbfb8aa3b, v113
	v_exp_f32_e32 v117, v117
	v_mul_f32_e32 v17, v34, v17
	v_mul_f32_e32 v34, v112, v116
	v_mul_f32_e32 v112, 0xbfb8aa3b, v114
	v_mul_f32_e32 v18, v34, v18
	v_add_f32_e32 v34, 1.0, v117
	v_exp_f32_e32 v112, v112
	v_mul_f32_e32 v116, 0xbfb8aa3b, v115
	v_rcp_f32_e32 v34, v34
	v_exp_f32_e32 v116, v116
	v_add_f32_e32 v112, 1.0, v112
	v_rcp_f32_e32 v112, v112
	v_mul_f32_e32 v34, v113, v34
	v_add_f32_e32 v113, 1.0, v116
	v_rcp_f32_e32 v113, v113
	v_mul_f32_e32 v19, v34, v19
	v_mul_f32_e32 v34, v114, v112
	v_mul_f32_e32 v20, v34, v20
	v_mul_f32_e32 v34, v115, v113
	v_mul_f32_e32 v112, 0xbfb8aa3b, v108
	v_mul_f32_e32 v113, 0xbfb8aa3b, v109
	v_exp_f32_e32 v112, v112
	v_exp_f32_e32 v113, v113
	v_mul_f32_e32 v21, v34, v21
	v_permlane32_swap_b32_e32 v2, v18
	v_add_f32_e32 v34, 1.0, v112
	v_add_f32_e32 v112, 1.0, v113
	v_mul_f32_e32 v113, 0xbfb8aa3b, v110
	v_rcp_f32_e32 v34, v34
	v_exp_f32_e32 v113, v113
	v_rcp_f32_e32 v112, v112
	v_permlane32_swap_b32_e32 v3, v19
	v_mul_f32_e32 v34, v108, v34
	v_add_f32_e32 v108, 1.0, v113
	v_mul_f32_e32 v22, v34, v22
	v_mul_f32_e32 v34, v109, v112
	v_rcp_f32_e32 v108, v108
	v_mul_f32_e32 v109, 0xbfb8aa3b, v111
	v_exp_f32_e32 v109, v109
	v_mul_f32_e32 v23, v34, v23
	v_mul_f32_e32 v34, v110, v108
	v_mul_f32_e32 v108, 0xbfb8aa3b, v104
	v_mul_f32_e32 v24, v34, v24
	v_add_f32_e32 v34, 1.0, v109
	v_exp_f32_e32 v108, v108
	v_mul_f32_e32 v109, 0xbfb8aa3b, v105
	v_exp_f32_e32 v109, v109
	v_rcp_f32_e32 v34, v34
	v_add_f32_e32 v108, 1.0, v108
	v_rcp_f32_e32 v108, v108
	v_add_f32_e32 v109, 1.0, v109
	v_rcp_f32_e32 v109, v109
	v_mul_f32_e32 v34, v111, v34
	v_mul_f32_e32 v25, v34, v25
	v_mul_f32_e32 v34, v104, v108
	v_mul_f32_e32 v104, 0xbfb8aa3b, v106
	v_mul_f32_e32 v26, v34, v26
	v_mul_f32_e32 v34, v105, v109
	v_exp_f32_e32 v104, v104
	v_mul_f32_e32 v105, 0xbfb8aa3b, v107
	v_exp_f32_e32 v105, v105
	v_mul_f32_e32 v27, v34, v27
	v_add_f32_e32 v34, 1.0, v104
	v_rcp_f32_e32 v34, v34
	v_add_f32_e32 v104, 1.0, v105
	v_mul_f32_e32 v105, 0xbfb8aa3b, v100
	v_rcp_f32_e32 v104, v104
	v_exp_f32_e32 v105, v105
	v_mul_f32_e32 v34, v106, v34
	v_mul_f32_e32 v28, v34, v28
	v_mul_f32_e32 v34, v107, v104
	v_add_f32_e32 v104, 1.0, v105
	v_rcp_f32_e32 v104, v104
	v_mul_f32_e32 v105, 0xbfb8aa3b, v101
	v_exp_f32_e32 v105, v105
	v_mul_f32_e32 v29, v34, v29
	v_mul_f32_e32 v34, v100, v104
	v_mul_f32_e32 v100, 0xbfb8aa3b, v102
	v_mul_f32_e32 v30, v34, v30
	v_add_f32_e32 v34, 1.0, v105
	v_exp_f32_e32 v100, v100
	v_mul_f32_e32 v104, 0xbfb8aa3b, v103
	v_rcp_f32_e32 v34, v34
	v_exp_f32_e32 v104, v104
	v_add_f32_e32 v100, 1.0, v100
	v_rcp_f32_e32 v100, v100
	v_mul_f32_e32 v34, v101, v34
	v_add_f32_e32 v101, 1.0, v104
	v_rcp_f32_e32 v101, v101
	v_mul_f32_e32 v31, v34, v31
	v_mul_f32_e32 v34, v102, v100
	v_permlane32_swap_b32_e32 v10, v26
	v_mul_f32_e32 v32, v34, v32
	v_mul_f32_e32 v34, v103, v101
	v_permlane32_swap_b32_e32 v11, v27
	v_permlane16_swap_b32_e32 v2, v10
	v_permlane16_swap_b32_e32 v18, v26
	v_mul_f32_e32 v33, v34, v33
	v_permlane16_swap_b32_e32 v3, v11
	v_permlane16_swap_b32_e32 v19, v27
	v_permlane32_swap_b32_e32 v4, v20
	v_permlane32_swap_b32_e32 v12, v28
	v_permlane32_swap_b32_e32 v5, v21
	v_permlane32_swap_b32_e32 v13, v29
	v_permlane16_swap_b32_e32 v4, v12
	v_permlane16_swap_b32_e32 v20, v28
	v_permlane16_swap_b32_e32 v5, v13
	v_permlane16_swap_b32_e32 v21, v29
	v_max_f32_e64 v34, |v2|, |v18|
	v_max3_f32 v34, v34, |v3|, |v19|
	v_permlane32_swap_b32_e32 v6, v22
	v_permlane32_swap_b32_e32 v14, v30
	v_permlane32_swap_b32_e32 v7, v23
	v_permlane32_swap_b32_e32 v15, v31
	v_permlane16_swap_b32_e32 v6, v14
	v_permlane16_swap_b32_e32 v22, v30
	v_permlane16_swap_b32_e32 v7, v15
	v_permlane16_swap_b32_e32 v23, v31
	v_max3_f32 v34, v34, |v4|, |v20|
	v_max3_f32 v34, v34, |v5|, |v21|
	v_permlane32_swap_b32_e32 v8, v24
	v_permlane32_swap_b32_e32 v16, v32
	v_permlane32_swap_b32_e32 v9, v25
	v_permlane32_swap_b32_e32 v17, v33
	v_permlane16_swap_b32_e32 v8, v16
	v_permlane16_swap_b32_e32 v24, v32
	v_permlane16_swap_b32_e32 v9, v17
	v_permlane16_swap_b32_e32 v25, v33
	v_max3_f32 v34, v34, |v6|, |v22|
	v_max3_f32 v34, v34, |v7|, |v23|
	v_max3_f32 v34, v34, |v8|, |v24|
	v_max3_f32 v34, v34, |v9|, |v25|
	v_max3_f32 v34, v34, |v10|, |v26|
	v_max3_f32 v34, v34, |v11|, |v27|
	v_max3_f32 v34, v34, |v12|, |v28|
	v_max3_f32 v34, v34, |v13|, |v29|
	v_max3_f32 v34, v34, |v14|, |v30|
	v_max3_f32 v34, v34, |v15|, |v31|
	v_max3_f32 v34, v34, |v16|, |v32|
	v_max3_f32 v34, v34, |v17|, |v33|
	v_bfe_u32 v100, v34, 23, 8
	v_and_b32_e32 v34, 0x7fffff, v34
	v_cmp_gt_u32_e32 vcc, s63, v34
	v_lshl_add_u32 v108, s52, 8, v147
	s_lshl_b32 s52, s53, 7
	v_cndmask_b32_e64 v34, -2, -3, vcc
	v_add3_u32 v34, v100, v34, s64
	v_max_i32_e32 v34, 0xffffff88, v34
	v_add_u32_e32 v34, 0x7f, v34
	v_lshlrev_b32_e32 v100, 23, v34
	v_cvt_scalef32_2xpk16_fp6_f32 v[102:107], v[2:17], v[18:33], v100
	v_mul_f32_e32 v4, 0xbfb8aa3b, v96
	v_exp_f32_e32 v4, v4
	v_mul_f32_e32 v5, 0xbfb8aa3b, v97
	v_exp_f32_e32 v5, v5
	v_mov_b64_e32 v[100:101], s[20:21]
	v_add_f32_e32 v4, 1.0, v4
	v_rcp_f32_e32 v4, v4
	v_add_f32_e32 v5, 1.0, v5
	v_mad_i64_i32 v[2:3], s[4:5], v108, s66, v[100:101]
	s_ashr_i32 s53, s52, 31
	v_rcp_f32_e32 v5, v5
	v_mul_f32_e32 v10, 0xbfb8aa3b, v80
	v_mul_f32_e32 v18, 0xbfb8aa3b, v68
	v_mul_f32_e32 v26, 0xbfb8aa3b, v52
	v_lshl_add_u64 v[2:3], v[2:3], 0, s[52:53]
	v_exp_f32_e32 v10, v10
	v_mul_f32_e32 v11, 0xbfb8aa3b, v81
	v_exp_f32_e32 v18, v18
	v_mul_f32_e32 v19, 0xbfb8aa3b, v69
	v_exp_f32_e32 v26, v26
	v_mul_f32_e32 v27, 0xbfb8aa3b, v53
	v_mul_lo_u32 v34, v34, s65
	v_lshl_add_u64 v[2:3], v[2:3], 0, s[18:19]
	v_mov_b32_e32 v32, v106
	v_mov_b32_e32 v33, v107
	v_exp_f32_e32 v11, v11
	v_exp_f32_e32 v19, v19
	v_exp_f32_e32 v27, v27
	global_store_dwordx4 v[2:3], v[102:105], off
	global_store_dwordx4 v[2:3], v[32:35], off offset:64
	v_mul_f32_e32 v2, v96, v4
	v_mul_f32_e32 v4, 0xbfb8aa3b, v98
	v_mul_f32_e32 v12, 0xbfb8aa3b, v82
	v_mul_f32_e32 v20, 0xbfb8aa3b, v70
	v_mul_f32_e32 v28, 0xbfb8aa3b, v54
	v_mul_f32_e32 v30, 0xbfb8aa3b, v44
	v_mul_f32_e32 v3, v97, v5
	v_exp_f32_e32 v4, v4
	v_mul_f32_e32 v5, 0xbfb8aa3b, v99
	v_exp_f32_e32 v12, v12
	v_mul_f32_e32 v13, 0xbfb8aa3b, v83
	v_exp_f32_e32 v20, v20
	v_mul_f32_e32 v21, 0xbfb8aa3b, v71
	v_exp_f32_e32 v28, v28
	v_mul_f32_e32 v29, 0xbfb8aa3b, v55
	v_exp_f32_e32 v30, v30
	v_mul_f32_e32 v31, 0xbfb8aa3b, v45
	v_exp_f32_e32 v5, v5
	v_add_f32_e32 v10, 1.0, v10
	v_exp_f32_e32 v13, v13
	v_add_f32_e32 v18, 1.0, v18
	v_exp_f32_e32 v21, v21
	v_add_f32_e32 v26, 1.0, v26
	v_exp_f32_e32 v29, v29
	v_exp_f32_e32 v31, v31
	v_mul_f32_e32 v6, 0xbfb8aa3b, v92
	v_rcp_f32_e32 v10, v10
	v_add_f32_e32 v11, 1.0, v11
	v_mul_f32_e32 v14, 0xbfb8aa3b, v76
	v_rcp_f32_e32 v18, v18
	v_add_f32_e32 v19, 1.0, v19
	v_mul_f32_e32 v22, 0xbfb8aa3b, v56
	v_rcp_f32_e32 v26, v26
	v_add_f32_e32 v27, 1.0, v27
	v_exp_f32_e32 v6, v6
	v_mul_f32_e32 v7, 0xbfb8aa3b, v93
	v_rcp_f32_e32 v11, v11
	v_exp_f32_e32 v14, v14
	v_mul_f32_e32 v15, 0xbfb8aa3b, v77
	v_rcp_f32_e32 v19, v19
	v_exp_f32_e32 v22, v22
	v_mul_f32_e32 v23, 0xbfb8aa3b, v57
	v_rcp_f32_e32 v27, v27
	v_mul_f32_e32 v32, 0xbfb8aa3b, v46
	v_add_f32_e32 v4, 1.0, v4
	v_exp_f32_e32 v7, v7
	v_add_f32_e32 v12, 1.0, v12
	v_exp_f32_e32 v15, v15
	v_add_f32_e32 v20, 1.0, v20
	v_exp_f32_e32 v23, v23
	v_add_f32_e32 v28, 1.0, v28
	v_add_f32_e32 v30, 1.0, v30
	v_exp_f32_e32 v32, v32
	v_rcp_f32_e32 v4, v4
	v_add_f32_e32 v5, 1.0, v5
	v_mul_f32_e32 v8, 0xbfb8aa3b, v94
	v_rcp_f32_e32 v12, v12
	v_add_f32_e32 v13, 1.0, v13
	v_mul_f32_e32 v16, 0xbfb8aa3b, v78
	v_rcp_f32_e32 v20, v20
	v_add_f32_e32 v21, 1.0, v21
	v_mul_f32_e32 v24, 0xbfb8aa3b, v58
	v_rcp_f32_e32 v28, v28
	v_add_f32_e32 v29, 1.0, v29
	v_rcp_f32_e32 v30, v30
	v_add_f32_e32 v31, 1.0, v31
	v_rcp_f32_e32 v5, v5
	v_exp_f32_e32 v8, v8
	v_mul_f32_e32 v9, 0xbfb8aa3b, v95
	v_mul_f32_e32 v10, v80, v10
	v_rcp_f32_e32 v13, v13
	v_exp_f32_e32 v16, v16
	v_mul_f32_e32 v17, 0xbfb8aa3b, v79
	v_mul_f32_e32 v18, v68, v18
	v_rcp_f32_e32 v21, v21
	v_exp_f32_e32 v24, v24
	v_mul_f32_e32 v25, 0xbfb8aa3b, v59
	v_mul_f32_e32 v26, v52, v26
	v_rcp_f32_e32 v29, v29
	v_rcp_f32_e32 v31, v31
	v_mul_f32_e32 v33, 0xbfb8aa3b, v47
	v_mul_f32_e32 v2, v2, v88
	v_add_f32_e32 v6, 1.0, v6
	v_exp_f32_e32 v9, v9
	v_mul_f32_e32 v10, v10, v72
	v_mul_f32_e32 v11, v81, v11
	v_add_f32_e32 v14, 1.0, v14
	v_exp_f32_e32 v17, v17
	v_mul_f32_e32 v18, v18, v60
	v_mul_f32_e32 v19, v69, v19
	v_add_f32_e32 v22, 1.0, v22
	v_exp_f32_e32 v25, v25
	v_mul_f32_e32 v26, v26, v40
	v_mul_f32_e32 v27, v53, v27
	v_exp_f32_e32 v33, v33
	v_mul_f32_e32 v3, v3, v89
	v_rcp_f32_e32 v6, v6
	v_add_f32_e32 v7, 1.0, v7
	v_mul_f32_e32 v11, v11, v73
	v_rcp_f32_e32 v14, v14
	v_add_f32_e32 v15, 1.0, v15
	v_mul_f32_e32 v19, v19, v61
	v_rcp_f32_e32 v22, v22
	v_add_f32_e32 v23, 1.0, v23
	v_mul_f32_e32 v27, v27, v41
	v_add_f32_e32 v32, 1.0, v32
	v_permlane32_swap_b32_e32 v2, v18
	v_permlane32_swap_b32_e32 v10, v26
	v_mul_f32_e32 v4, v98, v4
	v_rcp_f32_e32 v7, v7
	v_mul_f32_e32 v12, v82, v12
	v_rcp_f32_e32 v15, v15
	v_mul_f32_e32 v20, v70, v20
	v_rcp_f32_e32 v23, v23
	v_mul_f32_e32 v28, v54, v28
	v_mul_f32_e32 v30, v44, v30
	v_rcp_f32_e32 v32, v32
	v_permlane32_swap_b32_e32 v3, v19
	v_permlane32_swap_b32_e32 v11, v27
	v_permlane16_swap_b32_e32 v2, v10
	v_permlane16_swap_b32_e32 v18, v26
	v_mul_f32_e32 v4, v4, v90
	v_mul_f32_e32 v5, v99, v5
	v_add_f32_e32 v8, 1.0, v8
	v_mul_f32_e32 v12, v12, v74
	v_mul_f32_e32 v13, v83, v13
	v_add_f32_e32 v16, 1.0, v16
	v_mul_f32_e32 v20, v20, v62
	v_mul_f32_e32 v21, v71, v21
	v_add_f32_e32 v24, 1.0, v24
	v_mul_f32_e32 v28, v28, v42
	v_mul_f32_e32 v29, v55, v29
	v_mul_f32_e32 v30, v30, v36
	v_mul_f32_e32 v31, v45, v31
	v_permlane16_swap_b32_e32 v3, v11
	v_permlane16_swap_b32_e32 v19, v27
	v_mul_f32_e32 v5, v5, v91
	v_rcp_f32_e32 v8, v8
	v_add_f32_e32 v9, 1.0, v9
	v_mul_f32_e32 v13, v13, v75
	v_rcp_f32_e32 v16, v16
	v_add_f32_e32 v17, 1.0, v17
	v_mul_f32_e32 v21, v21, v63
	v_rcp_f32_e32 v24, v24
	v_add_f32_e32 v25, 1.0, v25
	v_mul_f32_e32 v29, v29, v43
	v_add_f32_e32 v33, 1.0, v33
	v_mul_f32_e32 v31, v31, v37
	v_permlane32_swap_b32_e32 v4, v20
	v_permlane32_swap_b32_e32 v12, v28
	v_mul_f32_e32 v6, v92, v6
	v_rcp_f32_e32 v9, v9
	v_mul_f32_e32 v14, v76, v14
	v_rcp_f32_e32 v17, v17
	v_mul_f32_e32 v22, v56, v22
	v_rcp_f32_e32 v25, v25
	v_rcp_f32_e32 v33, v33
	v_permlane32_swap_b32_e32 v5, v21
	v_permlane32_swap_b32_e32 v13, v29
	v_permlane16_swap_b32_e32 v4, v12
	v_permlane16_swap_b32_e32 v20, v28
	v_mul_f32_e32 v6, v6, v84
	v_mul_f32_e32 v7, v93, v7
	v_mul_f32_e32 v14, v14, v64
	v_mul_f32_e32 v15, v77, v15
	v_mul_f32_e32 v22, v22, v48
	v_mul_f32_e32 v23, v57, v23
	v_mul_f32_e32 v32, v46, v32
	v_permlane16_swap_b32_e32 v5, v13
	v_permlane16_swap_b32_e32 v21, v29
	v_max_f32_e64 v34, |v2|, |v18|
	v_max3_f32 v34, v34, |v3|, |v19|
	v_mul_f32_e32 v7, v7, v85
	v_mul_f32_e32 v15, v15, v65
	v_mul_f32_e32 v23, v23, v49
	v_mul_f32_e32 v32, v32, v38
	v_permlane32_swap_b32_e32 v6, v22
	v_permlane32_swap_b32_e32 v14, v30
	v_mul_f32_e32 v8, v94, v8
	v_mul_f32_e32 v16, v78, v16
	v_mul_f32_e32 v24, v58, v24
	v_permlane32_swap_b32_e32 v7, v23
	v_permlane32_swap_b32_e32 v15, v31
	v_permlane16_swap_b32_e32 v6, v14
	v_permlane16_swap_b32_e32 v22, v30
	v_mul_f32_e32 v8, v8, v86
	v_mul_f32_e32 v9, v95, v9
	v_mul_f32_e32 v16, v16, v66
	v_mul_f32_e32 v17, v79, v17
	v_mul_f32_e32 v24, v24, v50
	v_mul_f32_e32 v25, v59, v25
	v_mul_f32_e32 v33, v47, v33
	v_permlane16_swap_b32_e32 v7, v15
	v_permlane16_swap_b32_e32 v23, v31
	v_max3_f32 v34, v34, |v4|, |v20|
	v_max3_f32 v34, v34, |v5|, |v21|
	v_mul_f32_e32 v9, v9, v87
	v_mul_f32_e32 v17, v17, v67
	v_mul_f32_e32 v25, v25, v51
	v_mul_f32_e32 v33, v33, v39
	v_permlane32_swap_b32_e32 v8, v24
	v_permlane32_swap_b32_e32 v16, v32
	v_permlane32_swap_b32_e32 v9, v25
	v_permlane32_swap_b32_e32 v17, v33
	v_permlane16_swap_b32_e32 v8, v16
	v_permlane16_swap_b32_e32 v24, v32
	v_permlane16_swap_b32_e32 v9, v17
	v_permlane16_swap_b32_e32 v25, v33
	v_max3_f32 v34, v34, |v6|, |v22|
	v_max3_f32 v34, v34, |v7|, |v23|
	v_max3_f32 v34, v34, |v8|, |v24|
	v_max3_f32 v34, v34, |v9|, |v25|
	v_max3_f32 v34, v34, |v10|, |v26|
	v_max3_f32 v34, v34, |v11|, |v27|
	v_max3_f32 v34, v34, |v12|, |v28|
	v_max3_f32 v34, v34, |v13|, |v29|
	v_max3_f32 v34, v34, |v14|, |v30|
	v_max3_f32 v34, v34, |v15|, |v31|
	v_max3_f32 v34, v34, |v16|, |v32|
	v_max3_f32 v34, v34, |v17|, |v33|
	v_bfe_u32 v36, v34, 23, 8
	v_and_b32_e32 v34, 0x7fffff, v34
	v_cmp_gt_u32_e32 vcc, s63, v34
	s_nop 1
	v_cndmask_b32_e64 v34, -2, -3, vcc
	v_add3_u32 v34, v36, v34, s64
	v_max_i32_e32 v34, 0xffffff88, v34
	v_add_u32_e32 v34, 0x7f, v34
	v_lshlrev_b32_e32 v42, 23, v34
	v_cvt_scalef32_2xpk16_fp6_f32 v[36:41], v[2:17], v[18:33], v42
	v_add_u32_e32 v2, 0x80, v108
	v_mad_i64_i32 v[2:3], s[4:5], v2, s66, v[100:101]
	v_lshl_add_u64 v[2:3], v[2:3], 0, s[52:53]
	v_mul_lo_u32 v34, v34, s65
	v_lshl_add_u64 v[2:3], v[2:3], 0, s[18:19]
	v_mov_b32_e32 v32, v40
	v_mov_b32_e32 v33, v41
	s_andn2_b64 vcc, exec, s[6:7]
	s_mov_b64 s[4:5], -1
	global_store_dwordx4 v[2:3], v[36:39], off
	global_store_dwordx4 v[2:3], v[32:35], off offset:64
	s_cbranch_vccnz .LBB0_987
	s_andn2_b64 vcc, exec, s[16:17]
	s_cbranch_vccnz .LBB0_986
	s_barrier
	s_branch .LBB0_986

.LBB0_1216:
	ds_read_b128 v[142:145], v160
	ds_read_b128 v[146:149], v160 offset:1024
	ds_read_b128 v[150:153], v160 offset:2048
	ds_read_b128 v[154:157], v160 offset:3072
	ds_read_b128 v[164:167], v161
	ds_read_b128 v[168:171], v161 offset:1024
	ds_read_b128 v[172:175], v161 offset:2048
	ds_read_b128 v[176:179], v161 offset:3072
	s_add_u32 s65, s86, 0xfff80080
	s_addc_u32 s88, s87, -1
	s_cmp_eq_u32 s63, 28
	s_cselect_b32 s89, s4, s88
	s_cselect_b32 s88, s5, s65
	s_cselect_b32 s91, s9, s45
	s_cselect_b32 s90, s11, s22
	v_lshl_add_u64 v[158:159], s[86:87], 0, v[136:137]
	s_add_i32 m0, s28, 0xc000
	ds_read_b128 v[180:183], v162
	ds_read_b128 v[184:187], v162 offset:1024
	ds_read_b128 v[188:191], v162 offset:2048
	ds_read_b128 v[192:195], v162 offset:3072
	ds_read_b128 v[196:199], v162 offset:4096
	ds_read_b128 v[200:203], v162 offset:5120
	ds_read_b128 v[204:207], v162 offset:6144
	ds_read_b128 v[208:211], v162 offset:7168
	global_load_lds_dwordx4 v[158:159], off
	v_lshl_add_u64 v[158:159], v[158:159], 0, s[14:15]
	s_add_i32 m0, s28, 0xe000
	s_nop 0
	global_load_lds_dwordx4 v[158:159], off
	s_waitcnt vmcnt(8)
	s_waitcnt lgkmcnt(0)
	s_barrier
	s_setprio 1
	s_waitcnt lgkmcnt(0)
	v_mfma_f32_16x16x32_bf16 v[126:129], v[142:145], v[180:183], v[126:129]
	v_mfma_f32_16x16x32_bf16 v[122:125], v[150:153], v[180:183], v[122:125]
	v_mfma_f32_16x16x32_bf16 v[118:121], v[142:145], v[188:191], v[118:121]
	v_mfma_f32_16x16x32_bf16 v[114:117], v[150:153], v[188:191], v[114:117]
	v_mfma_f32_16x16x32_bf16 v[110:113], v[142:145], v[196:199], v[110:113]
	v_mfma_f32_16x16x32_bf16 v[106:109], v[150:153], v[196:199], v[106:109]
	v_mfma_f32_16x16x32_bf16 v[102:105], v[142:145], v[204:207], v[102:105]
	v_mfma_f32_16x16x32_bf16 v[98:101], v[150:153], v[204:207], v[98:101]
	v_mfma_f32_16x16x32_bf16 v[126:129], v[146:149], v[184:187], v[126:129]
	v_mfma_f32_16x16x32_bf16 v[122:125], v[154:157], v[184:187], v[122:125]
	v_mfma_f32_16x16x32_bf16 v[118:121], v[146:149], v[192:195], v[118:121]
	v_mfma_f32_16x16x32_bf16 v[114:117], v[154:157], v[192:195], v[114:117]
	v_mfma_f32_16x16x32_bf16 v[110:113], v[146:149], v[200:203], v[110:113]
	v_mfma_f32_16x16x32_bf16 v[106:109], v[154:157], v[200:203], v[106:109]
	v_mfma_f32_16x16x32_bf16 v[102:105], v[146:149], v[208:211], v[102:105]
	v_mfma_f32_16x16x32_bf16 v[98:101], v[154:157], v[208:211], v[98:101]
	v_mfma_f32_16x16x32_bf16 v[62:65], v[164:167], v[180:183], v[62:65]
	v_mfma_f32_16x16x32_bf16 v[58:61], v[172:175], v[180:183], v[58:61]
	v_mfma_f32_16x16x32_bf16 v[54:57], v[164:167], v[188:191], v[54:57]
	v_mfma_f32_16x16x32_bf16 v[50:53], v[172:175], v[188:191], v[50:53]
	v_mfma_f32_16x16x32_bf16 v[46:49], v[164:167], v[196:199], v[46:49]
	v_mfma_f32_16x16x32_bf16 v[42:45], v[172:175], v[196:199], v[42:45]
	v_mfma_f32_16x16x32_bf16 v[38:41], v[164:167], v[204:207], v[38:41]
	v_mfma_f32_16x16x32_bf16 v[34:37], v[172:175], v[204:207], v[34:37]
	v_mfma_f32_16x16x32_bf16 v[62:65], v[168:171], v[184:187], v[62:65]
	v_mfma_f32_16x16x32_bf16 v[58:61], v[176:179], v[184:187], v[58:61]
	v_mfma_f32_16x16x32_bf16 v[54:57], v[168:171], v[192:195], v[54:57]
	v_mfma_f32_16x16x32_bf16 v[50:53], v[176:179], v[192:195], v[50:53]
	v_mfma_f32_16x16x32_bf16 v[46:49], v[168:171], v[200:203], v[46:49]
	v_mfma_f32_16x16x32_bf16 v[42:45], v[176:179], v[200:203], v[42:45]
	v_mfma_f32_16x16x32_bf16 v[38:41], v[168:171], v[208:211], v[38:41]
	v_mfma_f32_16x16x32_bf16 v[34:37], v[176:179], v[208:211], v[34:37]
	s_setprio 0
	s_barrier
	s_add_i32 s65, s97, s25
	v_lshl_add_u64 v[158:159], s[90:91], 0, v[132:133]
	s_mov_b32 m0, s65
	ds_read_b128 v[180:183], v162 offset:16384
	ds_read_b128 v[184:187], v162 offset:17408
	ds_read_b128 v[188:191], v162 offset:18432
	ds_read_b128 v[192:195], v162 offset:19456
	ds_read_b128 v[196:199], v162 offset:20480
	ds_read_b128 v[200:203], v162 offset:21504
	ds_read_b128 v[204:207], v162 offset:22528
	ds_read_b128 v[208:211], v162 offset:23552
	global_load_lds_dwordx4 v[158:159], off
	v_lshl_add_u64 v[212:213], v[158:159], 0, s[14:15]
	s_add_i32 m0, s65, 0x2000
	s_add_i32 s65, s30, s25
	global_load_lds_dwordx4 v[212:213], off
	v_lshl_add_u64 v[212:213], v[158:159], 0, s[16:17]
	s_mov_b32 m0, s65
	s_nop 0
	global_load_lds_dwordx4 v[212:213], off
	v_lshl_add_u64 v[212:213], v[158:159], 0, s[18:19]
	s_add_i32 m0, s65, 0x2000
	s_nop 0
	global_load_lds_dwordx4 v[212:213], off
	v_lshl_add_u64 v[212:213], s[88:89], 0, v[130:131]
	s_mov_b32 m0, s28
	v_lshl_add_u64 v[214:215], v[212:213], 0, s[14:15]
	global_load_lds_dwordx4 v[212:213], off
	s_mov_b32 m0, s29
	s_nop 0
	global_load_lds_dwordx4 v[214:215], off
	s_waitcnt vmcnt(8)
	s_waitcnt lgkmcnt(0)
	s_barrier
	s_setprio 1
	s_waitcnt lgkmcnt(0)
	v_mfma_f32_16x16x32_bf16 v[94:97], v[142:145], v[180:183], v[94:97]
	v_mfma_f32_16x16x32_bf16 v[90:93], v[150:153], v[180:183], v[90:93]
	v_mfma_f32_16x16x32_bf16 v[86:89], v[142:145], v[188:191], v[86:89]
	v_mfma_f32_16x16x32_bf16 v[82:85], v[150:153], v[188:191], v[82:85]
	v_mfma_f32_16x16x32_bf16 v[78:81], v[142:145], v[196:199], v[78:81]
	v_mfma_f32_16x16x32_bf16 v[74:77], v[150:153], v[196:199], v[74:77]
	v_mfma_f32_16x16x32_bf16 v[70:73], v[142:145], v[204:207], v[70:73]
	v_mfma_f32_16x16x32_bf16 v[66:69], v[150:153], v[204:207], v[66:69]
	v_mfma_f32_16x16x32_bf16 v[94:97], v[146:149], v[184:187], v[94:97]
	v_mfma_f32_16x16x32_bf16 v[90:93], v[154:157], v[184:187], v[90:93]
	v_mfma_f32_16x16x32_bf16 v[86:89], v[146:149], v[192:195], v[86:89]
	v_mfma_f32_16x16x32_bf16 v[82:85], v[154:157], v[192:195], v[82:85]
	v_mfma_f32_16x16x32_bf16 v[78:81], v[146:149], v[200:203], v[78:81]
	v_mfma_f32_16x16x32_bf16 v[74:77], v[154:157], v[200:203], v[74:77]
	v_mfma_f32_16x16x32_bf16 v[70:73], v[146:149], v[208:211], v[70:73]
	v_mfma_f32_16x16x32_bf16 v[66:69], v[154:157], v[208:211], v[66:69]
	v_mfma_f32_16x16x32_bf16 v[30:33], v[164:167], v[180:183], v[30:33]
	v_mfma_f32_16x16x32_bf16 v[26:29], v[172:175], v[180:183], v[26:29]
	v_mfma_f32_16x16x32_bf16 v[22:25], v[164:167], v[188:191], v[22:25]
	v_mfma_f32_16x16x32_bf16 v[18:21], v[172:175], v[188:191], v[18:21]
	v_mfma_f32_16x16x32_bf16 v[14:17], v[164:167], v[196:199], v[14:17]
	v_mfma_f32_16x16x32_bf16 v[10:13], v[172:175], v[196:199], v[10:13]
	v_mfma_f32_16x16x32_bf16 v[6:9], v[164:167], v[204:207], v[6:9]
	v_mfma_f32_16x16x32_bf16 v[2:5], v[172:175], v[204:207], v[2:5]
	v_mfma_f32_16x16x32_bf16 v[30:33], v[168:171], v[184:187], v[30:33]
	v_mfma_f32_16x16x32_bf16 v[26:29], v[176:179], v[184:187], v[26:29]
	v_mfma_f32_16x16x32_bf16 v[22:25], v[168:171], v[192:195], v[22:25]
	v_mfma_f32_16x16x32_bf16 v[18:21], v[176:179], v[192:195], v[18:21]
	v_mfma_f32_16x16x32_bf16 v[14:17], v[168:171], v[200:203], v[14:17]
	v_mfma_f32_16x16x32_bf16 v[10:13], v[176:179], v[200:203], v[10:13]
	v_mfma_f32_16x16x32_bf16 v[6:9], v[168:171], v[208:211], v[6:9]
	v_mfma_f32_16x16x32_bf16 v[2:5], v[176:179], v[208:211], v[2:5]
	s_setprio 0
	s_barrier
	s_add_i32 s65, 0, 0x18000
	v_add_u32_e32 v134, s65, v1
	s_add_i32 s88, 0, 0x1c000
	ds_read_b128 v[142:145], v134
	ds_read_b128 v[146:149], v134 offset:1024
	ds_read_b128 v[150:153], v134 offset:2048
	ds_read_b128 v[154:157], v134 offset:3072
	v_add_u32_e32 v134, s88, v1
	ds_read_b128 v[164:167], v134
	ds_read_b128 v[168:171], v134 offset:1024
	ds_read_b128 v[172:175], v134 offset:2048
	ds_read_b128 v[176:179], v134 offset:3072
	s_mov_b32 m0, s33
	v_lshl_add_u64 v[214:215], v[212:213], 0, s[16:17]
	ds_read_b128 v[180:183], v162 offset:32768
	ds_read_b128 v[184:187], v162 offset:33792
	ds_read_b128 v[188:191], v162 offset:34816
	ds_read_b128 v[192:195], v162 offset:35840
	ds_read_b128 v[196:199], v162 offset:36864
	ds_read_b128 v[200:203], v162 offset:37888
	ds_read_b128 v[204:207], v162 offset:38912
	ds_read_b128 v[208:211], v162 offset:39936
	global_load_lds_dwordx4 v[214:215], off
	v_lshl_add_u64 v[214:215], v[212:213], 0, s[18:19]
	s_mov_b32 m0, s40
	s_nop 0
	global_load_lds_dwordx4 v[214:215], off
	s_waitcnt vmcnt(8)
	s_waitcnt lgkmcnt(0)
	s_barrier
	s_setprio 1
	s_waitcnt lgkmcnt(0)
	v_mfma_f32_16x16x32_bf16 v[126:129], v[142:145], v[180:183], v[126:129]
	v_mfma_f32_16x16x32_bf16 v[122:125], v[150:153], v[180:183], v[122:125]
	v_mfma_f32_16x16x32_bf16 v[118:121], v[142:145], v[188:191], v[118:121]
	v_mfma_f32_16x16x32_bf16 v[114:117], v[150:153], v[188:191], v[114:117]
	v_mfma_f32_16x16x32_bf16 v[110:113], v[142:145], v[196:199], v[110:113]
	v_mfma_f32_16x16x32_bf16 v[106:109], v[150:153], v[196:199], v[106:109]
	v_mfma_f32_16x16x32_bf16 v[102:105], v[142:145], v[204:207], v[102:105]
	v_mfma_f32_16x16x32_bf16 v[98:101], v[150:153], v[204:207], v[98:101]
	v_mfma_f32_16x16x32_bf16 v[126:129], v[146:149], v[184:187], v[126:129]
	v_mfma_f32_16x16x32_bf16 v[122:125], v[154:157], v[184:187], v[122:125]
	v_mfma_f32_16x16x32_bf16 v[118:121], v[146:149], v[192:195], v[118:121]
	v_mfma_f32_16x16x32_bf16 v[114:117], v[154:157], v[192:195], v[114:117]
	v_mfma_f32_16x16x32_bf16 v[110:113], v[146:149], v[200:203], v[110:113]
	v_mfma_f32_16x16x32_bf16 v[106:109], v[154:157], v[200:203], v[106:109]
	v_mfma_f32_16x16x32_bf16 v[102:105], v[146:149], v[208:211], v[102:105]
	v_mfma_f32_16x16x32_bf16 v[98:101], v[154:157], v[208:211], v[98:101]
	v_mfma_f32_16x16x32_bf16 v[62:65], v[164:167], v[180:183], v[62:65]
	v_mfma_f32_16x16x32_bf16 v[58:61], v[172:175], v[180:183], v[58:61]
	v_mfma_f32_16x16x32_bf16 v[54:57], v[164:167], v[188:191], v[54:57]
	v_mfma_f32_16x16x32_bf16 v[50:53], v[172:175], v[188:191], v[50:53]
	v_mfma_f32_16x16x32_bf16 v[46:49], v[164:167], v[196:199], v[46:49]
	v_mfma_f32_16x16x32_bf16 v[42:45], v[172:175], v[196:199], v[42:45]
	v_mfma_f32_16x16x32_bf16 v[38:41], v[164:167], v[204:207], v[38:41]
	v_mfma_f32_16x16x32_bf16 v[34:37], v[172:175], v[204:207], v[34:37]
	v_mfma_f32_16x16x32_bf16 v[62:65], v[168:171], v[184:187], v[62:65]
	v_mfma_f32_16x16x32_bf16 v[58:61], v[176:179], v[184:187], v[58:61]
	v_mfma_f32_16x16x32_bf16 v[54:57], v[168:171], v[192:195], v[54:57]
	v_mfma_f32_16x16x32_bf16 v[50:53], v[176:179], v[192:195], v[50:53]
	v_mfma_f32_16x16x32_bf16 v[46:49], v[168:171], v[200:203], v[46:49]
	v_mfma_f32_16x16x32_bf16 v[42:45], v[176:179], v[200:203], v[42:45]
	v_mfma_f32_16x16x32_bf16 v[38:41], v[168:171], v[208:211], v[38:41]
	v_mfma_f32_16x16x32_bf16 v[34:37], v[176:179], v[208:211], v[34:37]
	s_setprio 0
	s_barrier
	s_add_i32 s65, s65, s25
	v_lshl_add_u64 v[214:215], v[158:159], 0, s[52:53]
	s_mov_b32 m0, s65
	ds_read_b128 v[180:183], v162 offset:49152
	ds_read_b128 v[184:187], v162 offset:50176
	ds_read_b128 v[188:191], v162 offset:51200
	ds_read_b128 v[192:195], v162 offset:52224
	ds_read_b128 v[196:199], v162 offset:53248
	ds_read_b128 v[200:203], v162 offset:54272
	ds_read_b128 v[204:207], v162 offset:55296
	ds_read_b128 v[208:211], v162 offset:56320
	global_load_lds_dwordx4 v[214:215], off
	v_lshl_add_u64 v[214:215], v[158:159], 0, s[54:55]
	s_add_i32 m0, s65, 0x2000
	s_add_i32 s65, s88, s25
	global_load_lds_dwordx4 v[214:215], off
	v_lshl_add_u64 v[214:215], v[158:159], 0, s[56:57]
	s_mov_b32 m0, s65
	v_lshl_add_u64 v[158:159], v[158:159], 0, s[58:59]
	global_load_lds_dwordx4 v[214:215], off
	s_add_i32 m0, s65, 0x2000
	s_nop 0
	global_load_lds_dwordx4 v[158:159], off
	v_lshl_add_u64 v[158:159], v[212:213], 0, s[52:53]
	s_mov_b32 m0, s41
	s_nop 0
	global_load_lds_dwordx4 v[158:159], off
	v_lshl_add_u64 v[158:159], v[212:213], 0, s[54:55]
	s_mov_b32 m0, s42
	s_nop 0
	global_load_lds_dwordx4 v[158:159], off
	s_waitcnt vmcnt(8)
	s_waitcnt lgkmcnt(0)
	s_barrier
	s_setprio 1
	s_waitcnt lgkmcnt(0)
	v_mfma_f32_16x16x32_bf16 v[94:97], v[142:145], v[180:183], v[94:97]
	v_mfma_f32_16x16x32_bf16 v[90:93], v[150:153], v[180:183], v[90:93]
	v_mfma_f32_16x16x32_bf16 v[86:89], v[142:145], v[188:191], v[86:89]
	v_mfma_f32_16x16x32_bf16 v[82:85], v[150:153], v[188:191], v[82:85]
	v_mfma_f32_16x16x32_bf16 v[78:81], v[142:145], v[196:199], v[78:81]
	v_mfma_f32_16x16x32_bf16 v[74:77], v[150:153], v[196:199], v[74:77]
	v_mfma_f32_16x16x32_bf16 v[70:73], v[142:145], v[204:207], v[70:73]
	v_mfma_f32_16x16x32_bf16 v[66:69], v[150:153], v[204:207], v[66:69]
	v_mfma_f32_16x16x32_bf16 v[94:97], v[146:149], v[184:187], v[94:97]
	v_mfma_f32_16x16x32_bf16 v[90:93], v[154:157], v[184:187], v[90:93]
	v_mfma_f32_16x16x32_bf16 v[86:89], v[146:149], v[192:195], v[86:89]
	v_mfma_f32_16x16x32_bf16 v[82:85], v[154:157], v[192:195], v[82:85]
	v_mfma_f32_16x16x32_bf16 v[78:81], v[146:149], v[200:203], v[78:81]
	v_mfma_f32_16x16x32_bf16 v[74:77], v[154:157], v[200:203], v[74:77]
	v_mfma_f32_16x16x32_bf16 v[70:73], v[146:149], v[208:211], v[70:73]
	v_mfma_f32_16x16x32_bf16 v[66:69], v[154:157], v[208:211], v[66:69]
	v_mfma_f32_16x16x32_bf16 v[30:33], v[164:167], v[180:183], v[30:33]
	v_mfma_f32_16x16x32_bf16 v[26:29], v[172:175], v[180:183], v[26:29]
	v_mfma_f32_16x16x32_bf16 v[22:25], v[164:167], v[188:191], v[22:25]
	v_mfma_f32_16x16x32_bf16 v[18:21], v[172:175], v[188:191], v[18:21]
	v_mfma_f32_16x16x32_bf16 v[14:17], v[164:167], v[196:199], v[14:17]
	v_mfma_f32_16x16x32_bf16 v[10:13], v[172:175], v[196:199], v[10:13]
	v_mfma_f32_16x16x32_bf16 v[6:9], v[164:167], v[204:207], v[6:9]
	v_mfma_f32_16x16x32_bf16 v[2:5], v[172:175], v[204:207], v[2:5]
	v_mfma_f32_16x16x32_bf16 v[30:33], v[168:171], v[184:187], v[30:33]
	v_mfma_f32_16x16x32_bf16 v[26:29], v[176:179], v[184:187], v[26:29]
	v_mfma_f32_16x16x32_bf16 v[22:25], v[168:171], v[192:195], v[22:25]
	v_mfma_f32_16x16x32_bf16 v[18:21], v[176:179], v[192:195], v[18:21]
	v_mfma_f32_16x16x32_bf16 v[14:17], v[168:171], v[200:203], v[14:17]
	v_mfma_f32_16x16x32_bf16 v[10:13], v[176:179], v[200:203], v[10:13]
	v_mfma_f32_16x16x32_bf16 v[6:9], v[168:171], v[208:211], v[6:9]
	v_mfma_f32_16x16x32_bf16 v[2:5], v[176:179], v[208:211], v[2:5]
	s_setprio 0
	s_barrier
	s_add_i32 s63, s63, 2
	s_add_u32 s86, s86, 0x100
	s_addc_u32 s87, s87, 0
	s_add_u32 s22, s22, 0x100
	s_addc_u32 s45, s45, 0
	s_cmp_gt_u32 s63, 29
	s_cbranch_scc0 .LBB0_1216
	s_and_b64 vcc, exec, s[60:61]
	s_cbranch_vccz .LBB0_1219
	s_barrier

.LBB0_1442:
	ds_read_b128 v[138:141], v156
	ds_read_b128 v[142:145], v156 offset:1024
	ds_read_b128 v[146:149], v156 offset:2048
	ds_read_b128 v[150:153], v156 offset:3072
	ds_read_b128 v[160:163], v157
	ds_read_b128 v[164:167], v157 offset:1024
	ds_read_b128 v[168:171], v157 offset:2048
	ds_read_b128 v[172:175], v157 offset:3072
	s_add_u32 s86, s8, 0xfff80080
	s_addc_u32 s87, s9, -1
	s_cmp_eq_u32 s85, 28
	s_cselect_b32 s87, s5, s87
	s_cselect_b32 s86, s7, s86
	s_cselect_b32 s89, s26, s84
	s_cselect_b32 s88, s61, s63
	v_lshl_add_u64 v[154:155], s[8:9], 0, v[136:137]
	s_add_i32 m0, s24, 0xc000
	ds_read_b128 v[176:179], v158
	ds_read_b128 v[180:183], v158 offset:1024
	ds_read_b128 v[184:187], v158 offset:2048
	ds_read_b128 v[188:191], v158 offset:3072
	ds_read_b128 v[192:195], v158 offset:4096
	ds_read_b128 v[196:199], v158 offset:5120
	ds_read_b128 v[200:203], v158 offset:6144
	ds_read_b128 v[204:207], v158 offset:7168
	global_load_lds_dwordx4 v[154:155], off
	v_lshl_add_u64 v[154:155], v[154:155], 0, s[16:17]
	s_add_i32 m0, s24, 0xe000
	s_nop 0
	global_load_lds_dwordx4 v[154:155], off
	s_waitcnt vmcnt(8)
	s_waitcnt lgkmcnt(0)
	s_barrier
	s_setprio 1
	s_waitcnt lgkmcnt(0)
	v_mfma_f32_16x16x32_bf16 v[126:129], v[138:141], v[176:179], v[126:129]
	v_mfma_f32_16x16x32_bf16 v[122:125], v[146:149], v[176:179], v[122:125]
	v_mfma_f32_16x16x32_bf16 v[118:121], v[138:141], v[184:187], v[118:121]
	v_mfma_f32_16x16x32_bf16 v[114:117], v[146:149], v[184:187], v[114:117]
	v_mfma_f32_16x16x32_bf16 v[110:113], v[138:141], v[192:195], v[110:113]
	v_mfma_f32_16x16x32_bf16 v[106:109], v[146:149], v[192:195], v[106:109]
	v_mfma_f32_16x16x32_bf16 v[102:105], v[138:141], v[200:203], v[102:105]
	v_mfma_f32_16x16x32_bf16 v[98:101], v[146:149], v[200:203], v[98:101]
	v_mfma_f32_16x16x32_bf16 v[126:129], v[142:145], v[180:183], v[126:129]
	v_mfma_f32_16x16x32_bf16 v[122:125], v[150:153], v[180:183], v[122:125]
	v_mfma_f32_16x16x32_bf16 v[118:121], v[142:145], v[188:191], v[118:121]
	v_mfma_f32_16x16x32_bf16 v[114:117], v[150:153], v[188:191], v[114:117]
	v_mfma_f32_16x16x32_bf16 v[110:113], v[142:145], v[196:199], v[110:113]
	v_mfma_f32_16x16x32_bf16 v[106:109], v[150:153], v[196:199], v[106:109]
	v_mfma_f32_16x16x32_bf16 v[102:105], v[142:145], v[204:207], v[102:105]
	v_mfma_f32_16x16x32_bf16 v[98:101], v[150:153], v[204:207], v[98:101]
	v_mfma_f32_16x16x32_bf16 v[62:65], v[160:163], v[176:179], v[62:65]
	v_mfma_f32_16x16x32_bf16 v[58:61], v[168:171], v[176:179], v[58:61]
	v_mfma_f32_16x16x32_bf16 v[54:57], v[160:163], v[184:187], v[54:57]
	v_mfma_f32_16x16x32_bf16 v[50:53], v[168:171], v[184:187], v[50:53]
	v_mfma_f32_16x16x32_bf16 v[46:49], v[160:163], v[192:195], v[46:49]
	v_mfma_f32_16x16x32_bf16 v[42:45], v[168:171], v[192:195], v[42:45]
	v_mfma_f32_16x16x32_bf16 v[38:41], v[160:163], v[200:203], v[38:41]
	v_mfma_f32_16x16x32_bf16 v[34:37], v[168:171], v[200:203], v[34:37]
	v_mfma_f32_16x16x32_bf16 v[62:65], v[164:167], v[180:183], v[62:65]
	v_mfma_f32_16x16x32_bf16 v[58:61], v[172:175], v[180:183], v[58:61]
	v_mfma_f32_16x16x32_bf16 v[54:57], v[164:167], v[188:191], v[54:57]
	v_mfma_f32_16x16x32_bf16 v[50:53], v[172:175], v[188:191], v[50:53]
	v_mfma_f32_16x16x32_bf16 v[46:49], v[164:167], v[196:199], v[46:49]
	v_mfma_f32_16x16x32_bf16 v[42:45], v[172:175], v[196:199], v[42:45]
	v_mfma_f32_16x16x32_bf16 v[38:41], v[164:167], v[204:207], v[38:41]
	v_mfma_f32_16x16x32_bf16 v[34:37], v[172:175], v[204:207], v[34:37]
	s_setprio 0
	s_barrier
	v_lshl_add_u64 v[154:155], s[88:89], 0, v[132:133]
	s_add_i32 s88, s50, s11
	s_mov_b32 m0, s88
	ds_read_b128 v[176:179], v158 offset:16384
	ds_read_b128 v[180:183], v158 offset:17408
	ds_read_b128 v[184:187], v158 offset:18432
	ds_read_b128 v[188:191], v158 offset:19456
	ds_read_b128 v[192:195], v158 offset:20480
	ds_read_b128 v[196:199], v158 offset:21504
	ds_read_b128 v[200:203], v158 offset:22528
	ds_read_b128 v[204:207], v158 offset:23552
	global_load_lds_dwordx4 v[154:155], off
	v_lshl_add_u64 v[208:209], v[154:155], 0, s[16:17]
	s_add_i32 m0, s88, 0x2000
	s_add_i32 s88, s51, s11
	global_load_lds_dwordx4 v[208:209], off
	v_lshl_add_u64 v[208:209], v[154:155], 0, s[18:19]
	s_mov_b32 m0, s88
	s_nop 0
	global_load_lds_dwordx4 v[208:209], off
	v_lshl_add_u64 v[208:209], v[154:155], 0, s[20:21]
	s_add_i32 m0, s88, 0x2000
	s_nop 0
	global_load_lds_dwordx4 v[208:209], off
	v_lshl_add_u64 v[208:209], s[86:87], 0, v[130:131]
	s_mov_b32 m0, s24
	v_lshl_add_u64 v[210:211], v[208:209], 0, s[16:17]
	global_load_lds_dwordx4 v[208:209], off
	s_mov_b32 m0, s25
	s_nop 0
	global_load_lds_dwordx4 v[210:211], off
	s_waitcnt vmcnt(8)
	s_waitcnt lgkmcnt(0)
	s_barrier
	s_setprio 1
	s_waitcnt lgkmcnt(0)
	v_mfma_f32_16x16x32_bf16 v[94:97], v[138:141], v[176:179], v[94:97]
	v_mfma_f32_16x16x32_bf16 v[90:93], v[146:149], v[176:179], v[90:93]
	v_mfma_f32_16x16x32_bf16 v[86:89], v[138:141], v[184:187], v[86:89]
	v_mfma_f32_16x16x32_bf16 v[82:85], v[146:149], v[184:187], v[82:85]
	v_mfma_f32_16x16x32_bf16 v[78:81], v[138:141], v[192:195], v[78:81]
	v_mfma_f32_16x16x32_bf16 v[74:77], v[146:149], v[192:195], v[74:77]
	v_mfma_f32_16x16x32_bf16 v[70:73], v[138:141], v[200:203], v[70:73]
	v_mfma_f32_16x16x32_bf16 v[66:69], v[146:149], v[200:203], v[66:69]
	v_mfma_f32_16x16x32_bf16 v[94:97], v[142:145], v[180:183], v[94:97]
	v_mfma_f32_16x16x32_bf16 v[90:93], v[150:153], v[180:183], v[90:93]
	v_mfma_f32_16x16x32_bf16 v[86:89], v[142:145], v[188:191], v[86:89]
	v_mfma_f32_16x16x32_bf16 v[82:85], v[150:153], v[188:191], v[82:85]
	v_mfma_f32_16x16x32_bf16 v[78:81], v[142:145], v[196:199], v[78:81]
	v_mfma_f32_16x16x32_bf16 v[74:77], v[150:153], v[196:199], v[74:77]
	v_mfma_f32_16x16x32_bf16 v[70:73], v[142:145], v[204:207], v[70:73]
	v_mfma_f32_16x16x32_bf16 v[66:69], v[150:153], v[204:207], v[66:69]
	v_mfma_f32_16x16x32_bf16 v[30:33], v[160:163], v[176:179], v[30:33]
	v_mfma_f32_16x16x32_bf16 v[26:29], v[168:171], v[176:179], v[26:29]
	v_mfma_f32_16x16x32_bf16 v[22:25], v[160:163], v[184:187], v[22:25]
	v_mfma_f32_16x16x32_bf16 v[18:21], v[168:171], v[184:187], v[18:21]
	v_mfma_f32_16x16x32_bf16 v[14:17], v[160:163], v[192:195], v[14:17]
	v_mfma_f32_16x16x32_bf16 v[10:13], v[168:171], v[192:195], v[10:13]
	v_mfma_f32_16x16x32_bf16 v[6:9], v[160:163], v[200:203], v[6:9]
	v_mfma_f32_16x16x32_bf16 v[2:5], v[168:171], v[200:203], v[2:5]
	v_mfma_f32_16x16x32_bf16 v[30:33], v[164:167], v[180:183], v[30:33]
	v_mfma_f32_16x16x32_bf16 v[26:29], v[172:175], v[180:183], v[26:29]
	v_mfma_f32_16x16x32_bf16 v[22:25], v[164:167], v[188:191], v[22:25]
	v_mfma_f32_16x16x32_bf16 v[18:21], v[172:175], v[188:191], v[18:21]
	v_mfma_f32_16x16x32_bf16 v[14:17], v[164:167], v[196:199], v[14:17]
	v_mfma_f32_16x16x32_bf16 v[10:13], v[172:175], v[196:199], v[10:13]
	v_mfma_f32_16x16x32_bf16 v[6:9], v[164:167], v[204:207], v[6:9]
	v_mfma_f32_16x16x32_bf16 v[2:5], v[172:175], v[204:207], v[2:5]
	s_setprio 0
	s_barrier
	s_add_i32 s86, 0, 0x18000
	v_add_u32_e32 v134, s86, v1
	s_add_i32 s87, 0, 0x1c000
	ds_read_b128 v[138:141], v134
	ds_read_b128 v[142:145], v134 offset:1024
	ds_read_b128 v[146:149], v134 offset:2048
	ds_read_b128 v[150:153], v134 offset:3072
	v_add_u32_e32 v134, s87, v1
	ds_read_b128 v[160:163], v134
	ds_read_b128 v[164:167], v134 offset:1024
	ds_read_b128 v[168:171], v134 offset:2048
	ds_read_b128 v[172:175], v134 offset:3072
	s_mov_b32 m0, s28
	v_lshl_add_u64 v[210:211], v[208:209], 0, s[18:19]
	ds_read_b128 v[176:179], v158 offset:32768
	ds_read_b128 v[180:183], v158 offset:33792
	ds_read_b128 v[184:187], v158 offset:34816
	ds_read_b128 v[188:191], v158 offset:35840
	ds_read_b128 v[192:195], v158 offset:36864
	ds_read_b128 v[196:199], v158 offset:37888
	ds_read_b128 v[200:203], v158 offset:38912
	ds_read_b128 v[204:207], v158 offset:39936
	global_load_lds_dwordx4 v[210:211], off
	v_lshl_add_u64 v[210:211], v[208:209], 0, s[20:21]
	s_mov_b32 m0, s29
	s_nop 0
	global_load_lds_dwordx4 v[210:211], off
	s_waitcnt vmcnt(8)
	s_waitcnt lgkmcnt(0)
	s_barrier
	s_setprio 1
	s_waitcnt lgkmcnt(0)
	v_mfma_f32_16x16x32_bf16 v[126:129], v[138:141], v[176:179], v[126:129]
	v_mfma_f32_16x16x32_bf16 v[122:125], v[146:149], v[176:179], v[122:125]
	v_mfma_f32_16x16x32_bf16 v[118:121], v[138:141], v[184:187], v[118:121]
	v_mfma_f32_16x16x32_bf16 v[114:117], v[146:149], v[184:187], v[114:117]
	v_mfma_f32_16x16x32_bf16 v[110:113], v[138:141], v[192:195], v[110:113]
	v_mfma_f32_16x16x32_bf16 v[106:109], v[146:149], v[192:195], v[106:109]
	v_mfma_f32_16x16x32_bf16 v[102:105], v[138:141], v[200:203], v[102:105]
	v_mfma_f32_16x16x32_bf16 v[98:101], v[146:149], v[200:203], v[98:101]
	v_mfma_f32_16x16x32_bf16 v[126:129], v[142:145], v[180:183], v[126:129]
	v_mfma_f32_16x16x32_bf16 v[122:125], v[150:153], v[180:183], v[122:125]
	v_mfma_f32_16x16x32_bf16 v[118:121], v[142:145], v[188:191], v[118:121]
	v_mfma_f32_16x16x32_bf16 v[114:117], v[150:153], v[188:191], v[114:117]
	v_mfma_f32_16x16x32_bf16 v[110:113], v[142:145], v[196:199], v[110:113]
	v_mfma_f32_16x16x32_bf16 v[106:109], v[150:153], v[196:199], v[106:109]
	v_mfma_f32_16x16x32_bf16 v[102:105], v[142:145], v[204:207], v[102:105]
	v_mfma_f32_16x16x32_bf16 v[98:101], v[150:153], v[204:207], v[98:101]
	v_mfma_f32_16x16x32_bf16 v[62:65], v[160:163], v[176:179], v[62:65]
	v_mfma_f32_16x16x32_bf16 v[58:61], v[168:171], v[176:179], v[58:61]
	v_mfma_f32_16x16x32_bf16 v[54:57], v[160:163], v[184:187], v[54:57]
	v_mfma_f32_16x16x32_bf16 v[50:53], v[168:171], v[184:187], v[50:53]
	v_mfma_f32_16x16x32_bf16 v[46:49], v[160:163], v[192:195], v[46:49]
	v_mfma_f32_16x16x32_bf16 v[42:45], v[168:171], v[192:195], v[42:45]
	v_mfma_f32_16x16x32_bf16 v[38:41], v[160:163], v[200:203], v[38:41]
	v_mfma_f32_16x16x32_bf16 v[34:37], v[168:171], v[200:203], v[34:37]
	v_mfma_f32_16x16x32_bf16 v[62:65], v[164:167], v[180:183], v[62:65]
	v_mfma_f32_16x16x32_bf16 v[58:61], v[172:175], v[180:183], v[58:61]
	v_mfma_f32_16x16x32_bf16 v[54:57], v[164:167], v[188:191], v[54:57]
	v_mfma_f32_16x16x32_bf16 v[50:53], v[172:175], v[188:191], v[50:53]
	v_mfma_f32_16x16x32_bf16 v[46:49], v[164:167], v[196:199], v[46:49]
	v_mfma_f32_16x16x32_bf16 v[42:45], v[172:175], v[196:199], v[42:45]
	v_mfma_f32_16x16x32_bf16 v[38:41], v[164:167], v[204:207], v[38:41]
	v_mfma_f32_16x16x32_bf16 v[34:37], v[172:175], v[204:207], v[34:37]
	s_setprio 0
	s_barrier
	s_add_i32 s86, s86, s11
	v_lshl_add_u64 v[210:211], v[154:155], 0, s[48:49]
	s_mov_b32 m0, s86
	ds_read_b128 v[176:179], v158 offset:49152
	ds_read_b128 v[180:183], v158 offset:50176
	ds_read_b128 v[184:187], v158 offset:51200
	ds_read_b128 v[188:191], v158 offset:52224
	ds_read_b128 v[192:195], v158 offset:53248
	ds_read_b128 v[196:199], v158 offset:54272
	ds_read_b128 v[200:203], v158 offset:55296
	ds_read_b128 v[204:207], v158 offset:56320
	global_load_lds_dwordx4 v[210:211], off
	v_lshl_add_u64 v[210:211], v[154:155], 0, s[52:53]
	s_add_i32 m0, s86, 0x2000
	s_add_i32 s86, s87, s11
	global_load_lds_dwordx4 v[210:211], off
	v_lshl_add_u64 v[210:211], v[154:155], 0, s[54:55]
	s_mov_b32 m0, s86
	v_lshl_add_u64 v[154:155], v[154:155], 0, s[56:57]
	global_load_lds_dwordx4 v[210:211], off
	s_add_i32 m0, s86, 0x2000
	s_nop 0
	global_load_lds_dwordx4 v[154:155], off
	v_lshl_add_u64 v[154:155], v[208:209], 0, s[48:49]
	s_mov_b32 m0, s33
	s_nop 0
	global_load_lds_dwordx4 v[154:155], off
	v_lshl_add_u64 v[154:155], v[208:209], 0, s[52:53]
	s_mov_b32 m0, s40
	s_nop 0
	global_load_lds_dwordx4 v[154:155], off
	s_waitcnt vmcnt(8)
	s_waitcnt lgkmcnt(0)
	s_barrier
	s_setprio 1
	s_waitcnt lgkmcnt(0)
	v_mfma_f32_16x16x32_bf16 v[94:97], v[138:141], v[176:179], v[94:97]
	v_mfma_f32_16x16x32_bf16 v[90:93], v[146:149], v[176:179], v[90:93]
	v_mfma_f32_16x16x32_bf16 v[86:89], v[138:141], v[184:187], v[86:89]
	v_mfma_f32_16x16x32_bf16 v[82:85], v[146:149], v[184:187], v[82:85]
	v_mfma_f32_16x16x32_bf16 v[78:81], v[138:141], v[192:195], v[78:81]
	v_mfma_f32_16x16x32_bf16 v[74:77], v[146:149], v[192:195], v[74:77]
	v_mfma_f32_16x16x32_bf16 v[70:73], v[138:141], v[200:203], v[70:73]
	v_mfma_f32_16x16x32_bf16 v[66:69], v[146:149], v[200:203], v[66:69]
	v_mfma_f32_16x16x32_bf16 v[94:97], v[142:145], v[180:183], v[94:97]
	v_mfma_f32_16x16x32_bf16 v[90:93], v[150:153], v[180:183], v[90:93]
	v_mfma_f32_16x16x32_bf16 v[86:89], v[142:145], v[188:191], v[86:89]
	v_mfma_f32_16x16x32_bf16 v[82:85], v[150:153], v[188:191], v[82:85]
	v_mfma_f32_16x16x32_bf16 v[78:81], v[142:145], v[196:199], v[78:81]
	v_mfma_f32_16x16x32_bf16 v[74:77], v[150:153], v[196:199], v[74:77]
	v_mfma_f32_16x16x32_bf16 v[70:73], v[142:145], v[204:207], v[70:73]
	v_mfma_f32_16x16x32_bf16 v[66:69], v[150:153], v[204:207], v[66:69]
	v_mfma_f32_16x16x32_bf16 v[30:33], v[160:163], v[176:179], v[30:33]
	v_mfma_f32_16x16x32_bf16 v[26:29], v[168:171], v[176:179], v[26:29]
	v_mfma_f32_16x16x32_bf16 v[22:25], v[160:163], v[184:187], v[22:25]
	v_mfma_f32_16x16x32_bf16 v[18:21], v[168:171], v[184:187], v[18:21]
	v_mfma_f32_16x16x32_bf16 v[14:17], v[160:163], v[192:195], v[14:17]
	v_mfma_f32_16x16x32_bf16 v[10:13], v[168:171], v[192:195], v[10:13]
	v_mfma_f32_16x16x32_bf16 v[6:9], v[160:163], v[200:203], v[6:9]
	v_mfma_f32_16x16x32_bf16 v[2:5], v[168:171], v[200:203], v[2:5]
	v_mfma_f32_16x16x32_bf16 v[30:33], v[164:167], v[180:183], v[30:33]
	v_mfma_f32_16x16x32_bf16 v[26:29], v[172:175], v[180:183], v[26:29]
	v_mfma_f32_16x16x32_bf16 v[22:25], v[164:167], v[188:191], v[22:25]
	v_mfma_f32_16x16x32_bf16 v[18:21], v[172:175], v[188:191], v[18:21]
	v_mfma_f32_16x16x32_bf16 v[14:17], v[164:167], v[196:199], v[14:17]
	v_mfma_f32_16x16x32_bf16 v[10:13], v[172:175], v[196:199], v[10:13]
	v_mfma_f32_16x16x32_bf16 v[6:9], v[164:167], v[204:207], v[6:9]
	v_mfma_f32_16x16x32_bf16 v[2:5], v[172:175], v[204:207], v[2:5]
	s_setprio 0
	s_barrier
	s_add_i32 s85, s85, 2
	s_add_u32 s8, s8, 0x100
	s_addc_u32 s9, s9, 0
	s_add_u32 s63, s63, 0x100
	s_addc_u32 s84, s84, 0
	s_cmp_gt_u32 s85, 29
	s_cbranch_scc0 .LBB0_1442
	s_and_b64 vcc, exec, s[58:59]
	s_cbranch_vccz .LBB0_1445
	s_barrier

.LBB0_1593:
	ds_read_b128 v[140:143], v157
	ds_read_b128 v[144:147], v157 offset:1024
	ds_read_b128 v[148:151], v157 offset:2048
	ds_read_b128 v[152:155], v157 offset:3072
	ds_read_b128 v[186:189], v161
	ds_read_b128 v[190:193], v161 offset:1024
	ds_read_b128 v[198:201], v161 offset:2048
	ds_read_b128 v[202:205], v161 offset:3072
	s_add_u32 s43, s56, 0xfffe0080
	s_addc_u32 s47, s57, -1
	s_cmp_eq_u32 s42, 4
	s_cselect_b32 s51, s4, s47
	s_cselect_b32 s50, s5, s43
	s_cselect_b32 s59, s7, s41
	s_cselect_b32 s58, s24, s25
	v_lshl_add_u64 v[158:159], s[56:57], 0, v[136:137]
	s_add_i32 m0, s67, 0xc000
	ds_read_b128 v[206:209], v165
	ds_read_b128 v[210:213], v165 offset:1024
	ds_read_b128 v[214:217], v165 offset:2048
	ds_read_b128 v[218:221], v165 offset:3072
	ds_read_b128 v[222:225], v165 offset:4096
	ds_read_b128 v[226:229], v165 offset:5120
	ds_read_b128 v[230:233], v165 offset:6144
	ds_read_b128 v[234:237], v165 offset:7168
	global_load_lds_dwordx4 v[158:159], off
	v_lshl_add_u64 v[158:159], v[158:159], 0, s[8:9]
	s_add_i32 m0, s67, 0xe000
	s_nop 0
	global_load_lds_dwordx4 v[158:159], off
	s_waitcnt vmcnt(8)
	s_waitcnt lgkmcnt(0)
	s_barrier
	s_setprio 1
	s_waitcnt lgkmcnt(0)
	v_mfma_f32_16x16x32_bf16 v[18:21], v[140:143], v[206:209], v[18:21]
	v_mfma_f32_16x16x32_bf16 v[22:25], v[148:151], v[206:209], v[22:25]
	v_mfma_f32_16x16x32_bf16 v[26:29], v[140:143], v[214:217], v[26:29]
	v_mfma_f32_16x16x32_bf16 v[30:33], v[148:151], v[214:217], v[30:33]
	v_mfma_f32_16x16x32_bf16 v[2:5], v[140:143], v[222:225], v[2:5]
	v_mfma_f32_16x16x32_bf16 v[6:9], v[148:151], v[222:225], v[6:9]
	v_mfma_f32_16x16x32_bf16 v[10:13], v[140:143], v[230:233], v[10:13]
	v_mfma_f32_16x16x32_bf16 v[14:17], v[148:151], v[230:233], v[14:17]
	v_mfma_f32_16x16x32_bf16 v[18:21], v[144:147], v[210:213], v[18:21]
	v_mfma_f32_16x16x32_bf16 v[22:25], v[152:155], v[210:213], v[22:25]
	v_mfma_f32_16x16x32_bf16 v[26:29], v[144:147], v[218:221], v[26:29]
	v_mfma_f32_16x16x32_bf16 v[30:33], v[152:155], v[218:221], v[30:33]
	v_mfma_f32_16x16x32_bf16 v[2:5], v[144:147], v[226:229], v[2:5]
	v_mfma_f32_16x16x32_bf16 v[6:9], v[152:155], v[226:229], v[6:9]
	v_mfma_f32_16x16x32_bf16 v[10:13], v[144:147], v[234:237], v[10:13]
	v_mfma_f32_16x16x32_bf16 v[14:17], v[152:155], v[234:237], v[14:17]
	v_mfma_f32_16x16x32_bf16 v[84:87], v[186:189], v[206:209], v[84:87]
	v_mfma_f32_16x16x32_bf16 v[88:91], v[198:201], v[206:209], v[88:91]
	v_mfma_f32_16x16x32_bf16 v[92:95], v[186:189], v[214:217], v[92:95]
	v_mfma_f32_16x16x32_bf16 v[96:99], v[198:201], v[214:217], v[96:99]
	v_mfma_f32_16x16x32_bf16 v[68:71], v[186:189], v[222:225], v[68:71]
	v_mfma_f32_16x16x32_bf16 v[72:75], v[198:201], v[222:225], v[72:75]
	v_mfma_f32_16x16x32_bf16 v[76:79], v[186:189], v[230:233], v[76:79]
	v_mfma_f32_16x16x32_bf16 v[80:83], v[198:201], v[230:233], v[80:83]
	v_mfma_f32_16x16x32_bf16 v[84:87], v[190:193], v[210:213], v[84:87]
	v_mfma_f32_16x16x32_bf16 v[88:91], v[202:205], v[210:213], v[88:91]
	v_mfma_f32_16x16x32_bf16 v[92:95], v[190:193], v[218:221], v[92:95]
	v_mfma_f32_16x16x32_bf16 v[96:99], v[202:205], v[218:221], v[96:99]
	v_mfma_f32_16x16x32_bf16 v[68:71], v[190:193], v[226:229], v[68:71]
	v_mfma_f32_16x16x32_bf16 v[72:75], v[202:205], v[226:229], v[72:75]
	v_mfma_f32_16x16x32_bf16 v[76:79], v[190:193], v[234:237], v[76:79]
	v_mfma_f32_16x16x32_bf16 v[80:83], v[202:205], v[234:237], v[80:83]
	s_setprio 0
	s_barrier
	s_add_i32 s43, s93, s66
	v_lshl_add_u64 v[158:159], s[58:59], 0, v[134:135]
	s_mov_b32 m0, s43
	ds_read_b128 v[206:209], v165 offset:16384
	ds_read_b128 v[210:213], v165 offset:17408
	ds_read_b128 v[214:217], v165 offset:18432
	ds_read_b128 v[218:221], v165 offset:19456
	ds_read_b128 v[222:225], v165 offset:20480
	ds_read_b128 v[226:229], v165 offset:21504
	ds_read_b128 v[230:233], v165 offset:22528
	ds_read_b128 v[234:237], v165 offset:23552
	global_load_lds_dwordx4 v[158:159], off
	v_lshl_add_u64 v[162:163], v[158:159], 0, s[8:9]
	s_add_i32 m0, s43, 0x2000
	s_add_i32 s43, s94, s66
	global_load_lds_dwordx4 v[162:163], off
	v_lshl_add_u64 v[162:163], v[158:159], 0, s[16:17]
	s_mov_b32 m0, s43
	s_nop 0
	global_load_lds_dwordx4 v[162:163], off
	v_lshl_add_u64 v[162:163], v[158:159], 0, s[18:19]
	s_add_i32 m0, s43, 0x2000
	s_nop 0
	global_load_lds_dwordx4 v[162:163], off
	v_lshl_add_u64 v[162:163], s[50:51], 0, v[132:133]
	s_mov_b32 m0, s67
	v_lshl_add_u64 v[166:167], v[162:163], 0, s[8:9]
	global_load_lds_dwordx4 v[162:163], off
	s_mov_b32 m0, s84
	s_nop 0
	global_load_lds_dwordx4 v[166:167], off
	s_waitcnt vmcnt(8)
	s_waitcnt lgkmcnt(0)
	s_barrier
	s_setprio 1
	s_waitcnt lgkmcnt(0)
	v_mfma_f32_16x16x32_bf16 v[116:119], v[140:143], v[206:209], v[116:119]
	v_mfma_f32_16x16x32_bf16 v[120:123], v[148:151], v[206:209], v[120:123]
	v_mfma_f32_16x16x32_bf16 v[124:127], v[140:143], v[214:217], v[124:127]
	v_mfma_f32_16x16x32_bf16 v[128:131], v[148:151], v[214:217], v[128:131]
	v_mfma_f32_16x16x32_bf16 v[100:103], v[140:143], v[222:225], v[100:103]
	v_mfma_f32_16x16x32_bf16 v[104:107], v[148:151], v[222:225], v[104:107]
	v_mfma_f32_16x16x32_bf16 v[108:111], v[140:143], v[230:233], v[108:111]
	v_mfma_f32_16x16x32_bf16 v[112:115], v[148:151], v[230:233], v[112:115]
	v_mfma_f32_16x16x32_bf16 v[116:119], v[144:147], v[210:213], v[116:119]
	v_mfma_f32_16x16x32_bf16 v[120:123], v[152:155], v[210:213], v[120:123]
	v_mfma_f32_16x16x32_bf16 v[124:127], v[144:147], v[218:221], v[124:127]
	v_mfma_f32_16x16x32_bf16 v[128:131], v[152:155], v[218:221], v[128:131]
	v_mfma_f32_16x16x32_bf16 v[100:103], v[144:147], v[226:229], v[100:103]
	v_mfma_f32_16x16x32_bf16 v[104:107], v[152:155], v[226:229], v[104:107]
	v_mfma_f32_16x16x32_bf16 v[108:111], v[144:147], v[234:237], v[108:111]
	v_mfma_f32_16x16x32_bf16 v[112:115], v[152:155], v[234:237], v[112:115]
	v_mfma_f32_16x16x32_bf16 v[52:55], v[186:189], v[206:209], v[52:55]
	v_mfma_f32_16x16x32_bf16 v[56:59], v[198:201], v[206:209], v[56:59]
	v_mfma_f32_16x16x32_bf16 v[60:63], v[186:189], v[214:217], v[60:63]
	v_mfma_f32_16x16x32_bf16 v[64:67], v[198:201], v[214:217], v[64:67]
	v_mfma_f32_16x16x32_bf16 v[36:39], v[186:189], v[222:225], v[36:39]
	v_mfma_f32_16x16x32_bf16 v[44:47], v[198:201], v[222:225], v[44:47]
	v_mfma_f32_16x16x32_bf16 v[48:51], v[186:189], v[230:233], v[48:51]
	v_mfma_f32_16x16x32_bf16 v[40:43], v[198:201], v[230:233], v[40:43]
	v_mfma_f32_16x16x32_bf16 v[52:55], v[190:193], v[210:213], v[52:55]
	v_mfma_f32_16x16x32_bf16 v[56:59], v[202:205], v[210:213], v[56:59]
	v_mfma_f32_16x16x32_bf16 v[60:63], v[190:193], v[218:221], v[60:63]
	v_mfma_f32_16x16x32_bf16 v[64:67], v[202:205], v[218:221], v[64:67]
	v_mfma_f32_16x16x32_bf16 v[36:39], v[190:193], v[226:229], v[36:39]
	v_mfma_f32_16x16x32_bf16 v[44:47], v[202:205], v[226:229], v[44:47]
	v_mfma_f32_16x16x32_bf16 v[48:51], v[190:193], v[234:237], v[48:51]
	v_mfma_f32_16x16x32_bf16 v[40:43], v[202:205], v[234:237], v[40:43]
	s_setprio 0
	s_barrier
	s_add_i32 s43, 0, 0x18000
	v_add_u32_e32 v34, s43, v1
	s_add_i32 s47, 0, 0x1c000
	ds_read_b128 v[140:143], v34
	ds_read_b128 v[144:147], v34 offset:1024
	ds_read_b128 v[148:151], v34 offset:2048
	ds_read_b128 v[152:155], v34 offset:3072
	v_add_u32_e32 v34, s47, v1
	ds_read_b128 v[186:189], v34
	ds_read_b128 v[190:193], v34 offset:1024
	ds_read_b128 v[198:201], v34 offset:2048
	ds_read_b128 v[202:205], v34 offset:3072
	s_mov_b32 m0, s85
	v_lshl_add_u64 v[166:167], v[162:163], 0, s[16:17]
	ds_read_b128 v[206:209], v165 offset:32768
	ds_read_b128 v[210:213], v165 offset:33792
	ds_read_b128 v[214:217], v165 offset:34816
	ds_read_b128 v[218:221], v165 offset:35840
	ds_read_b128 v[222:225], v165 offset:36864
	ds_read_b128 v[226:229], v165 offset:37888
	ds_read_b128 v[230:233], v165 offset:38912
	ds_read_b128 v[234:237], v165 offset:39936
	global_load_lds_dwordx4 v[166:167], off
	v_lshl_add_u64 v[166:167], v[162:163], 0, s[18:19]
	s_mov_b32 m0, s86
	s_nop 0
	global_load_lds_dwordx4 v[166:167], off
	s_waitcnt vmcnt(8)
	s_waitcnt lgkmcnt(0)
	s_barrier
	s_setprio 1
	s_waitcnt lgkmcnt(0)
	v_mfma_f32_16x16x32_bf16 v[18:21], v[140:143], v[206:209], v[18:21]
	v_mfma_f32_16x16x32_bf16 v[22:25], v[148:151], v[206:209], v[22:25]
	v_mfma_f32_16x16x32_bf16 v[26:29], v[140:143], v[214:217], v[26:29]
	v_mfma_f32_16x16x32_bf16 v[30:33], v[148:151], v[214:217], v[30:33]
	v_mfma_f32_16x16x32_bf16 v[2:5], v[140:143], v[222:225], v[2:5]
	v_mfma_f32_16x16x32_bf16 v[6:9], v[148:151], v[222:225], v[6:9]
	v_mfma_f32_16x16x32_bf16 v[10:13], v[140:143], v[230:233], v[10:13]
	v_mfma_f32_16x16x32_bf16 v[14:17], v[148:151], v[230:233], v[14:17]
	v_mfma_f32_16x16x32_bf16 v[18:21], v[144:147], v[210:213], v[18:21]
	v_mfma_f32_16x16x32_bf16 v[22:25], v[152:155], v[210:213], v[22:25]
	v_mfma_f32_16x16x32_bf16 v[26:29], v[144:147], v[218:221], v[26:29]
	v_mfma_f32_16x16x32_bf16 v[30:33], v[152:155], v[218:221], v[30:33]
	v_mfma_f32_16x16x32_bf16 v[2:5], v[144:147], v[226:229], v[2:5]
	v_mfma_f32_16x16x32_bf16 v[6:9], v[152:155], v[226:229], v[6:9]
	v_mfma_f32_16x16x32_bf16 v[10:13], v[144:147], v[234:237], v[10:13]
	v_mfma_f32_16x16x32_bf16 v[14:17], v[152:155], v[234:237], v[14:17]
	v_mfma_f32_16x16x32_bf16 v[84:87], v[186:189], v[206:209], v[84:87]
	v_mfma_f32_16x16x32_bf16 v[88:91], v[198:201], v[206:209], v[88:91]
	v_mfma_f32_16x16x32_bf16 v[92:95], v[186:189], v[214:217], v[92:95]
	v_mfma_f32_16x16x32_bf16 v[96:99], v[198:201], v[214:217], v[96:99]
	v_mfma_f32_16x16x32_bf16 v[68:71], v[186:189], v[222:225], v[68:71]
	v_mfma_f32_16x16x32_bf16 v[72:75], v[198:201], v[222:225], v[72:75]
	v_mfma_f32_16x16x32_bf16 v[76:79], v[186:189], v[230:233], v[76:79]
	v_mfma_f32_16x16x32_bf16 v[80:83], v[198:201], v[230:233], v[80:83]
	v_mfma_f32_16x16x32_bf16 v[84:87], v[190:193], v[210:213], v[84:87]
	v_mfma_f32_16x16x32_bf16 v[88:91], v[202:205], v[210:213], v[88:91]
	v_mfma_f32_16x16x32_bf16 v[92:95], v[190:193], v[218:221], v[92:95]
	v_mfma_f32_16x16x32_bf16 v[96:99], v[202:205], v[218:221], v[96:99]
	v_mfma_f32_16x16x32_bf16 v[68:71], v[190:193], v[226:229], v[68:71]
	v_mfma_f32_16x16x32_bf16 v[72:75], v[202:205], v[226:229], v[72:75]
	v_mfma_f32_16x16x32_bf16 v[76:79], v[190:193], v[234:237], v[76:79]
	v_mfma_f32_16x16x32_bf16 v[80:83], v[202:205], v[234:237], v[80:83]
	s_setprio 0
	s_barrier
	s_add_i32 s43, s43, s66
	v_lshl_add_u64 v[166:167], v[158:159], 0, s[30:31]
	s_mov_b32 m0, s43
	ds_read_b128 v[206:209], v165 offset:49152
	ds_read_b128 v[210:213], v165 offset:50176
	ds_read_b128 v[214:217], v165 offset:51200
	ds_read_b128 v[218:221], v165 offset:52224
	ds_read_b128 v[222:225], v165 offset:53248
	ds_read_b128 v[226:229], v165 offset:54272
	ds_read_b128 v[230:233], v165 offset:55296
	ds_read_b128 v[234:237], v165 offset:56320
	global_load_lds_dwordx4 v[166:167], off
	v_lshl_add_u64 v[166:167], v[158:159], 0, s[34:35]
	s_add_i32 m0, s43, 0x2000
	s_add_i32 s43, s47, s66
	global_load_lds_dwordx4 v[166:167], off
	v_lshl_add_u64 v[166:167], v[158:159], 0, s[36:37]
	s_mov_b32 m0, s43
	v_lshl_add_u64 v[158:159], v[158:159], 0, s[38:39]
	global_load_lds_dwordx4 v[166:167], off
	s_add_i32 m0, s43, 0x2000
	s_nop 0
	global_load_lds_dwordx4 v[158:159], off
	v_lshl_add_u64 v[158:159], v[162:163], 0, s[30:31]
	s_mov_b32 m0, s88
	s_nop 0
	global_load_lds_dwordx4 v[158:159], off
	v_lshl_add_u64 v[158:159], v[162:163], 0, s[34:35]
	s_mov_b32 m0, s89
	s_nop 0
	global_load_lds_dwordx4 v[158:159], off
	s_waitcnt vmcnt(8)
	s_waitcnt lgkmcnt(0)
	s_barrier
	s_setprio 1
	s_waitcnt lgkmcnt(0)
	v_mfma_f32_16x16x32_bf16 v[116:119], v[140:143], v[206:209], v[116:119]
	v_mfma_f32_16x16x32_bf16 v[120:123], v[148:151], v[206:209], v[120:123]
	v_mfma_f32_16x16x32_bf16 v[124:127], v[140:143], v[214:217], v[124:127]
	v_mfma_f32_16x16x32_bf16 v[128:131], v[148:151], v[214:217], v[128:131]
	v_mfma_f32_16x16x32_bf16 v[100:103], v[140:143], v[222:225], v[100:103]
	v_mfma_f32_16x16x32_bf16 v[104:107], v[148:151], v[222:225], v[104:107]
	v_mfma_f32_16x16x32_bf16 v[108:111], v[140:143], v[230:233], v[108:111]
	v_mfma_f32_16x16x32_bf16 v[112:115], v[148:151], v[230:233], v[112:115]
	v_mfma_f32_16x16x32_bf16 v[116:119], v[144:147], v[210:213], v[116:119]
	v_mfma_f32_16x16x32_bf16 v[120:123], v[152:155], v[210:213], v[120:123]
	v_mfma_f32_16x16x32_bf16 v[124:127], v[144:147], v[218:221], v[124:127]
	v_mfma_f32_16x16x32_bf16 v[128:131], v[152:155], v[218:221], v[128:131]
	v_mfma_f32_16x16x32_bf16 v[100:103], v[144:147], v[226:229], v[100:103]
	v_mfma_f32_16x16x32_bf16 v[104:107], v[152:155], v[226:229], v[104:107]
	v_mfma_f32_16x16x32_bf16 v[108:111], v[144:147], v[234:237], v[108:111]
	v_mfma_f32_16x16x32_bf16 v[112:115], v[152:155], v[234:237], v[112:115]
	v_mfma_f32_16x16x32_bf16 v[52:55], v[186:189], v[206:209], v[52:55]
	v_mfma_f32_16x16x32_bf16 v[56:59], v[198:201], v[206:209], v[56:59]
	v_mfma_f32_16x16x32_bf16 v[60:63], v[186:189], v[214:217], v[60:63]
	v_mfma_f32_16x16x32_bf16 v[64:67], v[198:201], v[214:217], v[64:67]
	v_mfma_f32_16x16x32_bf16 v[36:39], v[186:189], v[222:225], v[36:39]
	v_mfma_f32_16x16x32_bf16 v[44:47], v[198:201], v[222:225], v[44:47]
	v_mfma_f32_16x16x32_bf16 v[48:51], v[186:189], v[230:233], v[48:51]
	v_mfma_f32_16x16x32_bf16 v[40:43], v[198:201], v[230:233], v[40:43]
	v_mfma_f32_16x16x32_bf16 v[52:55], v[190:193], v[210:213], v[52:55]
	v_mfma_f32_16x16x32_bf16 v[56:59], v[202:205], v[210:213], v[56:59]
	v_mfma_f32_16x16x32_bf16 v[60:63], v[190:193], v[218:221], v[60:63]
	v_mfma_f32_16x16x32_bf16 v[64:67], v[202:205], v[218:221], v[64:67]
	v_mfma_f32_16x16x32_bf16 v[36:39], v[190:193], v[226:229], v[36:39]
	v_mfma_f32_16x16x32_bf16 v[44:47], v[202:205], v[226:229], v[44:47]
	v_mfma_f32_16x16x32_bf16 v[48:51], v[190:193], v[234:237], v[48:51]
	v_mfma_f32_16x16x32_bf16 v[40:43], v[202:205], v[234:237], v[40:43]
	s_setprio 0
	s_barrier
	s_add_i32 s42, s42, 2
	s_add_u32 s56, s56, 0x100
	s_addc_u32 s57, s57, 0
	s_add_u32 s25, s25, 0x100
	s_addc_u32 s41, s41, 0
	s_cmp_gt_u32 s42, 5
	s_cbranch_scc0 .LBB0_1593
	s_and_b64 vcc, exec, s[44:45]
	s_cbranch_vccz .LBB0_1596
	s_barrier

.LBB0_1652:
	ds_read_b128 v[4:7], v150
	ds_read_b128 v[8:11], v150 offset:1024
	ds_read_b128 v[12:15], v150 offset:2048
	ds_read_b128 v[16:19], v150 offset:3072
	ds_read_b128 v[20:23], v151
	ds_read_b128 v[24:27], v151 offset:1024
	ds_read_b128 v[28:31], v151 offset:2048
	ds_read_b128 v[36:39], v151 offset:3072
	s_ashr_i32 s65, s64, 31
	s_lshl_b64 s[84:85], s[64:65], 17
	s_add_u32 s84, s1, s84
	s_addc_u32 s85, s3, s85
	s_and_b64 s[86:87], s[94:95], exec
	s_cselect_b32 s91, s85, s93
	s_cselect_b32 s90, s84, s92
	s_ashr_i32 s67, s66, 31
	s_lshl_b64 s[86:87], s[66:67], 17
	s_add_u32 s86, s4, s86
	s_addc_u32 s87, s5, s87
	s_and_b64 s[94:95], s[94:95], exec
	s_cselect_b32 s95, s87, s89
	s_cselect_b32 s94, s86, s88
	v_lshl_add_u64 v[2:3], s[92:93], 0, v[134:135]
	s_mov_b32 m0, s51
	v_lshl_add_u64 v[32:33], v[2:3], 0, s[36:37]
	ds_read_b128 v[40:43], v152
	ds_read_b128 v[44:47], v152 offset:1024
	ds_read_b128 v[48:51], v152 offset:2048
	ds_read_b128 v[52:55], v152 offset:3072
	ds_read_b128 v[56:59], v152 offset:4096
	ds_read_b128 v[60:63], v152 offset:5120
	ds_read_b128 v[64:67], v152 offset:6144
	ds_read_b128 v[68:71], v152 offset:7168
	global_load_lds_dwordx4 v[32:33], off
	v_lshl_add_u64 v[32:33], v[2:3], 0, s[38:39]
	s_mov_b32 m0, s96
	s_nop 0
	global_load_lds_dwordx4 v[32:33], off
	s_waitcnt vmcnt(8)
	s_waitcnt lgkmcnt(0)
	s_barrier
	s_setprio 1
	s_waitcnt lgkmcnt(0)
	v_mfma_f32_16x16x32_bf16 v[72:75], v[4:7], v[40:43], 0
	v_mfma_f32_16x16x32_bf16 v[76:79], v[12:15], v[40:43], 0
	v_mfma_f32_16x16x32_bf16 v[80:83], v[4:7], v[48:51], 0
	v_mfma_f32_16x16x32_bf16 v[84:87], v[12:15], v[48:51], 0
	v_mfma_f32_16x16x32_bf16 v[88:91], v[4:7], v[56:59], 0
	v_mfma_f32_16x16x32_bf16 v[92:95], v[12:15], v[56:59], 0
	v_mfma_f32_16x16x32_bf16 v[96:99], v[4:7], v[64:67], 0
	v_mfma_f32_16x16x32_bf16 v[100:103], v[12:15], v[64:67], 0
	v_mfma_f32_16x16x32_bf16 v[72:75], v[8:11], v[44:47], v[72:75]
	v_mfma_f32_16x16x32_bf16 v[76:79], v[16:19], v[44:47], v[76:79]
	v_mfma_f32_16x16x32_bf16 v[80:83], v[8:11], v[52:55], v[80:83]
	v_mfma_f32_16x16x32_bf16 v[84:87], v[16:19], v[52:55], v[84:87]
	v_mfma_f32_16x16x32_bf16 v[88:91], v[8:11], v[60:63], v[88:91]
	v_mfma_f32_16x16x32_bf16 v[92:95], v[16:19], v[60:63], v[92:95]
	v_mfma_f32_16x16x32_bf16 v[96:99], v[8:11], v[68:71], v[96:99]
	v_mfma_f32_16x16x32_bf16 v[100:103], v[16:19], v[68:71], v[100:103]
	v_mfma_f32_16x16x32_bf16 v[104:107], v[20:23], v[40:43], 0
	v_mfma_f32_16x16x32_bf16 v[40:43], v[28:31], v[40:43], 0
	v_mfma_f32_16x16x32_bf16 v[104:107], v[24:27], v[44:47], v[104:107]
	v_mfma_f32_16x16x32_bf16 v[40:43], v[36:39], v[44:47], v[40:43]
	v_mfma_f32_16x16x32_bf16 v[44:47], v[20:23], v[48:51], 0
	v_mfma_f32_16x16x32_bf16 v[48:51], v[28:31], v[48:51], 0
	v_mfma_f32_16x16x32_bf16 v[44:47], v[24:27], v[52:55], v[44:47]
	v_mfma_f32_16x16x32_bf16 v[48:51], v[36:39], v[52:55], v[48:51]
	v_mfma_f32_16x16x32_bf16 v[52:55], v[20:23], v[56:59], 0
	v_mfma_f32_16x16x32_bf16 v[56:59], v[28:31], v[56:59], 0
	v_mfma_f32_16x16x32_bf16 v[52:55], v[24:27], v[60:63], v[52:55]
	v_mfma_f32_16x16x32_bf16 v[56:59], v[36:39], v[60:63], v[56:59]
	v_mfma_f32_16x16x32_bf16 v[60:63], v[20:23], v[64:67], 0
	v_mfma_f32_16x16x32_bf16 v[64:67], v[28:31], v[64:67], 0
	v_mfma_f32_16x16x32_bf16 v[60:63], v[24:27], v[68:71], v[60:63]
	v_mfma_f32_16x16x32_bf16 v[64:67], v[36:39], v[68:71], v[64:67]
	s_setprio 0
	s_barrier
	v_lshl_add_u64 v[32:33], s[88:89], 0, v[132:133]
	s_mov_b32 m0, s97
	v_lshl_add_u64 v[140:141], v[32:33], 0, s[46:47]
	ds_read_b128 v[68:71], v152 offset:16384
	ds_read_b128 v[108:111], v152 offset:17408
	ds_read_b128 v[112:115], v152 offset:18432
	ds_read_b128 v[116:119], v152 offset:19456
	ds_read_b128 v[120:123], v152 offset:20480
	ds_read_b128 v[124:127], v152 offset:21504
	ds_read_b128 v[128:131], v152 offset:22528
	ds_read_b128 v[136:139], v152 offset:23552
	global_load_lds_dwordx4 v[140:141], off
	v_lshl_add_u64 v[140:141], v[32:33], 0, s[48:49]
	s_mov_b32 m0, s24
	s_add_i32 s9, s25, 0x2000
	global_load_lds_dwordx4 v[140:141], off
	v_lshl_add_u64 v[140:141], v[32:33], 0, s[52:53]
	s_mov_b32 m0, s25
	s_nop 0
	global_load_lds_dwordx4 v[140:141], off
	v_lshl_add_u64 v[140:141], v[32:33], 0, s[54:55]
	s_mov_b32 m0, s9
	s_nop 0
	global_load_lds_dwordx4 v[140:141], off
	v_lshl_add_u64 v[140:141], v[2:3], 0, s[46:47]
	s_mov_b32 m0, s11
	s_nop 0
	global_load_lds_dwordx4 v[140:141], off
	v_lshl_add_u64 v[140:141], v[2:3], 0, s[48:49]
	s_mov_b32 m0, s28
	s_nop 0
	global_load_lds_dwordx4 v[140:141], off
	s_waitcnt vmcnt(8)
	s_waitcnt lgkmcnt(0)
	s_barrier
	s_setprio 1
	s_waitcnt lgkmcnt(0)
	v_mfma_f32_16x16x32_bf16 v[140:143], v[4:7], v[68:71], 0
	v_mfma_f32_16x16x32_bf16 v[156:159], v[4:7], v[112:115], 0
	v_mfma_f32_16x16x32_bf16 v[164:167], v[4:7], v[120:123], 0
	v_mfma_f32_16x16x32_bf16 v[4:7], v[4:7], v[128:131], 0
	v_mfma_f32_16x16x32_bf16 v[140:143], v[8:11], v[108:111], v[140:143]
	v_mfma_f32_16x16x32_bf16 v[156:159], v[8:11], v[116:119], v[156:159]
	v_mfma_f32_16x16x32_bf16 v[164:167], v[8:11], v[124:127], v[164:167]
	v_mfma_f32_16x16x32_bf16 v[4:7], v[8:11], v[136:139], v[4:7]
	v_mfma_f32_16x16x32_bf16 v[8:11], v[12:15], v[128:131], 0
	v_mfma_f32_16x16x32_bf16 v[144:147], v[12:15], v[68:71], 0
	v_mfma_f32_16x16x32_bf16 v[160:163], v[12:15], v[112:115], 0
	v_mfma_f32_16x16x32_bf16 v[168:171], v[12:15], v[120:123], 0
	v_mfma_f32_16x16x32_bf16 v[8:11], v[16:19], v[136:139], v[8:11]
	v_mfma_f32_16x16x32_bf16 v[144:147], v[16:19], v[108:111], v[144:147]
	v_mfma_f32_16x16x32_bf16 v[160:163], v[16:19], v[116:119], v[160:163]
	v_mfma_f32_16x16x32_bf16 v[168:171], v[16:19], v[124:127], v[168:171]
	v_mfma_f32_16x16x32_bf16 v[12:15], v[20:23], v[68:71], 0
	v_mfma_f32_16x16x32_bf16 v[16:19], v[28:31], v[68:71], 0
	v_mfma_f32_16x16x32_bf16 v[12:15], v[24:27], v[108:111], v[12:15]
	v_mfma_f32_16x16x32_bf16 v[16:19], v[36:39], v[108:111], v[16:19]
	v_mfma_f32_16x16x32_bf16 v[68:71], v[20:23], v[112:115], 0
	v_mfma_f32_16x16x32_bf16 v[108:111], v[28:31], v[112:115], 0
	v_mfma_f32_16x16x32_bf16 v[112:115], v[20:23], v[120:123], 0
	v_mfma_f32_16x16x32_bf16 v[20:23], v[20:23], v[128:131], 0
	v_mfma_f32_16x16x32_bf16 v[68:71], v[24:27], v[116:119], v[68:71]
	v_mfma_f32_16x16x32_bf16 v[108:111], v[36:39], v[116:119], v[108:111]
	v_mfma_f32_16x16x32_bf16 v[112:115], v[24:27], v[124:127], v[112:115]
	v_mfma_f32_16x16x32_bf16 v[116:119], v[28:31], v[120:123], 0
	v_mfma_f32_16x16x32_bf16 v[20:23], v[24:27], v[136:139], v[20:23]
	v_mfma_f32_16x16x32_bf16 v[24:27], v[28:31], v[128:131], 0
	v_mfma_f32_16x16x32_bf16 v[116:119], v[36:39], v[124:127], v[116:119]
	v_mfma_f32_16x16x32_bf16 v[24:27], v[36:39], v[136:139], v[24:27]
	s_setprio 0
	s_barrier
	s_add_i32 s89, 0, 0x18000
	s_add_i32 s67, 0, 0x1c000
	v_add_u32_e32 v34, s89, v1
	v_add_u32_e32 v155, s67, v1
	ds_read_b128 v[28:31], v34
	ds_read_b128 v[36:39], v34 offset:1024
	ds_read_b128 v[120:123], v34 offset:2048
	ds_read_b128 v[124:127], v34 offset:3072
	ds_read_b128 v[128:131], v155
	ds_read_b128 v[136:139], v155 offset:1024
	ds_read_b128 v[172:175], v155 offset:2048
	ds_read_b128 v[176:179], v155 offset:3072
	s_mov_b32 m0, s29
	v_lshl_add_u64 v[148:149], v[2:3], 0, s[52:53]
	ds_read_b128 v[180:183], v152 offset:32768
	ds_read_b128 v[184:187], v152 offset:33792
	ds_read_b128 v[188:191], v152 offset:34816
	ds_read_b128 v[192:195], v152 offset:35840
	ds_read_b128 v[196:199], v152 offset:36864
	ds_read_b128 v[200:203], v152 offset:37888
	ds_read_b128 v[204:207], v152 offset:38912
	ds_read_b128 v[208:211], v152 offset:39936
	global_load_lds_dwordx4 v[148:149], off
	v_lshl_add_u64 v[148:149], v[2:3], 0, s[54:55]
	s_mov_b32 m0, s33
	s_nop 0
	global_load_lds_dwordx4 v[148:149], off
	s_waitcnt vmcnt(8)
	s_waitcnt lgkmcnt(0)
	s_barrier
	s_setprio 1
	s_waitcnt lgkmcnt(0)
	v_mfma_f32_16x16x32_bf16 v[72:75], v[28:31], v[180:183], v[72:75]
	v_mfma_f32_16x16x32_bf16 v[76:79], v[120:123], v[180:183], v[76:79]
	v_mfma_f32_16x16x32_bf16 v[80:83], v[28:31], v[188:191], v[80:83]
	v_mfma_f32_16x16x32_bf16 v[84:87], v[120:123], v[188:191], v[84:87]
	v_mfma_f32_16x16x32_bf16 v[88:91], v[28:31], v[196:199], v[88:91]
	v_mfma_f32_16x16x32_bf16 v[92:95], v[120:123], v[196:199], v[92:95]
	v_mfma_f32_16x16x32_bf16 v[96:99], v[28:31], v[204:207], v[96:99]
	v_mfma_f32_16x16x32_bf16 v[100:103], v[120:123], v[204:207], v[100:103]
	v_mfma_f32_16x16x32_bf16 v[72:75], v[36:39], v[184:187], v[72:75]
	v_mfma_f32_16x16x32_bf16 v[76:79], v[124:127], v[184:187], v[76:79]
	v_mfma_f32_16x16x32_bf16 v[80:83], v[36:39], v[192:195], v[80:83]
	v_mfma_f32_16x16x32_bf16 v[84:87], v[124:127], v[192:195], v[84:87]
	v_mfma_f32_16x16x32_bf16 v[88:91], v[36:39], v[200:203], v[88:91]
	v_mfma_f32_16x16x32_bf16 v[92:95], v[124:127], v[200:203], v[92:95]
	v_mfma_f32_16x16x32_bf16 v[96:99], v[36:39], v[208:211], v[96:99]
	v_mfma_f32_16x16x32_bf16 v[100:103], v[124:127], v[208:211], v[100:103]
	v_mfma_f32_16x16x32_bf16 v[104:107], v[128:131], v[180:183], v[104:107]
	v_mfma_f32_16x16x32_bf16 v[40:43], v[172:175], v[180:183], v[40:43]
	v_mfma_f32_16x16x32_bf16 v[44:47], v[128:131], v[188:191], v[44:47]
	v_mfma_f32_16x16x32_bf16 v[48:51], v[172:175], v[188:191], v[48:51]
	v_mfma_f32_16x16x32_bf16 v[52:55], v[128:131], v[196:199], v[52:55]
	v_mfma_f32_16x16x32_bf16 v[56:59], v[172:175], v[196:199], v[56:59]
	v_mfma_f32_16x16x32_bf16 v[60:63], v[128:131], v[204:207], v[60:63]
	v_mfma_f32_16x16x32_bf16 v[64:67], v[172:175], v[204:207], v[64:67]
	v_mfma_f32_16x16x32_bf16 v[104:107], v[136:139], v[184:187], v[104:107]
	v_mfma_f32_16x16x32_bf16 v[40:43], v[176:179], v[184:187], v[40:43]
	v_mfma_f32_16x16x32_bf16 v[44:47], v[136:139], v[192:195], v[44:47]
	v_mfma_f32_16x16x32_bf16 v[48:51], v[176:179], v[192:195], v[48:51]
	v_mfma_f32_16x16x32_bf16 v[52:55], v[136:139], v[200:203], v[52:55]
	v_mfma_f32_16x16x32_bf16 v[56:59], v[176:179], v[200:203], v[56:59]
	v_mfma_f32_16x16x32_bf16 v[60:63], v[136:139], v[208:211], v[60:63]
	v_mfma_f32_16x16x32_bf16 v[64:67], v[176:179], v[208:211], v[64:67]
	s_setprio 0
	s_barrier
	s_add_i32 s89, s89, s10
	v_lshl_add_u64 v[148:149], v[32:33], 0, s[56:57]
	s_mov_b32 m0, s89
	s_add_i32 s65, s89, 0x2000
	ds_read_b128 v[180:183], v152 offset:49152
	ds_read_b128 v[184:187], v152 offset:50176
	ds_read_b128 v[188:191], v152 offset:51200
	ds_read_b128 v[192:195], v152 offset:52224
	ds_read_b128 v[196:199], v152 offset:53248
	ds_read_b128 v[200:203], v152 offset:54272
	ds_read_b128 v[204:207], v152 offset:55296
	ds_read_b128 v[208:211], v152 offset:56320
	global_load_lds_dwordx4 v[148:149], off
	v_lshl_add_u64 v[148:149], v[32:33], 0, s[58:59]
	s_mov_b32 m0, s65
	s_add_i32 s67, s67, s10
	global_load_lds_dwordx4 v[148:149], off
	v_lshl_add_u64 v[148:149], v[32:33], 0, s[60:61]
	s_mov_b32 m0, s67
	s_add_i32 s88, s67, 0x2000
	global_load_lds_dwordx4 v[148:149], off
	v_lshl_add_u64 v[32:33], v[32:33], 0, s[62:63]
	s_mov_b32 m0, s88
	s_nop 0
	global_load_lds_dwordx4 v[32:33], off
	v_lshl_add_u64 v[32:33], v[2:3], 0, s[56:57]
	s_mov_b32 m0, s41
	s_nop 0
	global_load_lds_dwordx4 v[32:33], off
	v_lshl_add_u64 v[32:33], v[2:3], 0, s[58:59]
	s_mov_b32 m0, s42
	s_nop 0
	global_load_lds_dwordx4 v[32:33], off
	s_waitcnt vmcnt(8)
	s_waitcnt lgkmcnt(0)
	s_barrier
	s_setprio 1
	s_waitcnt lgkmcnt(0)
	v_mfma_f32_16x16x32_bf16 v[4:7], v[28:31], v[204:207], v[4:7]
	v_mfma_f32_16x16x32_bf16 v[8:11], v[120:123], v[204:207], v[8:11]
	v_mfma_f32_16x16x32_bf16 v[140:143], v[28:31], v[180:183], v[140:143]
	v_mfma_f32_16x16x32_bf16 v[144:147], v[120:123], v[180:183], v[144:147]
	v_mfma_f32_16x16x32_bf16 v[156:159], v[28:31], v[188:191], v[156:159]
	v_mfma_f32_16x16x32_bf16 v[160:163], v[120:123], v[188:191], v[160:163]
	v_mfma_f32_16x16x32_bf16 v[164:167], v[28:31], v[196:199], v[164:167]
	v_mfma_f32_16x16x32_bf16 v[168:171], v[120:123], v[196:199], v[168:171]
	v_mfma_f32_16x16x32_bf16 v[4:7], v[36:39], v[208:211], v[4:7]
	v_mfma_f32_16x16x32_bf16 v[8:11], v[124:127], v[208:211], v[8:11]
	v_mfma_f32_16x16x32_bf16 v[140:143], v[36:39], v[184:187], v[140:143]
	v_mfma_f32_16x16x32_bf16 v[144:147], v[124:127], v[184:187], v[144:147]
	v_mfma_f32_16x16x32_bf16 v[156:159], v[36:39], v[192:195], v[156:159]
	v_mfma_f32_16x16x32_bf16 v[160:163], v[124:127], v[192:195], v[160:163]
	v_mfma_f32_16x16x32_bf16 v[164:167], v[36:39], v[200:203], v[164:167]
	v_mfma_f32_16x16x32_bf16 v[168:171], v[124:127], v[200:203], v[168:171]
	v_mfma_f32_16x16x32_bf16 v[12:15], v[128:131], v[180:183], v[12:15]
	v_mfma_f32_16x16x32_bf16 v[16:19], v[172:175], v[180:183], v[16:19]
	v_mfma_f32_16x16x32_bf16 v[28:31], v[128:131], v[188:191], v[68:71]
	v_mfma_f32_16x16x32_bf16 v[36:39], v[172:175], v[188:191], v[108:111]
	v_mfma_f32_16x16x32_bf16 v[68:71], v[128:131], v[196:199], v[112:115]
	v_mfma_f32_16x16x32_bf16 v[108:111], v[172:175], v[196:199], v[116:119]
	v_mfma_f32_16x16x32_bf16 v[20:23], v[128:131], v[204:207], v[20:23]
	v_mfma_f32_16x16x32_bf16 v[24:27], v[172:175], v[204:207], v[24:27]
	v_mfma_f32_16x16x32_bf16 v[12:15], v[136:139], v[184:187], v[12:15]
	v_mfma_f32_16x16x32_bf16 v[16:19], v[176:179], v[184:187], v[16:19]
	v_mfma_f32_16x16x32_bf16 v[28:31], v[136:139], v[192:195], v[28:31]
	v_mfma_f32_16x16x32_bf16 v[36:39], v[176:179], v[192:195], v[36:39]
	v_mfma_f32_16x16x32_bf16 v[68:71], v[136:139], v[200:203], v[68:71]
	v_mfma_f32_16x16x32_bf16 v[108:111], v[176:179], v[200:203], v[108:111]
	v_mfma_f32_16x16x32_bf16 v[20:23], v[136:139], v[208:211], v[20:23]
	v_mfma_f32_16x16x32_bf16 v[24:27], v[176:179], v[208:211], v[24:27]
	s_setprio 0
	s_barrier
	ds_read_b128 v[112:115], v150
	ds_read_b128 v[116:119], v150 offset:1024
	ds_read_b128 v[120:123], v150 offset:2048
	ds_read_b128 v[124:127], v150 offset:3072
	ds_read_b128 v[128:131], v151
	ds_read_b128 v[136:139], v151 offset:1024
	ds_read_b128 v[172:175], v151 offset:2048
	ds_read_b128 v[176:179], v151 offset:3072
	s_mov_b32 m0, s51
	v_lshl_add_u64 v[32:33], v[2:3], 0, s[60:61]
	ds_read_b128 v[180:183], v152
	ds_read_b128 v[184:187], v152 offset:1024
	ds_read_b128 v[188:191], v152 offset:2048
	ds_read_b128 v[192:195], v152 offset:3072
	ds_read_b128 v[196:199], v152 offset:4096
	ds_read_b128 v[200:203], v152 offset:5120
	ds_read_b128 v[204:207], v152 offset:6144
	ds_read_b128 v[208:211], v152 offset:7168
	global_load_lds_dwordx4 v[32:33], off
	v_lshl_add_u64 v[2:3], v[2:3], 0, s[62:63]
	s_mov_b32 m0, s96
	s_nop 0
	global_load_lds_dwordx4 v[2:3], off
	s_waitcnt vmcnt(8)
	s_waitcnt lgkmcnt(0)
	s_barrier
	s_setprio 1
	s_waitcnt lgkmcnt(0)
	v_mfma_f32_16x16x32_bf16 v[72:75], v[112:115], v[180:183], v[72:75]
	v_mfma_f32_16x16x32_bf16 v[76:79], v[120:123], v[180:183], v[76:79]
	v_mfma_f32_16x16x32_bf16 v[80:83], v[112:115], v[188:191], v[80:83]
	v_mfma_f32_16x16x32_bf16 v[84:87], v[120:123], v[188:191], v[84:87]
	v_mfma_f32_16x16x32_bf16 v[88:91], v[112:115], v[196:199], v[88:91]
	v_mfma_f32_16x16x32_bf16 v[92:95], v[120:123], v[196:199], v[92:95]
	v_mfma_f32_16x16x32_bf16 v[96:99], v[112:115], v[204:207], v[96:99]
	v_mfma_f32_16x16x32_bf16 v[100:103], v[120:123], v[204:207], v[100:103]
	v_mfma_f32_16x16x32_bf16 v[72:75], v[116:119], v[184:187], v[72:75]
	v_mfma_f32_16x16x32_bf16 v[76:79], v[124:127], v[184:187], v[76:79]
	v_mfma_f32_16x16x32_bf16 v[80:83], v[116:119], v[192:195], v[80:83]
	v_mfma_f32_16x16x32_bf16 v[84:87], v[124:127], v[192:195], v[84:87]
	v_mfma_f32_16x16x32_bf16 v[88:91], v[116:119], v[200:203], v[88:91]
	v_mfma_f32_16x16x32_bf16 v[92:95], v[124:127], v[200:203], v[92:95]
	v_mfma_f32_16x16x32_bf16 v[96:99], v[116:119], v[208:211], v[96:99]
	v_mfma_f32_16x16x32_bf16 v[100:103], v[124:127], v[208:211], v[100:103]
	v_mfma_f32_16x16x32_bf16 v[104:107], v[128:131], v[180:183], v[104:107]
	v_mfma_f32_16x16x32_bf16 v[40:43], v[172:175], v[180:183], v[40:43]
	v_mfma_f32_16x16x32_bf16 v[44:47], v[128:131], v[188:191], v[44:47]
	v_mfma_f32_16x16x32_bf16 v[48:51], v[172:175], v[188:191], v[48:51]
	v_mfma_f32_16x16x32_bf16 v[52:55], v[128:131], v[196:199], v[52:55]
	v_mfma_f32_16x16x32_bf16 v[56:59], v[172:175], v[196:199], v[56:59]
	v_mfma_f32_16x16x32_bf16 v[60:63], v[128:131], v[204:207], v[60:63]
	v_mfma_f32_16x16x32_bf16 v[64:67], v[172:175], v[204:207], v[64:67]
	v_mfma_f32_16x16x32_bf16 v[104:107], v[136:139], v[184:187], v[104:107]
	v_mfma_f32_16x16x32_bf16 v[40:43], v[176:179], v[184:187], v[40:43]
	v_mfma_f32_16x16x32_bf16 v[44:47], v[136:139], v[192:195], v[44:47]
	v_mfma_f32_16x16x32_bf16 v[48:51], v[176:179], v[192:195], v[48:51]
	v_mfma_f32_16x16x32_bf16 v[52:55], v[136:139], v[200:203], v[52:55]
	v_mfma_f32_16x16x32_bf16 v[56:59], v[176:179], v[200:203], v[56:59]
	v_mfma_f32_16x16x32_bf16 v[60:63], v[136:139], v[208:211], v[60:63]
	v_mfma_f32_16x16x32_bf16 v[64:67], v[176:179], v[208:211], v[64:67]
	s_setprio 0
	s_barrier
	s_mov_b32 m0, s97
	v_lshl_add_u64 v[148:149], s[94:95], 0, v[132:133]
	s_mov_b64 s[92:93], 0x8000
	ds_read_b128 v[180:183], v152 offset:16384
	ds_read_b128 v[184:187], v152 offset:17408
	ds_read_b128 v[188:191], v152 offset:18432
	ds_read_b128 v[192:195], v152 offset:19456
	ds_read_b128 v[196:199], v152 offset:20480
	ds_read_b128 v[200:203], v152 offset:21504
	ds_read_b128 v[204:207], v152 offset:22528
	ds_read_b128 v[208:211], v152 offset:23552
	global_load_lds_dwordx4 v[148:149], off
	v_lshl_add_u64 v[2:3], v[148:149], 0, s[92:93]
	s_mov_b32 m0, s24
	v_lshl_add_u64 v[252:253], s[90:91], 0, v[134:135]
	global_load_lds_dwordx4 v[2:3], off
	v_lshl_add_u64 v[2:3], v[148:149], 0, s[12:13]
	s_mov_b32 m0, s25
	s_nop 0
	global_load_lds_dwordx4 v[2:3], off
	v_lshl_add_u64 v[2:3], v[148:149], 0, s[14:15]
	s_mov_b32 m0, s9
	s_nop 0
	global_load_lds_dwordx4 v[2:3], off
	s_mov_b32 m0, s11
	v_lshl_add_u64 v[2:3], v[252:253], 0, s[92:93]
	global_load_lds_dwordx4 v[252:253], off
	s_mov_b32 m0, s28
	s_nop 0
	global_load_lds_dwordx4 v[2:3], off
	s_waitcnt vmcnt(8)
	s_waitcnt lgkmcnt(0)
	s_barrier
	s_setprio 1
	s_waitcnt lgkmcnt(0)
	v_mfma_f32_16x16x32_bf16 v[2:5], v[112:115], v[204:207], v[4:7]
	v_mfma_f32_16x16x32_bf16 v[140:143], v[112:115], v[180:183], v[140:143]
	v_mfma_f32_16x16x32_bf16 v[144:147], v[120:123], v[180:183], v[144:147]
	v_mfma_f32_16x16x32_bf16 v[156:159], v[112:115], v[188:191], v[156:159]
	v_mfma_f32_16x16x32_bf16 v[160:163], v[120:123], v[188:191], v[160:163]
	v_mfma_f32_16x16x32_bf16 v[164:167], v[112:115], v[196:199], v[164:167]
	v_mfma_f32_16x16x32_bf16 v[168:171], v[120:123], v[196:199], v[168:171]
	v_mfma_f32_16x16x32_bf16 v[212:215], v[116:119], v[208:211], v[2:5]
	v_mfma_f32_16x16x32_bf16 v[2:5], v[120:123], v[204:207], v[8:11]
	v_mfma_f32_16x16x32_bf16 v[140:143], v[116:119], v[184:187], v[140:143]
	v_mfma_f32_16x16x32_bf16 v[144:147], v[124:127], v[184:187], v[144:147]
	v_mfma_f32_16x16x32_bf16 v[156:159], v[116:119], v[192:195], v[156:159]
	v_mfma_f32_16x16x32_bf16 v[160:163], v[124:127], v[192:195], v[160:163]
	v_mfma_f32_16x16x32_bf16 v[164:167], v[116:119], v[200:203], v[164:167]
	v_mfma_f32_16x16x32_bf16 v[168:171], v[124:127], v[200:203], v[168:171]
	v_mfma_f32_16x16x32_bf16 v[216:219], v[124:127], v[208:211], v[2:5]
	v_mfma_f32_16x16x32_bf16 v[2:5], v[128:131], v[180:183], v[12:15]
	v_mfma_f32_16x16x32_bf16 v[220:223], v[136:139], v[184:187], v[2:5]
	v_mfma_f32_16x16x32_bf16 v[2:5], v[172:175], v[180:183], v[16:19]
	v_mfma_f32_16x16x32_bf16 v[180:183], v[176:179], v[184:187], v[2:5]
	v_mfma_f32_16x16x32_bf16 v[2:5], v[128:131], v[188:191], v[28:31]
	v_mfma_f32_16x16x32_bf16 v[184:187], v[136:139], v[192:195], v[2:5]
	v_mfma_f32_16x16x32_bf16 v[2:5], v[172:175], v[188:191], v[36:39]
	v_mfma_f32_16x16x32_bf16 v[188:191], v[176:179], v[192:195], v[2:5]
	v_mfma_f32_16x16x32_bf16 v[2:5], v[128:131], v[196:199], v[68:71]
	v_mfma_f32_16x16x32_bf16 v[68:71], v[136:139], v[200:203], v[2:5]
	v_mfma_f32_16x16x32_bf16 v[2:5], v[172:175], v[196:199], v[108:111]
	v_mfma_f32_16x16x32_bf16 v[192:195], v[176:179], v[200:203], v[2:5]
	v_mfma_f32_16x16x32_bf16 v[2:5], v[128:131], v[204:207], v[20:23]
	v_mfma_f32_16x16x32_bf16 v[136:139], v[136:139], v[208:211], v[2:5]
	v_mfma_f32_16x16x32_bf16 v[2:5], v[172:175], v[204:207], v[24:27]
	v_mfma_f32_16x16x32_bf16 v[172:175], v[176:179], v[208:211], v[2:5]
	s_setprio 0
	s_barrier
	ds_read_b128 v[176:179], v34
	ds_read_b128 v[196:199], v34 offset:1024
	ds_read_b128 v[200:203], v34 offset:2048
	ds_read_b128 v[204:207], v34 offset:3072
	ds_read_b128 v[208:211], v155
	ds_read_b128 v[224:227], v155 offset:1024
	ds_read_b128 v[228:231], v155 offset:2048
	ds_read_b128 v[232:235], v155 offset:3072
	s_mov_b32 m0, s29
	v_lshl_add_u64 v[2:3], v[252:253], 0, s[12:13]
	ds_read_b128 v[36:39], v152 offset:32768
	ds_read_b128 v[108:111], v152 offset:33792
	ds_read_b128 v[112:115], v152 offset:34816
	ds_read_b128 v[120:123], v152 offset:35840
	ds_read_b128 v[236:239], v152 offset:36864
	ds_read_b128 v[240:243], v152 offset:37888
	ds_read_b128 v[244:247], v152 offset:38912
	ds_read_b128 v[248:251], v152 offset:39936
	global_load_lds_dwordx4 v[2:3], off
	v_lshl_add_u64 v[2:3], v[252:253], 0, s[14:15]
	s_mov_b32 m0, s33
	s_nop 0
	global_load_lds_dwordx4 v[2:3], off
	s_waitcnt vmcnt(8)
	s_waitcnt lgkmcnt(0)
	s_barrier
	s_setprio 1
	s_waitcnt lgkmcnt(0)
	v_mfma_f32_16x16x32_bf16 v[2:5], v[176:179], v[36:39], v[72:75]
	v_mfma_f32_16x16x32_bf16 v[6:9], v[200:203], v[36:39], v[76:79]
	v_mfma_f32_16x16x32_bf16 v[10:13], v[176:179], v[112:115], v[80:83]
	v_mfma_f32_16x16x32_bf16 v[14:17], v[200:203], v[112:115], v[84:87]
	v_mfma_f32_16x16x32_bf16 v[18:21], v[176:179], v[236:239], v[88:91]
	v_mfma_f32_16x16x32_bf16 v[22:25], v[200:203], v[236:239], v[92:95]
	v_mfma_f32_16x16x32_bf16 v[26:29], v[176:179], v[244:247], v[96:99]
	v_mfma_f32_16x16x32_bf16 v[30:33], v[200:203], v[244:247], v[100:103]
	v_mfma_f32_16x16x32_bf16 v[2:5], v[196:199], v[108:111], v[2:5]
	v_mfma_f32_16x16x32_bf16 v[6:9], v[204:207], v[108:111], v[6:9]
	v_mfma_f32_16x16x32_bf16 v[10:13], v[196:199], v[120:123], v[10:13]
	v_mfma_f32_16x16x32_bf16 v[14:17], v[204:207], v[120:123], v[14:17]
	v_mfma_f32_16x16x32_bf16 v[18:21], v[196:199], v[240:243], v[18:21]
	v_mfma_f32_16x16x32_bf16 v[22:25], v[204:207], v[240:243], v[22:25]
	v_mfma_f32_16x16x32_bf16 v[26:29], v[196:199], v[248:251], v[26:29]
	v_mfma_f32_16x16x32_bf16 v[30:33], v[204:207], v[248:251], v[30:33]
	v_mfma_f32_16x16x32_bf16 v[72:75], v[208:211], v[36:39], v[104:107]
	v_mfma_f32_16x16x32_bf16 v[36:39], v[228:231], v[36:39], v[40:43]
	v_mfma_f32_16x16x32_bf16 v[128:131], v[232:235], v[108:111], v[36:39]
	v_mfma_f32_16x16x32_bf16 v[36:39], v[208:211], v[112:115], v[44:47]
	v_mfma_f32_16x16x32_bf16 v[116:119], v[224:227], v[120:123], v[36:39]
	v_mfma_f32_16x16x32_bf16 v[36:39], v[228:231], v[112:115], v[48:51]
	v_mfma_f32_16x16x32_bf16 v[120:123], v[232:235], v[120:123], v[36:39]
	v_mfma_f32_16x16x32_bf16 v[36:39], v[208:211], v[236:239], v[52:55]
	v_mfma_f32_16x16x32_bf16 v[124:127], v[224:227], v[108:111], v[72:75]
	v_mfma_f32_16x16x32_bf16 v[108:111], v[224:227], v[240:243], v[36:39]
	v_mfma_f32_16x16x32_bf16 v[36:39], v[228:231], v[236:239], v[56:59]
	v_mfma_f32_16x16x32_bf16 v[112:115], v[232:235], v[240:243], v[36:39]
	v_mfma_f32_16x16x32_bf16 v[36:39], v[208:211], v[244:247], v[60:63]
	v_mfma_f32_16x16x32_bf16 v[100:103], v[224:227], v[248:251], v[36:39]
	v_mfma_f32_16x16x32_bf16 v[36:39], v[228:231], v[244:247], v[64:67]
	v_mfma_f32_16x16x32_bf16 v[104:107], v[232:235], v[248:251], v[36:39]
	s_setprio 0
	s_barrier
	s_mov_b32 m0, s89
	s_nop 3
	v_lshl_add_u64 v[36:37], v[148:149], 0, s[30:31]
	ds_read_b128 v[72:75], v152 offset:49152
	ds_read_b128 v[76:79], v152 offset:50176
	ds_read_b128 v[80:83], v152 offset:51200
	ds_read_b128 v[88:91], v152 offset:52224
	ds_read_b128 v[236:239], v152 offset:53248
	ds_read_b128 v[240:243], v152 offset:54272
	ds_read_b128 v[244:247], v152 offset:55296
	ds_read_b128 v[248:251], v152 offset:56320
	global_load_lds_dwordx4 v[36:37], off
	v_lshl_add_u64 v[36:37], v[148:149], 0, s[34:35]
	s_mov_b32 m0, s65
	s_nop 0
	global_load_lds_dwordx4 v[36:37], off
	v_lshl_add_u64 v[36:37], v[148:149], 0, s[36:37]
	s_mov_b32 m0, s67
	s_nop 0
	global_load_lds_dwordx4 v[36:37], off
	v_lshl_add_u64 v[36:37], v[148:149], 0, s[38:39]
	s_mov_b32 m0, s88
	s_nop 0
	global_load_lds_dwordx4 v[36:37], off
	v_lshl_add_u64 v[36:37], v[252:253], 0, s[30:31]
	s_mov_b32 m0, s41
	s_nop 0
	global_load_lds_dwordx4 v[36:37], off
	v_lshl_add_u64 v[36:37], v[252:253], 0, s[34:35]
	s_mov_b32 m0, s42
	s_nop 0
	global_load_lds_dwordx4 v[36:37], off
	s_waitcnt vmcnt(8)
	s_waitcnt lgkmcnt(0)
	s_barrier
	s_setprio 1
	s_waitcnt lgkmcnt(0)
	v_mfma_f32_16x16x32_bf16 v[40:43], v[200:203], v[72:75], v[144:147]
	v_mfma_f32_16x16x32_bf16 v[44:47], v[204:207], v[76:79], v[40:43]
	v_mfma_f32_16x16x32_bf16 v[40:43], v[176:179], v[80:83], v[156:159]
	v_mfma_f32_16x16x32_bf16 v[52:55], v[196:199], v[88:91], v[40:43]
	v_mfma_f32_16x16x32_bf16 v[40:43], v[200:203], v[80:83], v[160:163]
	v_mfma_f32_16x16x32_bf16 v[36:39], v[176:179], v[72:75], v[140:143]
	v_mfma_f32_16x16x32_bf16 v[60:63], v[204:207], v[88:91], v[40:43]
	v_mfma_f32_16x16x32_bf16 v[40:43], v[176:179], v[236:239], v[164:167]
	v_mfma_f32_16x16x32_bf16 v[48:51], v[200:203], v[236:239], v[168:171]
	v_mfma_f32_16x16x32_bf16 v[56:59], v[176:179], v[244:247], v[212:215]
	v_mfma_f32_16x16x32_bf16 v[64:67], v[200:203], v[244:247], v[216:219]
	v_mfma_f32_16x16x32_bf16 v[36:39], v[196:199], v[76:79], v[36:39]
	v_mfma_f32_16x16x32_bf16 v[40:43], v[196:199], v[240:243], v[40:43]
	v_mfma_f32_16x16x32_bf16 v[48:51], v[204:207], v[240:243], v[48:51]
	v_mfma_f32_16x16x32_bf16 v[56:59], v[196:199], v[248:251], v[56:59]
	v_mfma_f32_16x16x32_bf16 v[64:67], v[204:207], v[248:251], v[64:67]
	v_mfma_f32_16x16x32_bf16 v[84:87], v[208:211], v[72:75], v[220:223]
	v_mfma_f32_16x16x32_bf16 v[72:75], v[228:231], v[72:75], v[180:183]
	v_mfma_f32_16x16x32_bf16 v[96:99], v[232:235], v[76:79], v[72:75]
	v_mfma_f32_16x16x32_bf16 v[72:75], v[208:211], v[80:83], v[184:187]
	v_mfma_f32_16x16x32_bf16 v[68:71], v[208:211], v[236:239], v[68:71]
	v_mfma_f32_16x16x32_bf16 v[92:95], v[224:227], v[76:79], v[84:87]
	v_mfma_f32_16x16x32_bf16 v[84:87], v[224:227], v[88:91], v[72:75]
	v_mfma_f32_16x16x32_bf16 v[72:75], v[228:231], v[80:83], v[188:191]
	v_mfma_f32_16x16x32_bf16 v[76:79], v[224:227], v[240:243], v[68:71]
	v_mfma_f32_16x16x32_bf16 v[68:71], v[228:231], v[236:239], v[192:195]
	v_mfma_f32_16x16x32_bf16 v[88:91], v[232:235], v[88:91], v[72:75]
	v_mfma_f32_16x16x32_bf16 v[80:83], v[232:235], v[240:243], v[68:71]
	v_mfma_f32_16x16x32_bf16 v[68:71], v[208:211], v[244:247], v[136:139]
	v_mfma_f32_16x16x32_bf16 v[72:75], v[228:231], v[244:247], v[172:175]
	v_mfma_f32_16x16x32_bf16 v[68:71], v[224:227], v[248:251], v[68:71]
	v_mfma_f32_16x16x32_bf16 v[72:75], v[232:235], v[248:251], v[72:75]
	s_setprio 0
	s_barrier
	s_andn2_b64 vcc, exec, s[44:45]
	s_cbranch_vccnz .LBB0_1654
	s_barrier

.LBB0_1880:
	v_add_u32_e32 v3, s77, v1
	ds_read_b128 v[134:137], v3
	ds_read_b128 v[138:141], v3 offset:1024
	ds_read_b128 v[142:145], v3 offset:2048
	ds_read_b128 v[146:149], v3 offset:3072
	v_add_u32_e32 v3, s78, v1
	s_add_u32 s8, s62, s64
	ds_read_b128 v[152:155], v3
	ds_read_b128 v[156:159], v3 offset:1024
	ds_read_b128 v[160:163], v3 offset:2048
	ds_read_b128 v[182:185], v3 offset:3072
	s_addc_u32 s9, s63, s65
	s_add_u32 s8, s8, 0x100
	s_addc_u32 s9, s9, 0
	s_add_u32 s86, s81, s64
	s_addc_u32 s87, s84, s65
	s_cmpk_eq_i32 s64, 0xf00
	s_cselect_b32 s9, s5, s9
	s_cselect_b32 s8, s57, s8
	s_cselect_b32 s87, s55, s87
	s_cselect_b32 s86, s80, s86
	v_lshl_add_u64 v[4:5], v[150:151], 0, s[64:65]
	v_lshl_add_u64 v[164:165], v[4:5], 0, s[34:35]
	s_add_i32 m0, s33, 0xc000
	ds_read_b128 v[186:189], v179
	ds_read_b128 v[190:193], v179 offset:1024
	ds_read_b128 v[194:197], v179 offset:2048
	ds_read_b128 v[198:201], v179 offset:3072
	ds_read_b128 v[202:205], v179 offset:4096
	ds_read_b128 v[206:209], v179 offset:5120
	ds_read_b128 v[210:213], v179 offset:6144
	ds_read_b128 v[214:217], v179 offset:7168
	global_load_lds_dwordx4 v[164:165], off
	v_lshl_add_u64 v[4:5], v[4:5], 0, s[36:37]
	s_add_i32 m0, s33, 0xe000
	s_nop 0
	global_load_lds_dwordx4 v[4:5], off
	s_waitcnt vmcnt(8)
	s_waitcnt lgkmcnt(0)
	s_barrier
	s_setprio 1
	s_waitcnt lgkmcnt(0)
	v_mfma_f32_16x16x32_bf16 v[130:133], v[134:137], v[186:189], v[130:133]
	v_mfma_f32_16x16x32_bf16 v[126:129], v[142:145], v[186:189], v[126:129]
	v_mfma_f32_16x16x32_bf16 v[114:117], v[134:137], v[194:197], v[114:117]
	v_mfma_f32_16x16x32_bf16 v[110:113], v[142:145], v[194:197], v[110:113]
	v_mfma_f32_16x16x32_bf16 v[98:101], v[134:137], v[202:205], v[98:101]
	v_mfma_f32_16x16x32_bf16 v[94:97], v[142:145], v[202:205], v[94:97]
	v_mfma_f32_16x16x32_bf16 v[82:85], v[134:137], v[210:213], v[82:85]
	v_mfma_f32_16x16x32_bf16 v[78:81], v[142:145], v[210:213], v[78:81]
	v_mfma_f32_16x16x32_bf16 v[130:133], v[138:141], v[190:193], v[130:133]
	v_mfma_f32_16x16x32_bf16 v[126:129], v[146:149], v[190:193], v[126:129]
	v_mfma_f32_16x16x32_bf16 v[114:117], v[138:141], v[198:201], v[114:117]
	v_mfma_f32_16x16x32_bf16 v[110:113], v[146:149], v[198:201], v[110:113]
	v_mfma_f32_16x16x32_bf16 v[98:101], v[138:141], v[206:209], v[98:101]
	v_mfma_f32_16x16x32_bf16 v[94:97], v[146:149], v[206:209], v[94:97]
	v_mfma_f32_16x16x32_bf16 v[82:85], v[138:141], v[214:217], v[82:85]
	v_mfma_f32_16x16x32_bf16 v[78:81], v[146:149], v[214:217], v[78:81]
	v_mfma_f32_16x16x32_bf16 v[122:125], v[152:155], v[186:189], v[122:125]
	v_mfma_f32_16x16x32_bf16 v[118:121], v[160:163], v[186:189], v[118:121]
	v_mfma_f32_16x16x32_bf16 v[106:109], v[152:155], v[194:197], v[106:109]
	v_mfma_f32_16x16x32_bf16 v[102:105], v[160:163], v[194:197], v[102:105]
	v_mfma_f32_16x16x32_bf16 v[90:93], v[152:155], v[202:205], v[90:93]
	v_mfma_f32_16x16x32_bf16 v[86:89], v[160:163], v[202:205], v[86:89]
	v_mfma_f32_16x16x32_bf16 v[74:77], v[152:155], v[210:213], v[74:77]
	v_mfma_f32_16x16x32_bf16 v[70:73], v[160:163], v[210:213], v[70:73]
	v_mfma_f32_16x16x32_bf16 v[122:125], v[156:159], v[190:193], v[122:125]
	v_mfma_f32_16x16x32_bf16 v[118:121], v[182:185], v[190:193], v[118:121]
	v_mfma_f32_16x16x32_bf16 v[106:109], v[156:159], v[198:201], v[106:109]
	v_mfma_f32_16x16x32_bf16 v[102:105], v[182:185], v[198:201], v[102:105]
	v_mfma_f32_16x16x32_bf16 v[90:93], v[156:159], v[206:209], v[90:93]
	v_mfma_f32_16x16x32_bf16 v[86:89], v[182:185], v[206:209], v[86:89]
	v_mfma_f32_16x16x32_bf16 v[74:77], v[156:159], v[214:217], v[74:77]
	v_mfma_f32_16x16x32_bf16 v[70:73], v[182:185], v[214:217], v[70:73]
	s_setprio 0
	s_barrier
	v_lshl_add_u64 v[164:165], s[86:87], 0, v[168:169]
	s_add_i32 s86, s77, s29
	s_mov_b32 m0, s86
	ds_read_b128 v[186:189], v179 offset:16384
	ds_read_b128 v[190:193], v179 offset:17408
	ds_read_b128 v[194:197], v179 offset:18432
	ds_read_b128 v[198:201], v179 offset:19456
	ds_read_b128 v[202:205], v179 offset:20480
	ds_read_b128 v[206:209], v179 offset:21504
	ds_read_b128 v[210:213], v179 offset:22528
	ds_read_b128 v[214:217], v179 offset:23552
	global_load_lds_dwordx4 v[164:165], off
	v_lshl_add_u64 v[4:5], v[164:165], 0, s[12:13]
	s_add_i32 m0, s86, 0x2000
	s_add_i32 s86, s78, s29
	global_load_lds_dwordx4 v[4:5], off
	v_lshl_add_u64 v[4:5], v[164:165], 0, s[14:15]
	s_mov_b32 m0, s86
	v_lshl_add_u64 v[176:177], s[8:9], 0, v[166:167]
	global_load_lds_dwordx4 v[4:5], off
	v_lshl_add_u64 v[4:5], v[164:165], 0, s[16:17]
	s_add_i32 m0, s86, 0x2000
	s_nop 0
	global_load_lds_dwordx4 v[4:5], off
	s_mov_b32 m0, s33
	v_lshl_add_u64 v[4:5], v[176:177], 0, s[12:13]
	global_load_lds_dwordx4 v[176:177], off
	s_mov_b32 m0, s40
	s_nop 0
	global_load_lds_dwordx4 v[4:5], off
	s_waitcnt vmcnt(8)
	s_waitcnt lgkmcnt(0)
	s_barrier
	s_setprio 1
	s_waitcnt lgkmcnt(0)
	v_mfma_f32_16x16x32_bf16 v[66:69], v[134:137], v[186:189], v[66:69]
	v_mfma_f32_16x16x32_bf16 v[62:65], v[142:145], v[186:189], v[62:65]
	v_mfma_f32_16x16x32_bf16 v[50:53], v[134:137], v[194:197], v[50:53]
	v_mfma_f32_16x16x32_bf16 v[46:49], v[142:145], v[194:197], v[46:49]
	v_mfma_f32_16x16x32_bf16 v[34:37], v[134:137], v[202:205], v[34:37]
	v_mfma_f32_16x16x32_bf16 v[30:33], v[142:145], v[202:205], v[30:33]
	v_mfma_f32_16x16x32_bf16 v[18:21], v[134:137], v[210:213], v[18:21]
	v_mfma_f32_16x16x32_bf16 v[14:17], v[142:145], v[210:213], v[14:17]
	v_mfma_f32_16x16x32_bf16 v[66:69], v[138:141], v[190:193], v[66:69]
	v_mfma_f32_16x16x32_bf16 v[62:65], v[146:149], v[190:193], v[62:65]
	v_mfma_f32_16x16x32_bf16 v[50:53], v[138:141], v[198:201], v[50:53]
	v_mfma_f32_16x16x32_bf16 v[46:49], v[146:149], v[198:201], v[46:49]
	v_mfma_f32_16x16x32_bf16 v[34:37], v[138:141], v[206:209], v[34:37]
	v_mfma_f32_16x16x32_bf16 v[30:33], v[146:149], v[206:209], v[30:33]
	v_mfma_f32_16x16x32_bf16 v[18:21], v[138:141], v[214:217], v[18:21]
	v_mfma_f32_16x16x32_bf16 v[14:17], v[146:149], v[214:217], v[14:17]
	v_mfma_f32_16x16x32_bf16 v[58:61], v[152:155], v[186:189], v[58:61]
	v_mfma_f32_16x16x32_bf16 v[54:57], v[160:163], v[186:189], v[54:57]
	v_mfma_f32_16x16x32_bf16 v[42:45], v[152:155], v[194:197], v[42:45]
	v_mfma_f32_16x16x32_bf16 v[38:41], v[160:163], v[194:197], v[38:41]
	v_mfma_f32_16x16x32_bf16 v[26:29], v[152:155], v[202:205], v[26:29]
	v_mfma_f32_16x16x32_bf16 v[22:25], v[160:163], v[202:205], v[22:25]
	v_mfma_f32_16x16x32_bf16 v[10:13], v[152:155], v[210:213], v[10:13]
	v_mfma_f32_16x16x32_bf16 v[4:7], v[160:163], v[210:213], v[6:9]
	v_mfma_f32_16x16x32_bf16 v[58:61], v[156:159], v[190:193], v[58:61]
	v_mfma_f32_16x16x32_bf16 v[54:57], v[182:185], v[190:193], v[54:57]
	v_mfma_f32_16x16x32_bf16 v[42:45], v[156:159], v[198:201], v[42:45]
	v_mfma_f32_16x16x32_bf16 v[38:41], v[182:185], v[198:201], v[38:41]
	v_mfma_f32_16x16x32_bf16 v[26:29], v[156:159], v[206:209], v[26:29]
	v_mfma_f32_16x16x32_bf16 v[22:25], v[182:185], v[206:209], v[22:25]
	v_mfma_f32_16x16x32_bf16 v[10:13], v[156:159], v[214:217], v[10:13]
	v_mfma_f32_16x16x32_bf16 v[4:7], v[182:185], v[214:217], v[4:7]
	s_setprio 0
	s_barrier
	s_add_i32 s8, 0, 0x18000
	v_add_u32_e32 v3, s8, v1
	s_add_i32 s9, 0, 0x1c000
	ds_read_b128 v[134:137], v3
	ds_read_b128 v[138:141], v3 offset:1024
	ds_read_b128 v[142:145], v3 offset:2048
	ds_read_b128 v[146:149], v3 offset:3072
	v_add_u32_e32 v3, s9, v1
	ds_read_b128 v[152:155], v3
	ds_read_b128 v[156:159], v3 offset:1024
	ds_read_b128 v[160:163], v3 offset:2048
	ds_read_b128 v[182:185], v3 offset:3072
	s_mov_b32 m0, s41
	v_lshl_add_u64 v[8:9], v[176:177], 0, s[14:15]
	ds_read_b128 v[186:189], v179 offset:32768
	ds_read_b128 v[190:193], v179 offset:33792
	ds_read_b128 v[194:197], v179 offset:34816
	ds_read_b128 v[198:201], v179 offset:35840
	ds_read_b128 v[202:205], v179 offset:36864
	ds_read_b128 v[206:209], v179 offset:37888
	ds_read_b128 v[210:213], v179 offset:38912
	ds_read_b128 v[214:217], v179 offset:39936
	global_load_lds_dwordx4 v[8:9], off
	v_lshl_add_u64 v[8:9], v[176:177], 0, s[16:17]
	s_mov_b32 m0, s42
	s_nop 0
	global_load_lds_dwordx4 v[8:9], off
	s_waitcnt vmcnt(8)
	s_waitcnt lgkmcnt(0)
	s_barrier
	s_setprio 1
	s_waitcnt lgkmcnt(0)
	v_mfma_f32_16x16x32_bf16 v[130:133], v[134:137], v[186:189], v[130:133]
	v_mfma_f32_16x16x32_bf16 v[126:129], v[142:145], v[186:189], v[126:129]
	v_mfma_f32_16x16x32_bf16 v[114:117], v[134:137], v[194:197], v[114:117]
	v_mfma_f32_16x16x32_bf16 v[110:113], v[142:145], v[194:197], v[110:113]
	v_mfma_f32_16x16x32_bf16 v[98:101], v[134:137], v[202:205], v[98:101]
	v_mfma_f32_16x16x32_bf16 v[94:97], v[142:145], v[202:205], v[94:97]
	v_mfma_f32_16x16x32_bf16 v[82:85], v[134:137], v[210:213], v[82:85]
	v_mfma_f32_16x16x32_bf16 v[78:81], v[142:145], v[210:213], v[78:81]
	v_mfma_f32_16x16x32_bf16 v[130:133], v[138:141], v[190:193], v[130:133]
	v_mfma_f32_16x16x32_bf16 v[126:129], v[146:149], v[190:193], v[126:129]
	v_mfma_f32_16x16x32_bf16 v[114:117], v[138:141], v[198:201], v[114:117]
	v_mfma_f32_16x16x32_bf16 v[110:113], v[146:149], v[198:201], v[110:113]
	v_mfma_f32_16x16x32_bf16 v[98:101], v[138:141], v[206:209], v[98:101]
	v_mfma_f32_16x16x32_bf16 v[94:97], v[146:149], v[206:209], v[94:97]
	v_mfma_f32_16x16x32_bf16 v[82:85], v[138:141], v[214:217], v[82:85]
	v_mfma_f32_16x16x32_bf16 v[78:81], v[146:149], v[214:217], v[78:81]
	v_mfma_f32_16x16x32_bf16 v[122:125], v[152:155], v[186:189], v[122:125]
	v_mfma_f32_16x16x32_bf16 v[118:121], v[160:163], v[186:189], v[118:121]
	v_mfma_f32_16x16x32_bf16 v[106:109], v[152:155], v[194:197], v[106:109]
	v_mfma_f32_16x16x32_bf16 v[102:105], v[160:163], v[194:197], v[102:105]
	v_mfma_f32_16x16x32_bf16 v[90:93], v[152:155], v[202:205], v[90:93]
	v_mfma_f32_16x16x32_bf16 v[86:89], v[160:163], v[202:205], v[86:89]
	v_mfma_f32_16x16x32_bf16 v[74:77], v[152:155], v[210:213], v[74:77]
	v_mfma_f32_16x16x32_bf16 v[70:73], v[160:163], v[210:213], v[70:73]
	v_mfma_f32_16x16x32_bf16 v[122:125], v[156:159], v[190:193], v[122:125]
	v_mfma_f32_16x16x32_bf16 v[118:121], v[182:185], v[190:193], v[118:121]
	v_mfma_f32_16x16x32_bf16 v[106:109], v[156:159], v[198:201], v[106:109]
	v_mfma_f32_16x16x32_bf16 v[102:105], v[182:185], v[198:201], v[102:105]
	v_mfma_f32_16x16x32_bf16 v[90:93], v[156:159], v[206:209], v[90:93]
	v_mfma_f32_16x16x32_bf16 v[86:89], v[182:185], v[206:209], v[86:89]
	v_mfma_f32_16x16x32_bf16 v[74:77], v[156:159], v[214:217], v[74:77]
	v_mfma_f32_16x16x32_bf16 v[70:73], v[182:185], v[214:217], v[70:73]
	s_setprio 0
	s_barrier
	s_add_i32 s8, s8, s29
	v_lshl_add_u64 v[8:9], v[164:165], 0, s[26:27]
	s_mov_b32 m0, s8
	ds_read_b128 v[186:189], v179 offset:49152
	ds_read_b128 v[190:193], v179 offset:50176
	ds_read_b128 v[194:197], v179 offset:51200
	ds_read_b128 v[198:201], v179 offset:52224
	ds_read_b128 v[202:205], v179 offset:53248
	ds_read_b128 v[206:209], v179 offset:54272
	ds_read_b128 v[210:213], v179 offset:55296
	ds_read_b128 v[214:217], v179 offset:56320
	global_load_lds_dwordx4 v[8:9], off
	v_lshl_add_u64 v[8:9], v[164:165], 0, s[30:31]
	s_add_i32 m0, s8, 0x2000
	s_add_i32 s8, s9, s29
	global_load_lds_dwordx4 v[8:9], off
	v_lshl_add_u64 v[8:9], v[164:165], 0, s[34:35]
	s_mov_b32 m0, s8
	s_nop 0
	global_load_lds_dwordx4 v[8:9], off
	v_lshl_add_u64 v[8:9], v[164:165], 0, s[36:37]
	s_add_i32 m0, s8, 0x2000
	s_nop 0
	global_load_lds_dwordx4 v[8:9], off
	v_lshl_add_u64 v[8:9], v[176:177], 0, s[26:27]
	s_mov_b32 m0, s50
	s_nop 0
	global_load_lds_dwordx4 v[8:9], off
	v_lshl_add_u64 v[8:9], v[176:177], 0, s[30:31]
	s_mov_b32 m0, s51
	s_nop 0
	global_load_lds_dwordx4 v[8:9], off
	s_waitcnt vmcnt(8)
	s_waitcnt lgkmcnt(0)
	s_barrier
	s_setprio 1
	s_waitcnt lgkmcnt(0)
	v_mfma_f32_16x16x32_bf16 v[66:69], v[134:137], v[186:189], v[66:69]
	v_mfma_f32_16x16x32_bf16 v[62:65], v[142:145], v[186:189], v[62:65]
	v_mfma_f32_16x16x32_bf16 v[50:53], v[134:137], v[194:197], v[50:53]
	v_mfma_f32_16x16x32_bf16 v[46:49], v[142:145], v[194:197], v[46:49]
	v_mfma_f32_16x16x32_bf16 v[34:37], v[134:137], v[202:205], v[34:37]
	v_mfma_f32_16x16x32_bf16 v[30:33], v[142:145], v[202:205], v[30:33]
	v_mfma_f32_16x16x32_bf16 v[18:21], v[134:137], v[210:213], v[18:21]
	v_mfma_f32_16x16x32_bf16 v[14:17], v[142:145], v[210:213], v[14:17]
	v_mfma_f32_16x16x32_bf16 v[66:69], v[138:141], v[190:193], v[66:69]
	v_mfma_f32_16x16x32_bf16 v[62:65], v[146:149], v[190:193], v[62:65]
	v_mfma_f32_16x16x32_bf16 v[50:53], v[138:141], v[198:201], v[50:53]
	v_mfma_f32_16x16x32_bf16 v[46:49], v[146:149], v[198:201], v[46:49]
	v_mfma_f32_16x16x32_bf16 v[34:37], v[138:141], v[206:209], v[34:37]
	v_mfma_f32_16x16x32_bf16 v[30:33], v[146:149], v[206:209], v[30:33]
	v_mfma_f32_16x16x32_bf16 v[18:21], v[138:141], v[214:217], v[18:21]
	v_mfma_f32_16x16x32_bf16 v[14:17], v[146:149], v[214:217], v[14:17]
	v_mfma_f32_16x16x32_bf16 v[58:61], v[152:155], v[186:189], v[58:61]
	v_mfma_f32_16x16x32_bf16 v[54:57], v[160:163], v[186:189], v[54:57]
	v_mfma_f32_16x16x32_bf16 v[42:45], v[152:155], v[194:197], v[42:45]
	v_mfma_f32_16x16x32_bf16 v[38:41], v[160:163], v[194:197], v[38:41]
	v_mfma_f32_16x16x32_bf16 v[26:29], v[152:155], v[202:205], v[26:29]
	v_mfma_f32_16x16x32_bf16 v[22:25], v[160:163], v[202:205], v[22:25]
	v_mfma_f32_16x16x32_bf16 v[8:11], v[152:155], v[210:213], v[10:13]
	v_mfma_f32_16x16x32_bf16 v[4:7], v[160:163], v[210:213], v[4:7]
	v_mfma_f32_16x16x32_bf16 v[58:61], v[156:159], v[190:193], v[58:61]
	v_mfma_f32_16x16x32_bf16 v[54:57], v[182:185], v[190:193], v[54:57]
	v_mfma_f32_16x16x32_bf16 v[42:45], v[156:159], v[198:201], v[42:45]
	v_mfma_f32_16x16x32_bf16 v[38:41], v[182:185], v[198:201], v[38:41]
	v_mfma_f32_16x16x32_bf16 v[26:29], v[156:159], v[206:209], v[26:29]
	v_mfma_f32_16x16x32_bf16 v[22:25], v[182:185], v[206:209], v[22:25]
	v_mfma_f32_16x16x32_bf16 v[10:13], v[156:159], v[214:217], v[8:11]
	v_mfma_f32_16x16x32_bf16 v[6:9], v[182:185], v[214:217], v[4:7]
	s_setprio 0
	s_barrier
	s_add_i32 s85, s85, 2
	s_add_u32 s64, s64, 0x100
	s_addc_u32 s65, s65, 0
	s_cmp_gt_u32 s85, 29
	s_cbranch_scc1 .LBB0_1883

.LBB0_2190:
	v_mul_f32_e32 v141, 0xbfb8aa3b, v128
	v_exp_f32_e32 v141, v141
	v_mul_f32_e32 v142, 0xbfb8aa3b, v129
	v_exp_f32_e32 v142, v142
	v_mov_b32_e32 v34, v0
	v_add_f32_e32 v141, 1.0, v141
	v_rcp_f32_e32 v141, v141
	v_add_f32_e32 v142, 1.0, v142
	v_rcp_f32_e32 v142, v142
	s_nop 15
	s_nop 15
	v_readlane_b32 s76, v254, 6
	v_and_or_b32 v143, v34, 63, s55
	v_mul_f32_e32 v34, v128, v141
	v_mul_f32_e32 v128, 0xbfb8aa3b, v130
	v_mul_f32_e32 v2, v34, v2
	v_mul_f32_e32 v34, v129, v142
	v_exp_f32_e32 v128, v128
	v_mul_f32_e32 v129, 0xbfb8aa3b, v131
	v_exp_f32_e32 v129, v129
	v_mul_f32_e32 v3, v34, v3
	v_add_f32_e32 v34, 1.0, v128
	v_rcp_f32_e32 v34, v34
	v_add_f32_e32 v128, 1.0, v129
	v_mul_f32_e32 v129, 0xbfb8aa3b, v124
	v_rcp_f32_e32 v128, v128
	v_exp_f32_e32 v129, v129
	v_mul_f32_e32 v34, v130, v34
	v_mul_f32_e32 v4, v34, v4
	v_mul_f32_e32 v34, v131, v128
	v_add_f32_e32 v128, 1.0, v129
	v_rcp_f32_e32 v128, v128
	v_mul_f32_e32 v129, 0xbfb8aa3b, v125
	v_exp_f32_e32 v129, v129
	v_mul_f32_e32 v5, v34, v5
	v_mul_f32_e32 v34, v124, v128
	v_mul_f32_e32 v124, 0xbfb8aa3b, v126
	v_mul_f32_e32 v6, v34, v6
	v_add_f32_e32 v34, 1.0, v129
	v_exp_f32_e32 v124, v124
	v_mul_f32_e32 v128, 0xbfb8aa3b, v127
	v_rcp_f32_e32 v34, v34
	v_exp_f32_e32 v128, v128
	v_add_f32_e32 v124, 1.0, v124
	v_rcp_f32_e32 v124, v124
	v_mul_f32_e32 v34, v125, v34
	v_add_f32_e32 v125, 1.0, v128
	v_rcp_f32_e32 v125, v125
	v_mul_f32_e32 v7, v34, v7
	v_mul_f32_e32 v34, v126, v124
	v_mul_f32_e32 v8, v34, v8
	v_mul_f32_e32 v34, v127, v125
	v_mul_f32_e32 v124, 0xbfb8aa3b, v120
	v_mul_f32_e32 v125, 0xbfb8aa3b, v121
	v_exp_f32_e32 v124, v124
	v_exp_f32_e32 v125, v125
	v_mul_f32_e32 v9, v34, v9
	v_readlane_b32 s82, v254, 12
	v_add_f32_e32 v34, 1.0, v124
	v_add_f32_e32 v124, 1.0, v125
	v_mul_f32_e32 v125, 0xbfb8aa3b, v122
	v_rcp_f32_e32 v34, v34
	v_exp_f32_e32 v125, v125
	v_rcp_f32_e32 v124, v124
	v_readlane_b32 s83, v254, 13
	v_mul_f32_e32 v34, v120, v34
	v_add_f32_e32 v120, 1.0, v125
	v_mul_f32_e32 v10, v34, v10
	v_mul_f32_e32 v34, v121, v124
	v_rcp_f32_e32 v120, v120
	v_mul_f32_e32 v121, 0xbfb8aa3b, v123
	v_exp_f32_e32 v121, v121
	v_mul_f32_e32 v11, v34, v11
	v_mul_f32_e32 v34, v122, v120
	v_mul_f32_e32 v120, 0xbfb8aa3b, v116
	v_mul_f32_e32 v12, v34, v12
	v_add_f32_e32 v34, 1.0, v121
	v_exp_f32_e32 v120, v120
	v_mul_f32_e32 v121, 0xbfb8aa3b, v117
	v_exp_f32_e32 v121, v121
	v_rcp_f32_e32 v34, v34
	v_add_f32_e32 v120, 1.0, v120
	v_rcp_f32_e32 v120, v120
	v_add_f32_e32 v121, 1.0, v121
	v_rcp_f32_e32 v121, v121
	v_mul_f32_e32 v34, v123, v34
	v_mul_f32_e32 v13, v34, v13
	v_mul_f32_e32 v34, v116, v120
	v_mul_f32_e32 v116, 0xbfb8aa3b, v118
	v_mul_f32_e32 v14, v34, v14
	v_mul_f32_e32 v34, v117, v121
	v_exp_f32_e32 v116, v116
	v_mul_f32_e32 v117, 0xbfb8aa3b, v119
	v_exp_f32_e32 v117, v117
	v_mul_f32_e32 v15, v34, v15
	v_add_f32_e32 v34, 1.0, v116
	v_rcp_f32_e32 v34, v34
	v_add_f32_e32 v116, 1.0, v117
	v_mul_f32_e32 v117, 0xbfb8aa3b, v112
	v_rcp_f32_e32 v116, v116
	v_exp_f32_e32 v117, v117
	v_mul_f32_e32 v34, v118, v34
	v_mul_f32_e32 v16, v34, v16
	v_mul_f32_e32 v34, v119, v116
	v_add_f32_e32 v116, 1.0, v117
	v_rcp_f32_e32 v116, v116
	v_mul_f32_e32 v117, 0xbfb8aa3b, v113
	v_exp_f32_e32 v117, v117
	v_mul_f32_e32 v17, v34, v17
	v_mul_f32_e32 v34, v112, v116
	v_mul_f32_e32 v112, 0xbfb8aa3b, v114
	v_mul_f32_e32 v18, v34, v18
	v_add_f32_e32 v34, 1.0, v117
	v_exp_f32_e32 v112, v112
	v_mul_f32_e32 v116, 0xbfb8aa3b, v115
	v_rcp_f32_e32 v34, v34
	v_exp_f32_e32 v116, v116
	v_add_f32_e32 v112, 1.0, v112
	v_rcp_f32_e32 v112, v112
	v_mul_f32_e32 v34, v113, v34
	v_add_f32_e32 v113, 1.0, v116
	v_rcp_f32_e32 v113, v113
	v_mul_f32_e32 v19, v34, v19
	v_mul_f32_e32 v34, v114, v112
	v_mul_f32_e32 v20, v34, v20
	v_mul_f32_e32 v34, v115, v113
	v_mul_f32_e32 v112, 0xbfb8aa3b, v108
	v_mul_f32_e32 v113, 0xbfb8aa3b, v109
	v_exp_f32_e32 v112, v112
	v_exp_f32_e32 v113, v113
	v_mul_f32_e32 v21, v34, v21
	v_permlane32_swap_b32_e32 v2, v18
	v_add_f32_e32 v34, 1.0, v112
	v_add_f32_e32 v112, 1.0, v113
	v_mul_f32_e32 v113, 0xbfb8aa3b, v110
	v_rcp_f32_e32 v34, v34
	v_exp_f32_e32 v113, v113
	v_rcp_f32_e32 v112, v112
	v_permlane32_swap_b32_e32 v3, v19
	v_mul_f32_e32 v34, v108, v34
	v_add_f32_e32 v108, 1.0, v113
	v_mul_f32_e32 v22, v34, v22
	v_mul_f32_e32 v34, v109, v112
	v_rcp_f32_e32 v108, v108
	v_mul_f32_e32 v109, 0xbfb8aa3b, v111
	v_exp_f32_e32 v109, v109
	v_mul_f32_e32 v23, v34, v23
	v_mul_f32_e32 v34, v110, v108
	v_mul_f32_e32 v108, 0xbfb8aa3b, v104
	v_mul_f32_e32 v24, v34, v24
	v_add_f32_e32 v34, 1.0, v109
	v_exp_f32_e32 v108, v108
	v_mul_f32_e32 v109, 0xbfb8aa3b, v105
	v_exp_f32_e32 v109, v109
	v_rcp_f32_e32 v34, v34
	v_add_f32_e32 v108, 1.0, v108
	v_rcp_f32_e32 v108, v108
	v_add_f32_e32 v109, 1.0, v109
	v_rcp_f32_e32 v109, v109
	v_mul_f32_e32 v34, v111, v34
	v_mul_f32_e32 v25, v34, v25
	v_mul_f32_e32 v34, v104, v108
	v_mul_f32_e32 v104, 0xbfb8aa3b, v106
	v_mul_f32_e32 v26, v34, v26
	v_mul_f32_e32 v34, v105, v109
	v_exp_f32_e32 v104, v104
	v_mul_f32_e32 v105, 0xbfb8aa3b, v107
	v_exp_f32_e32 v105, v105
	v_mul_f32_e32 v27, v34, v27
	v_add_f32_e32 v34, 1.0, v104
	v_rcp_f32_e32 v34, v34
	v_add_f32_e32 v104, 1.0, v105
	v_mul_f32_e32 v105, 0xbfb8aa3b, v100
	v_rcp_f32_e32 v104, v104
	v_exp_f32_e32 v105, v105
	v_mul_f32_e32 v34, v106, v34
	v_mul_f32_e32 v28, v34, v28
	v_mul_f32_e32 v34, v107, v104
	v_add_f32_e32 v104, 1.0, v105
	v_rcp_f32_e32 v104, v104
	v_mul_f32_e32 v105, 0xbfb8aa3b, v101
	v_exp_f32_e32 v105, v105
	v_mul_f32_e32 v29, v34, v29
	v_mul_f32_e32 v34, v100, v104
	v_mul_f32_e32 v100, 0xbfb8aa3b, v102
	v_mul_f32_e32 v30, v34, v30
	v_add_f32_e32 v34, 1.0, v105
	v_exp_f32_e32 v100, v100
	v_mul_f32_e32 v104, 0xbfb8aa3b, v103
	v_rcp_f32_e32 v34, v34
	v_exp_f32_e32 v104, v104
	v_add_f32_e32 v100, 1.0, v100
	v_rcp_f32_e32 v100, v100
	v_mul_f32_e32 v34, v101, v34
	v_add_f32_e32 v101, 1.0, v104
	v_rcp_f32_e32 v101, v101
	v_mul_f32_e32 v31, v34, v31
	v_mul_f32_e32 v34, v102, v100
	v_permlane32_swap_b32_e32 v10, v26
	v_mul_f32_e32 v32, v34, v32
	v_mul_f32_e32 v34, v103, v101
	v_permlane32_swap_b32_e32 v11, v27
	v_permlane16_swap_b32_e32 v2, v10
	v_permlane16_swap_b32_e32 v18, v26
	v_mul_f32_e32 v33, v34, v33
	v_permlane16_swap_b32_e32 v3, v11
	v_permlane16_swap_b32_e32 v19, v27
	v_permlane32_swap_b32_e32 v4, v20
	v_permlane32_swap_b32_e32 v12, v28
	v_permlane32_swap_b32_e32 v5, v21
	v_permlane32_swap_b32_e32 v13, v29
	v_permlane16_swap_b32_e32 v4, v12
	v_permlane16_swap_b32_e32 v20, v28
	v_permlane16_swap_b32_e32 v5, v13
	v_permlane16_swap_b32_e32 v21, v29
	v_max_f32_e64 v34, |v2|, |v18|
	v_max3_f32 v34, v34, |v3|, |v19|
	v_permlane32_swap_b32_e32 v6, v22
	v_permlane32_swap_b32_e32 v14, v30
	v_permlane32_swap_b32_e32 v7, v23
	v_permlane32_swap_b32_e32 v15, v31
	v_permlane16_swap_b32_e32 v6, v14
	v_permlane16_swap_b32_e32 v22, v30
	v_permlane16_swap_b32_e32 v7, v15
	v_permlane16_swap_b32_e32 v23, v31
	v_max3_f32 v34, v34, |v4|, |v20|
	v_max3_f32 v34, v34, |v5|, |v21|
	v_permlane32_swap_b32_e32 v8, v24
	v_permlane32_swap_b32_e32 v16, v32
	v_permlane32_swap_b32_e32 v9, v25
	v_permlane32_swap_b32_e32 v17, v33
	v_permlane16_swap_b32_e32 v8, v16
	v_permlane16_swap_b32_e32 v24, v32
	v_permlane16_swap_b32_e32 v9, v17
	v_permlane16_swap_b32_e32 v25, v33
	v_max3_f32 v34, v34, |v6|, |v22|
	v_max3_f32 v34, v34, |v7|, |v23|
	v_max3_f32 v34, v34, |v8|, |v24|
	v_max3_f32 v34, v34, |v9|, |v25|
	v_max3_f32 v34, v34, |v10|, |v26|
	v_max3_f32 v34, v34, |v11|, |v27|
	v_max3_f32 v34, v34, |v12|, |v28|
	v_max3_f32 v34, v34, |v13|, |v29|
	v_max3_f32 v34, v34, |v14|, |v30|
	v_max3_f32 v34, v34, |v15|, |v31|
	v_max3_f32 v34, v34, |v16|, |v32|
	v_max3_f32 v34, v34, |v17|, |v33|
	v_bfe_u32 v100, v34, 23, 8
	v_and_b32_e32 v34, 0x7fffff, v34
	v_cmp_gt_u32_e32 vcc, s59, v34
	v_lshl_add_u32 v108, s46, 8, v143
	v_readlane_b32 s77, v254, 7
	v_cndmask_b32_e64 v34, -2, -3, vcc
	v_add3_u32 v34, v100, v34, s60
	v_max_i32_e32 v34, 0xffffff88, v34
	v_add_u32_e32 v34, 0x7f, v34
	v_lshlrev_b32_e32 v100, 23, v34
	v_cvt_scalef32_2xpk16_fp6_f32 v[102:107], v[2:17], v[18:33], v100
	v_mul_f32_e32 v4, 0xbfb8aa3b, v96
	v_exp_f32_e32 v4, v4
	v_mul_f32_e32 v5, 0xbfb8aa3b, v97
	v_exp_f32_e32 v5, v5
	v_mov_b64_e32 v[100:101], s[18:19]
	v_mad_i64_i32 v[2:3], s[46:47], v108, s62, v[100:101]
	v_add_f32_e32 v4, 1.0, v4
	s_lshl_b32 s46, s5, 7
	v_rcp_f32_e32 v4, v4
	v_add_f32_e32 v5, 1.0, v5
	s_ashr_i32 s47, s46, 31
	v_rcp_f32_e32 v5, v5
	v_mul_f32_e32 v10, 0xbfb8aa3b, v80
	v_mul_f32_e32 v18, 0xbfb8aa3b, v68
	v_mul_f32_e32 v26, 0xbfb8aa3b, v52
	v_lshl_add_u64 v[2:3], v[2:3], 0, s[46:47]
	v_exp_f32_e32 v10, v10
	v_mul_f32_e32 v11, 0xbfb8aa3b, v81
	v_exp_f32_e32 v18, v18
	v_mul_f32_e32 v19, 0xbfb8aa3b, v69
	v_exp_f32_e32 v26, v26
	v_mul_f32_e32 v27, 0xbfb8aa3b, v53
	v_mul_lo_u32 v34, v34, s61
	v_lshl_add_u64 v[2:3], v[2:3], 0, s[12:13]
	v_mov_b32_e32 v32, v106
	v_mov_b32_e32 v33, v107
	v_exp_f32_e32 v11, v11
	v_exp_f32_e32 v19, v19
	v_exp_f32_e32 v27, v27
	global_store_dwordx4 v[2:3], v[102:105], off
	global_store_dwordx4 v[2:3], v[32:35], off offset:64
	v_mul_f32_e32 v2, v96, v4
	v_mul_f32_e32 v4, 0xbfb8aa3b, v98
	v_mul_f32_e32 v12, 0xbfb8aa3b, v82
	v_mul_f32_e32 v20, 0xbfb8aa3b, v70
	v_mul_f32_e32 v28, 0xbfb8aa3b, v54
	v_mul_f32_e32 v30, 0xbfb8aa3b, v44
	v_mul_f32_e32 v3, v97, v5
	v_exp_f32_e32 v4, v4
	v_mul_f32_e32 v5, 0xbfb8aa3b, v99
	v_exp_f32_e32 v12, v12
	v_mul_f32_e32 v13, 0xbfb8aa3b, v83
	v_exp_f32_e32 v20, v20
	v_mul_f32_e32 v21, 0xbfb8aa3b, v71
	v_exp_f32_e32 v28, v28
	v_mul_f32_e32 v29, 0xbfb8aa3b, v55
	v_exp_f32_e32 v30, v30
	v_mul_f32_e32 v31, 0xbfb8aa3b, v45
	v_exp_f32_e32 v5, v5
	v_add_f32_e32 v10, 1.0, v10
	v_exp_f32_e32 v13, v13
	v_add_f32_e32 v18, 1.0, v18
	v_exp_f32_e32 v21, v21
	v_add_f32_e32 v26, 1.0, v26
	v_exp_f32_e32 v29, v29
	v_exp_f32_e32 v31, v31
	v_mul_f32_e32 v6, 0xbfb8aa3b, v92
	v_rcp_f32_e32 v10, v10
	v_add_f32_e32 v11, 1.0, v11
	v_mul_f32_e32 v14, 0xbfb8aa3b, v76
	v_rcp_f32_e32 v18, v18
	v_add_f32_e32 v19, 1.0, v19
	v_mul_f32_e32 v22, 0xbfb8aa3b, v56
	v_rcp_f32_e32 v26, v26
	v_add_f32_e32 v27, 1.0, v27
	v_exp_f32_e32 v6, v6
	v_mul_f32_e32 v7, 0xbfb8aa3b, v93
	v_rcp_f32_e32 v11, v11
	v_exp_f32_e32 v14, v14
	v_mul_f32_e32 v15, 0xbfb8aa3b, v77
	v_rcp_f32_e32 v19, v19
	v_exp_f32_e32 v22, v22
	v_mul_f32_e32 v23, 0xbfb8aa3b, v57
	v_rcp_f32_e32 v27, v27
	v_mul_f32_e32 v32, 0xbfb8aa3b, v46
	v_add_f32_e32 v4, 1.0, v4
	v_exp_f32_e32 v7, v7
	v_add_f32_e32 v12, 1.0, v12
	v_exp_f32_e32 v15, v15
	v_add_f32_e32 v20, 1.0, v20
	v_exp_f32_e32 v23, v23
	v_add_f32_e32 v28, 1.0, v28
	v_add_f32_e32 v30, 1.0, v30
	v_exp_f32_e32 v32, v32
	v_rcp_f32_e32 v4, v4
	v_add_f32_e32 v5, 1.0, v5
	v_mul_f32_e32 v8, 0xbfb8aa3b, v94
	v_rcp_f32_e32 v12, v12
	v_add_f32_e32 v13, 1.0, v13
	v_mul_f32_e32 v16, 0xbfb8aa3b, v78
	v_rcp_f32_e32 v20, v20
	v_add_f32_e32 v21, 1.0, v21
	v_mul_f32_e32 v24, 0xbfb8aa3b, v58
	v_rcp_f32_e32 v28, v28
	v_add_f32_e32 v29, 1.0, v29
	v_rcp_f32_e32 v30, v30
	v_add_f32_e32 v31, 1.0, v31
	v_rcp_f32_e32 v5, v5
	v_exp_f32_e32 v8, v8
	v_mul_f32_e32 v9, 0xbfb8aa3b, v95
	v_mul_f32_e32 v10, v80, v10
	v_rcp_f32_e32 v13, v13
	v_exp_f32_e32 v16, v16
	v_mul_f32_e32 v17, 0xbfb8aa3b, v79
	v_mul_f32_e32 v18, v68, v18
	v_rcp_f32_e32 v21, v21
	v_exp_f32_e32 v24, v24
	v_mul_f32_e32 v25, 0xbfb8aa3b, v59
	v_mul_f32_e32 v26, v52, v26
	v_rcp_f32_e32 v29, v29
	v_rcp_f32_e32 v31, v31
	v_mul_f32_e32 v33, 0xbfb8aa3b, v47
	v_mul_f32_e32 v2, v2, v88
	v_add_f32_e32 v6, 1.0, v6
	v_exp_f32_e32 v9, v9
	v_mul_f32_e32 v10, v10, v72
	v_mul_f32_e32 v11, v81, v11
	v_add_f32_e32 v14, 1.0, v14
	v_exp_f32_e32 v17, v17
	v_mul_f32_e32 v18, v18, v60
	v_mul_f32_e32 v19, v69, v19
	v_add_f32_e32 v22, 1.0, v22
	v_exp_f32_e32 v25, v25
	v_mul_f32_e32 v26, v26, v40
	v_mul_f32_e32 v27, v53, v27
	v_exp_f32_e32 v33, v33
	v_mul_f32_e32 v3, v3, v89
	v_rcp_f32_e32 v6, v6
	v_add_f32_e32 v7, 1.0, v7
	v_mul_f32_e32 v11, v11, v73
	v_rcp_f32_e32 v14, v14
	v_add_f32_e32 v15, 1.0, v15
	v_mul_f32_e32 v19, v19, v61
	v_rcp_f32_e32 v22, v22
	v_add_f32_e32 v23, 1.0, v23
	v_mul_f32_e32 v27, v27, v41
	v_add_f32_e32 v32, 1.0, v32
	v_permlane32_swap_b32_e32 v2, v18
	v_permlane32_swap_b32_e32 v10, v26
	v_mul_f32_e32 v4, v98, v4
	v_rcp_f32_e32 v7, v7
	v_mul_f32_e32 v12, v82, v12
	v_rcp_f32_e32 v15, v15
	v_mul_f32_e32 v20, v70, v20
	v_rcp_f32_e32 v23, v23
	v_mul_f32_e32 v28, v54, v28
	v_mul_f32_e32 v30, v44, v30
	v_rcp_f32_e32 v32, v32
	v_permlane32_swap_b32_e32 v3, v19
	v_permlane32_swap_b32_e32 v11, v27
	v_permlane16_swap_b32_e32 v2, v10
	v_permlane16_swap_b32_e32 v18, v26
	v_mul_f32_e32 v4, v4, v90
	v_mul_f32_e32 v5, v99, v5
	v_add_f32_e32 v8, 1.0, v8
	v_mul_f32_e32 v12, v12, v74
	v_mul_f32_e32 v13, v83, v13
	v_add_f32_e32 v16, 1.0, v16
	v_mul_f32_e32 v20, v20, v62
	v_mul_f32_e32 v21, v71, v21
	v_add_f32_e32 v24, 1.0, v24
	v_mul_f32_e32 v28, v28, v42
	v_mul_f32_e32 v29, v55, v29
	v_mul_f32_e32 v30, v30, v36
	v_mul_f32_e32 v31, v45, v31
	v_permlane16_swap_b32_e32 v3, v11
	v_permlane16_swap_b32_e32 v19, v27
	v_mul_f32_e32 v5, v5, v91
	v_rcp_f32_e32 v8, v8
	v_add_f32_e32 v9, 1.0, v9
	v_mul_f32_e32 v13, v13, v75
	v_rcp_f32_e32 v16, v16
	v_add_f32_e32 v17, 1.0, v17
	v_mul_f32_e32 v21, v21, v63
	v_rcp_f32_e32 v24, v24
	v_add_f32_e32 v25, 1.0, v25
	v_mul_f32_e32 v29, v29, v43
	v_add_f32_e32 v33, 1.0, v33
	v_mul_f32_e32 v31, v31, v37
	v_permlane32_swap_b32_e32 v4, v20
	v_permlane32_swap_b32_e32 v12, v28
	v_mul_f32_e32 v6, v92, v6
	v_rcp_f32_e32 v9, v9
	v_mul_f32_e32 v14, v76, v14
	v_rcp_f32_e32 v17, v17
	v_mul_f32_e32 v22, v56, v22
	v_rcp_f32_e32 v25, v25
	v_rcp_f32_e32 v33, v33
	v_permlane32_swap_b32_e32 v5, v21
	v_permlane32_swap_b32_e32 v13, v29
	v_permlane16_swap_b32_e32 v4, v12
	v_permlane16_swap_b32_e32 v20, v28
	v_mul_f32_e32 v6, v6, v84
	v_mul_f32_e32 v7, v93, v7
	v_mul_f32_e32 v14, v14, v64
	v_mul_f32_e32 v15, v77, v15
	v_mul_f32_e32 v22, v22, v48
	v_mul_f32_e32 v23, v57, v23
	v_mul_f32_e32 v32, v46, v32
	v_permlane16_swap_b32_e32 v5, v13
	v_permlane16_swap_b32_e32 v21, v29
	v_max_f32_e64 v34, |v2|, |v18|
	v_max3_f32 v34, v34, |v3|, |v19|
	v_mul_f32_e32 v7, v7, v85
	v_mul_f32_e32 v15, v15, v65
	v_mul_f32_e32 v23, v23, v49
	v_mul_f32_e32 v32, v32, v38
	v_permlane32_swap_b32_e32 v6, v22
	v_permlane32_swap_b32_e32 v14, v30
	v_mul_f32_e32 v8, v94, v8
	v_mul_f32_e32 v16, v78, v16
	v_mul_f32_e32 v24, v58, v24
	v_permlane32_swap_b32_e32 v7, v23
	v_permlane32_swap_b32_e32 v15, v31
	v_permlane16_swap_b32_e32 v6, v14
	v_permlane16_swap_b32_e32 v22, v30
	v_mul_f32_e32 v8, v8, v86
	v_mul_f32_e32 v9, v95, v9
	v_mul_f32_e32 v16, v16, v66
	v_mul_f32_e32 v17, v79, v17
	v_mul_f32_e32 v24, v24, v50
	v_mul_f32_e32 v25, v59, v25
	v_mul_f32_e32 v33, v47, v33
	v_permlane16_swap_b32_e32 v7, v15
	v_permlane16_swap_b32_e32 v23, v31
	v_max3_f32 v34, v34, |v4|, |v20|
	v_max3_f32 v34, v34, |v5|, |v21|
	v_mul_f32_e32 v9, v9, v87
	v_mul_f32_e32 v17, v17, v67
	v_mul_f32_e32 v25, v25, v51
	v_mul_f32_e32 v33, v33, v39
	v_permlane32_swap_b32_e32 v8, v24
	v_permlane32_swap_b32_e32 v16, v32
	v_permlane32_swap_b32_e32 v9, v25
	v_permlane32_swap_b32_e32 v17, v33
	v_permlane16_swap_b32_e32 v8, v16
	v_permlane16_swap_b32_e32 v24, v32
	v_permlane16_swap_b32_e32 v9, v17
	v_permlane16_swap_b32_e32 v25, v33
	v_max3_f32 v34, v34, |v6|, |v22|
	v_max3_f32 v34, v34, |v7|, |v23|
	v_max3_f32 v34, v34, |v8|, |v24|
	v_max3_f32 v34, v34, |v9|, |v25|
	v_max3_f32 v34, v34, |v10|, |v26|
	v_max3_f32 v34, v34, |v11|, |v27|
	v_max3_f32 v34, v34, |v12|, |v28|
	v_max3_f32 v34, v34, |v13|, |v29|
	v_max3_f32 v34, v34, |v14|, |v30|
	v_max3_f32 v34, v34, |v15|, |v31|
	v_max3_f32 v34, v34, |v16|, |v32|
	v_max3_f32 v34, v34, |v17|, |v33|
	v_bfe_u32 v36, v34, 23, 8
	v_and_b32_e32 v34, 0x7fffff, v34
	v_cmp_gt_u32_e32 vcc, s59, v34
	s_cmp_eq_u32 s4, s56
	s_mov_b64 s[4:5], -1
	v_cndmask_b32_e64 v34, -2, -3, vcc
	v_add3_u32 v34, v36, v34, s60
	v_max_i32_e32 v34, 0xffffff88, v34
	v_add_u32_e32 v34, 0x7f, v34
	v_lshlrev_b32_e32 v42, 23, v34
	v_cvt_scalef32_2xpk16_fp6_f32 v[36:41], v[2:17], v[18:33], v42
	v_add_u32_e32 v2, 0x80, v108
	v_mad_i64_i32 v[2:3], s[48:49], v2, s62, v[100:101]
	v_lshl_add_u64 v[2:3], v[2:3], 0, s[46:47]
	v_mul_lo_u32 v34, v34, s61
	v_lshl_add_u64 v[2:3], v[2:3], 0, s[12:13]
	v_mov_b32_e32 v32, v40
	v_mov_b32_e32 v33, v41
	global_store_dwordx4 v[2:3], v[36:39], off
	global_store_dwordx4 v[2:3], v[32:35], off offset:64
	v_readlane_b32 s78, v254, 8
	v_readlane_b32 s79, v254, 9
	v_readlane_b32 s80, v254, 10
	v_readlane_b32 s81, v254, 11
	s_cbranch_scc1 .LBB0_2183
	s_andn2_b64 vcc, exec, s[14:15]
	s_cbranch_vccnz .LBB0_2182
	s_barrier
	s_branch .LBB0_2182
